# GEMM epilogues: the xor-16 / xor-32 cross-lane row-sum exchanges use v_permlane16_swap / v_permlane32_swap (VALU) instead of ds_bpermute LDS round trips (64 sites: residual epilogues' sum-of-squares,
# speedup vs baseline: 1.0406x; 1.0037x over previous
;     __device__ __forceinline__ void operator()(const f32x4 (&acc)[2][2][4][2], const Unit& u, int ui, int wr, int wc, int fr, int fq) const {
;     ...
;         const int row0 = u.pm * BM + wr * 64 + fr, col0 = u.pn * BM + wc * 32 + 8 * fq;
;         f32x4 bv[2][2];
; #pragma unroll
;         for (int bj = 0; bj < 2; ++bj)
; #pragma unroll
;             for (int n = 0; n < 2; ++n) bv[bj][n] = HAS_BIAS ? *(const f32x4*)(bias + col0 + bj * HALF + 4 * n) : (f32x4){0.f, 0.f, 0.f, 0.f};
; #pragma unroll
;         for (int ai = 0; ai < 2; ++ai)
; #pragma unroll
;             for (int m = 0; m < 4; ++m) { const int row = row0 + ai * HALF + m * 16; const size_t off = (size_t)row * 1024 + col0; float q = 0.f;
;                 f32x4 v[2][2];
;                 if (basef) {
; #pragma unroll
;                     for (int bj = 0; bj < 2; ++bj) { v[bj][0] = *(const f32x4*)(basef + off + bj * HALF); v[bj][1] = *(const f32x4*)(basef + off + bj * HALF + 4); }
;                 } else {
; #pragma unroll
;                     for (int bj = 0; bj < 2; ++bj) { const u32x4 raw = *(const u32x4*)(xb + off + bj * HALF);
;                         v[bj][0] = (f32x4){__builtin_bit_cast(float, raw.x << 16), __builtin_bit_cast(float, raw.x & 0xffff0000u), __builtin_bit_cast(float, raw.y << 16), __builtin_bit_cast(float, raw.y & 0xffff0000u)};
;                         v[bj][1] = (f32x4){__builtin_bit_cast(float, raw.z << 16), __builtin_bit_cast(float, raw.z & 0xffff0000u), __builtin_bit_cast(float, raw.w << 16), __builtin_bit_cast(float, raw.w & 0xffff0000u)}; }
;                 }
; #pragma unroll
;                 for (int bj = 0; bj < 2; ++bj) {
;                     f32x4 v0 = v[bj][0] + acc[ai][bj][m][0] * alpha, v1 = v[bj][1] + acc[ai][bj][m][1] * alpha;
;                     if (HAS_BIAS) { v0 += bv[bj][0]; v1 += bv[bj][1]; }
;                     if (outf) { *(f32x4*)(outf + off + bj * HALF) = v0; *(f32x4*)(outf + off + bj * HALF + 4) = v1; }
;                     else *(u32x4*)(xb + off + bj * HALF) = pack8(v0, v1);
;                     q += (v0[0] * v0[0] + v0[1] * v0[1]) + (v0[2] * v0[2] + v0[3] * v0[3]) + (v1[0] * v1[0] + v1[1] * v1[1]) + (v1[2] * v1[2] + v1[3] * v1[3]); }
;                 q += __shfl_xor(q, 16); q += __shfl_xor(q, 32);
;                 if (fq == 0) ssp[(size_t)row * 16 + u.pn * 4 + wc] = q;
.LBB0_330:
	v_mov_b32_e32 v176, v147
	v_mov_b32_e32 v177, v178
	s_lshl_b32 s0, s13, 8
	s_add_i32 s0, s0, s43
	s_lshl_b32 s1, s12, 8
	s_or_b32 s1, s1, s44
	v_add_u32_e32 v176, s0, v176
	v_lshl_add_u32 v174, v177, 3, s1
	v_cmp_eq_u32_e32 vcc, 0, v177
	v_ashrrev_i32_e32 v177, 31, v176
	v_lshlrev_b64 v[182:183], 11, v[176:177]
	v_ashrrev_i32_e32 v175, 31, v174
	v_lshl_add_u64 v[182:183], s[16:17], 0, v[182:183]
	v_lshl_add_u64 v[76:77], v[174:175], 2, s[20:21]
	v_lshl_add_u64 v[186:187], v[174:175], 1, v[182:183]
	global_load_dwordx4 v[72:75], v[76:77], off offset:16
	global_load_dwordx4 v[80:83], v[76:77], off
	global_load_dwordx4 v[68:71], v[76:77], off offset:528
	s_nop 0
	global_load_dwordx4 v[76:79], v[76:77], off offset:512
	s_lshl_b32 s0, s12, 2
	global_load_dwordx4 v[182:185], v[186:187], off
	s_ashr_i32 s1, s0, 31
	s_waitcnt vmcnt(0)
	v_lshlrev_b32_e32 v188, 16, v182
	v_and_b32_e32 v189, 0xffff0000, v182
	v_lshlrev_b32_e32 v190, 16, v183
	v_and_b32_e32 v191, 0xffff0000, v183
	v_lshlrev_b32_e32 v208, 16, v184
	v_and_b32_e32 v209, 0xffff0000, v184
	v_lshlrev_b32_e32 v210, 16, v185
	v_and_b32_e32 v211, 0xffff0000, v185
	global_load_dwordx4 v[182:185], v[186:187], off offset:256
	v_pk_add_f32 v[140:141], v[140:141], v[188:189]
	v_pk_add_f32 v[142:143], v[142:143], v[190:191]
	v_pk_add_f32 v[136:137], v[136:137], v[208:209]
	v_pk_add_f32 v[138:139], v[138:139], v[210:211]
	v_pk_add_f32 v[142:143], v[82:83], v[142:143]
	v_pk_add_f32 v[140:141], v[80:81], v[140:141]
	v_pk_add_f32 v[188:189], v[72:73], v[136:137]
	v_cvt_pk_bf16_f32 v136, v140, v141
	v_cvt_pk_bf16_f32 v137, v142, v143
	v_pk_add_f32 v[190:191], v[74:75], v[138:139]
	v_cvt_pk_bf16_f32 v138, v188, v189
	s_waitcnt vmcnt(0)
	v_lshlrev_b32_e32 v212, 16, v182
	v_cvt_pk_bf16_f32 v139, v190, v191
	global_store_dwordx4 v[186:187], v[136:139], off
	v_and_b32_e32 v213, 0xffff0000, v182
	v_lshlrev_b32_e32 v182, 16, v183
	v_mul_f32_e32 v136, v140, v140
	v_mul_f32_e32 v137, v142, v142
	v_fmac_f32_e32 v136, v141, v141
	v_fmac_f32_e32 v137, v143, v143
	v_add_f32_e32 v136, v137, v136
	v_mul_f32_e32 v137, v188, v188
	v_and_b32_e32 v183, 0xffff0000, v183
	v_lshlrev_b32_e32 v214, 16, v184
	v_and_b32_e32 v215, 0xffff0000, v184
	v_fmac_f32_e32 v137, v189, v189
	v_lshlrev_b32_e32 v184, 16, v185
	v_and_b32_e32 v185, 0xffff0000, v185
	v_add_f32_e32 v136, v137, v136
	v_mul_f32_e32 v137, v191, v191
	v_pk_add_f32 v[132:133], v[132:133], v[212:213]
	v_pk_add_f32 v[134:135], v[134:135], v[182:183]
	v_pk_add_f32 v[128:129], v[128:129], v[214:215]
	v_fmac_f32_e32 v137, v190, v190
	v_pk_add_f32 v[130:131], v[130:131], v[184:185]
	v_pk_add_f32 v[134:135], v[78:79], v[134:135]
	v_pk_add_f32 v[132:133], v[76:77], v[132:133]
	v_pk_add_f32 v[138:139], v[68:69], v[128:129]
	v_cvt_pk_bf16_f32 v128, v132, v133
	v_cvt_pk_bf16_f32 v129, v134, v135
	v_add_f32_e32 v140, v137, v136
	v_pk_add_f32 v[136:137], v[70:71], v[130:131]
	v_cvt_pk_bf16_f32 v130, v138, v139
	s_nop 0
	v_cvt_pk_bf16_f32 v131, v136, v137
	global_store_dwordx4 v[186:187], v[128:131], off offset:256
	s_nop 1
	v_mul_f32_e32 v128, v132, v132
	v_mul_f32_e32 v129, v134, v134
	v_fmac_f32_e32 v128, v133, v133
	v_fmac_f32_e32 v129, v135, v135
	v_add_f32_e32 v128, v129, v128
	v_mul_f32_e32 v129, v138, v138
	v_fmac_f32_e32 v129, v139, v139
	v_add_f32_e32 v128, v129, v128
	v_mul_f32_e32 v129, v136, v136
	v_fmac_f32_e32 v129, v137, v137
	v_and_b32_e32 v130, 64, v192
	v_add_f32_e32 v128, v129, v128
	v_xor_b32_e32 v129, 16, v192
	v_add_u32_e32 v131, 64, v130
	v_cmp_lt_i32_e64 s[12:13], v129, v131
	v_add_f32_e32 v128, v140, v128
	s_nop 0
	v_cndmask_b32_e64 v129, v192, v129, s[12:13]
	v_lshlrev_b32_e32 v130, 2, v129
	v_mov_b32_e32 v129, v128
	s_nop 1
	v_permlane16_swap_b32_e32 v129, v128
	s_waitcnt lgkmcnt(0)
	v_add_f32_e32 v128, v128, v129
	v_xor_b32_e32 v129, 32, v192
	v_cmp_lt_i32_e64 s[12:13], v129, v131
	s_nop 1
	v_cndmask_b32_e64 v129, v192, v129, s[12:13]
	v_lshlrev_b32_e32 v131, 2, v129
	v_mov_b32_e32 v129, v128
	s_nop 1
	v_permlane32_swap_b32_e32 v129, v128
	s_and_saveexec_b64 s[2:3], vcc
	s_cbranch_execz .LBB0_332
	v_lshlrev_b64 v[132:133], 6, v[176:177]
	v_lshl_add_u64 v[132:133], s[18:19], 0, v[132:133]
	v_lshl_add_u64 v[132:133], s[0:1], 2, v[132:133]
	s_lshl_b32 s88, s42, 2
	v_lshl_add_u64 v[132:133], v[132:133], 0, s[88:89]
	s_waitcnt lgkmcnt(0)
	v_add_f32_e32 v128, v128, v129
	global_store_dword v[132:133], v128, off
; __device__ __forceinline__ u32x4 pack8(const f32x4& a, const f32x4& b) { u32x4 w; w.x = cvt_pk_bf16(a[0], a[1]); w.y = cvt_pk_bf16(a[2], a[3]); w.z = cvt_pk_bf16(b[0], b[1]); w.w = cvt_pk_bf16(b[2], b[3]); return w; }
;     __device__ __forceinline__ void operator()(const f32x4 (&acc)[2][2][4][2], const Unit& u, int ui, int wr, int wc, int fr, int fq) const {
;     ...
;             for (int m = 0; m < 4; ++m) { const int row = row0 + ai * HALF + m * 16; const size_t off = (size_t)row * 1024 + col0; float q = 0.f;
;                 f32x4 v[2][2];
;                 if (basef) {
; #pragma unroll
;                     for (int bj = 0; bj < 2; ++bj) { v[bj][0] = *(const f32x4*)(basef + off + bj * HALF); v[bj][1] = *(const f32x4*)(basef + off + bj * HALF + 4); }
;                 } else {
; #pragma unroll
;                     for (int bj = 0; bj < 2; ++bj) { const u32x4 raw = *(const u32x4*)(xb + off + bj * HALF);
;                         v[bj][0] = (f32x4){__builtin_bit_cast(float, raw.x << 16), __builtin_bit_cast(float, raw.x & 0xffff0000u), __builtin_bit_cast(float, raw.y << 16), __builtin_bit_cast(float, raw.y & 0xffff0000u)};
;                         v[bj][1] = (f32x4){__builtin_bit_cast(float, raw.z << 16), __builtin_bit_cast(float, raw.z & 0xffff0000u), __builtin_bit_cast(float, raw.w << 16), __builtin_bit_cast(float, raw.w & 0xffff0000u)}; }
;                 }
; #pragma unroll
;                 for (int bj = 0; bj < 2; ++bj) {
;                     f32x4 v0 = v[bj][0] + acc[ai][bj][m][0] * alpha, v1 = v[bj][1] + acc[ai][bj][m][1] * alpha;
;                     if (HAS_BIAS) { v0 += bv[bj][0]; v1 += bv[bj][1]; }
;                     if (outf) { *(f32x4*)(outf + off + bj * HALF) = v0; *(f32x4*)(outf + off + bj * HALF + 4) = v1; }
;                     else *(u32x4*)(xb + off + bj * HALF) = pack8(v0, v1);
;                     q += (v0[0] * v0[0] + v0[1] * v0[1]) + (v0[2] * v0[2] + v0[3] * v0[3]) + (v1[0] * v1[0] + v1[1] * v1[1]) + (v1[2] * v1[2] + v1[3] * v1[3]); }
;                 q += __shfl_xor(q, 16); q += __shfl_xor(q, 32);
;                 if (fq == 0) ssp[(size_t)row * 16 + u.pn * 4 + wc] = q;
.LBB0_332:
	s_or_b64 exec, exec, s[2:3]
	v_add_u32_e32 v128, 16, v176
	s_waitcnt lgkmcnt(0)
	v_ashrrev_i32_e32 v129, 31, v128
	v_lshlrev_b64 v[132:133], 11, v[128:129]
	v_lshl_add_u64 v[132:133], s[16:17], 0, v[132:133]
	v_lshl_add_u64 v[140:141], v[174:175], 1, v[132:133]
	global_load_dwordx4 v[132:135], v[140:141], off
	global_load_dwordx4 v[136:139], v[140:141], off offset:256
	s_waitcnt vmcnt(1)
	v_lshlrev_b32_e32 v142, 16, v132
	v_and_b32_e32 v143, 0xffff0000, v132
	v_lshlrev_b32_e32 v132, 16, v133
	v_and_b32_e32 v133, 0xffff0000, v133
	s_waitcnt vmcnt(0)
	v_lshlrev_b32_e32 v184, 16, v136
	v_and_b32_e32 v185, 0xffff0000, v136
	v_lshlrev_b32_e32 v136, 16, v137
	v_and_b32_e32 v137, 0xffff0000, v137
	v_lshlrev_b32_e32 v182, 16, v134
	v_and_b32_e32 v183, 0xffff0000, v134
	v_lshlrev_b32_e32 v186, 16, v138
	v_and_b32_e32 v187, 0xffff0000, v138
	v_lshlrev_b32_e32 v138, 16, v139
	v_and_b32_e32 v139, 0xffff0000, v139
	v_pk_add_f32 v[124:125], v[124:125], v[142:143]
	v_pk_add_f32 v[126:127], v[126:127], v[132:133]
	v_pk_add_f32 v[116:117], v[116:117], v[184:185]
	v_pk_add_f32 v[118:119], v[118:119], v[136:137]
	v_lshlrev_b32_e32 v134, 16, v135
	v_and_b32_e32 v135, 0xffff0000, v135
	v_pk_add_f32 v[120:121], v[120:121], v[182:183]
	v_pk_add_f32 v[112:113], v[112:113], v[186:187]
	v_pk_add_f32 v[114:115], v[114:115], v[138:139]
	v_pk_add_f32 v[126:127], v[82:83], v[126:127]
	v_pk_add_f32 v[124:125], v[80:81], v[124:125]
	v_pk_add_f32 v[118:119], v[78:79], v[118:119]
	v_pk_add_f32 v[116:117], v[76:77], v[116:117]
	v_pk_add_f32 v[122:123], v[122:123], v[134:135]
	v_pk_add_f32 v[120:121], v[72:73], v[120:121]
	v_pk_add_f32 v[132:133], v[70:71], v[114:115]
	v_pk_add_f32 v[134:135], v[68:69], v[112:113]
	v_mul_f32_e32 v114, v124, v124
	v_mul_f32_e32 v115, v126, v126
	v_mul_f32_e32 v136, v116, v116
	v_mul_f32_e32 v137, v118, v118
	v_pk_add_f32 v[122:123], v[74:75], v[122:123]
	v_cvt_pk_bf16_f32 v112, v124, v125
	v_mul_f32_e32 v124, v120, v120
	v_mul_f32_e32 v138, v134, v134
	v_fmac_f32_e32 v114, v125, v125
	v_fmac_f32_e32 v115, v127, v127
	v_fmac_f32_e32 v136, v117, v117
	v_fmac_f32_e32 v137, v119, v119
	v_cvt_pk_bf16_f32 v113, v126, v127
	v_mul_f32_e32 v126, v123, v123
	v_mul_f32_e32 v139, v132, v132
	v_fmac_f32_e32 v124, v121, v121
	v_fmac_f32_e32 v138, v135, v135
	v_add_f32_e32 v114, v115, v114
	v_add_f32_e32 v115, v137, v136
	v_fmac_f32_e32 v126, v122, v122
	v_fmac_f32_e32 v139, v133, v133
	v_add_f32_e32 v114, v124, v114
	v_add_f32_e32 v115, v138, v115
	v_add_f32_e32 v114, v126, v114
	v_add_f32_e32 v115, v139, v115
	v_add_f32_e32 v124, v114, v115
	v_mov_b32_e32 v125, v124
	s_nop 1
	v_permlane16_swap_b32_e32 v125, v124
	v_cvt_pk_bf16_f32 v114, v120, v121
	v_cvt_pk_bf16_f32 v115, v122, v123
	global_store_dwordx4 v[140:141], v[112:115], off
	s_waitcnt lgkmcnt(0)
	s_nop 0
	v_add_f32_e32 v112, v124, v125
	v_mov_b32_e32 v113, v112
	s_nop 1
	v_permlane32_swap_b32_e32 v113, v112
	v_cvt_pk_bf16_f32 v114, v116, v117
	v_cvt_pk_bf16_f32 v115, v118, v119
	v_cvt_pk_bf16_f32 v116, v134, v135
	v_cvt_pk_bf16_f32 v117, v132, v133
	global_store_dwordx4 v[140:141], v[114:117], off offset:256
	s_and_saveexec_b64 s[2:3], vcc
	s_cbranch_execz .LBB0_334
	v_lshlrev_b64 v[114:115], 6, v[128:129]
	v_lshl_add_u64 v[114:115], s[18:19], 0, v[114:115]
	v_lshl_add_u64 v[114:115], s[0:1], 2, v[114:115]
	s_lshl_b32 s88, s42, 2
	v_lshl_add_u64 v[114:115], v[114:115], 0, s[88:89]
	s_waitcnt lgkmcnt(0)
	v_add_f32_e32 v112, v112, v113
	global_store_dword v[114:115], v112, off
.LBB0_334:
	s_or_b64 exec, exec, s[2:3]
	v_add_u32_e32 v112, 32, v176
	s_waitcnt lgkmcnt(0)
	v_ashrrev_i32_e32 v113, 31, v112
	v_lshlrev_b64 v[114:115], 11, v[112:113]
	v_lshl_add_u64 v[114:115], s[16:17], 0, v[114:115]
	v_lshl_add_u64 v[122:123], v[174:175], 1, v[114:115]
	global_load_dwordx4 v[114:117], v[122:123], off
	global_load_dwordx4 v[118:121], v[122:123], off offset:256
	s_waitcnt vmcnt(1)
	v_lshlrev_b32_e32 v124, 16, v114
	v_and_b32_e32 v125, 0xffff0000, v114
	v_lshlrev_b32_e32 v114, 16, v115
	v_and_b32_e32 v115, 0xffff0000, v115
	s_waitcnt vmcnt(0)
	v_lshlrev_b32_e32 v128, 16, v118
	v_and_b32_e32 v129, 0xffff0000, v118
	v_lshlrev_b32_e32 v118, 16, v119
	v_and_b32_e32 v119, 0xffff0000, v119
	v_lshlrev_b32_e32 v126, 16, v116
	v_and_b32_e32 v127, 0xffff0000, v116
	v_lshlrev_b32_e32 v132, 16, v120
	v_and_b32_e32 v133, 0xffff0000, v120
	v_lshlrev_b32_e32 v120, 16, v121
	v_and_b32_e32 v121, 0xffff0000, v121
	v_pk_add_f32 v[108:109], v[108:109], v[124:125]
	v_pk_add_f32 v[110:111], v[110:111], v[114:115]
	v_pk_add_f32 v[100:101], v[100:101], v[128:129]
	v_pk_add_f32 v[102:103], v[102:103], v[118:119]
	v_lshlrev_b32_e32 v116, 16, v117
	v_and_b32_e32 v117, 0xffff0000, v117
	v_pk_add_f32 v[104:105], v[104:105], v[126:127]
	v_pk_add_f32 v[96:97], v[96:97], v[132:133]
	v_pk_add_f32 v[98:99], v[98:99], v[120:121]
	v_pk_add_f32 v[110:111], v[82:83], v[110:111]
	v_pk_add_f32 v[108:109], v[80:81], v[108:109]
	v_pk_add_f32 v[102:103], v[78:79], v[102:103]
	v_pk_add_f32 v[100:101], v[76:77], v[100:101]
	v_pk_add_f32 v[106:107], v[106:107], v[116:117]
	v_pk_add_f32 v[104:105], v[72:73], v[104:105]
	v_pk_add_f32 v[114:115], v[70:71], v[98:99]
	v_pk_add_f32 v[116:117], v[68:69], v[96:97]
	v_mul_f32_e32 v98, v108, v108
	v_mul_f32_e32 v99, v110, v110
	v_mul_f32_e32 v118, v100, v100
	v_mul_f32_e32 v119, v102, v102
	v_pk_add_f32 v[106:107], v[74:75], v[106:107]
	v_cvt_pk_bf16_f32 v96, v108, v109
	v_mul_f32_e32 v108, v104, v104
	v_mul_f32_e32 v120, v116, v116
	v_fmac_f32_e32 v98, v109, v109
	v_fmac_f32_e32 v99, v111, v111
	v_fmac_f32_e32 v118, v101, v101
	v_fmac_f32_e32 v119, v103, v103
	v_cvt_pk_bf16_f32 v97, v110, v111
	v_mul_f32_e32 v110, v107, v107
	v_mul_f32_e32 v121, v114, v114
	v_fmac_f32_e32 v108, v105, v105
	v_fmac_f32_e32 v120, v117, v117
	v_add_f32_e32 v98, v99, v98
	v_add_f32_e32 v99, v119, v118
	v_fmac_f32_e32 v110, v106, v106
	v_fmac_f32_e32 v121, v115, v115
	v_add_f32_e32 v98, v108, v98
	v_add_f32_e32 v99, v120, v99
	v_add_f32_e32 v98, v110, v98
	v_add_f32_e32 v99, v121, v99
	v_add_f32_e32 v108, v98, v99
	v_mov_b32_e32 v109, v108
	s_nop 1
	v_permlane16_swap_b32_e32 v109, v108
	v_cvt_pk_bf16_f32 v98, v104, v105
	v_cvt_pk_bf16_f32 v99, v106, v107
	global_store_dwordx4 v[122:123], v[96:99], off
	s_waitcnt lgkmcnt(0)
	s_nop 0
	v_add_f32_e32 v96, v108, v109
	v_mov_b32_e32 v97, v96
	s_nop 1
	v_permlane32_swap_b32_e32 v97, v96
	v_cvt_pk_bf16_f32 v98, v100, v101
	v_cvt_pk_bf16_f32 v99, v102, v103
	v_cvt_pk_bf16_f32 v100, v116, v117
	v_cvt_pk_bf16_f32 v101, v114, v115
	global_store_dwordx4 v[122:123], v[98:101], off offset:256
	s_and_saveexec_b64 s[2:3], vcc
	s_movk_i32 s59, 0x1600
	s_cbranch_execz .LBB0_336
	v_lshlrev_b64 v[98:99], 6, v[112:113]
	v_lshl_add_u64 v[98:99], s[18:19], 0, v[98:99]
	v_lshl_add_u64 v[98:99], s[0:1], 2, v[98:99]
	s_lshl_b32 s88, s42, 2
	v_lshl_add_u64 v[98:99], v[98:99], 0, s[88:89]
	s_waitcnt lgkmcnt(0)
	v_add_f32_e32 v96, v96, v97
	global_store_dword v[98:99], v96, off
; __device__ __forceinline__ u32x4 pack8(const f32x4& a, const f32x4& b) { u32x4 w; w.x = cvt_pk_bf16(a[0], a[1]); w.y = cvt_pk_bf16(a[2], a[3]); w.z = cvt_pk_bf16(b[0], b[1]); w.w = cvt_pk_bf16(b[2], b[3]); return w; }
;     __device__ __forceinline__ void operator()(const f32x4 (&acc)[2][2][4][2], const Unit& u, int ui, int wr, int wc, int fr, int fq) const {
;     ...
;             for (int m = 0; m < 4; ++m) { const int row = row0 + ai * HALF + m * 16; const size_t off = (size_t)row * 1024 + col0; float q = 0.f;
;                 f32x4 v[2][2];
;                 if (basef) {
; #pragma unroll
;                     for (int bj = 0; bj < 2; ++bj) { v[bj][0] = *(const f32x4*)(basef + off + bj * HALF); v[bj][1] = *(const f32x4*)(basef + off + bj * HALF + 4); }
;                 } else {
; #pragma unroll
;                     for (int bj = 0; bj < 2; ++bj) { const u32x4 raw = *(const u32x4*)(xb + off + bj * HALF);
;                         v[bj][0] = (f32x4){__builtin_bit_cast(float, raw.x << 16), __builtin_bit_cast(float, raw.x & 0xffff0000u), __builtin_bit_cast(float, raw.y << 16), __builtin_bit_cast(float, raw.y & 0xffff0000u)};
;                         v[bj][1] = (f32x4){__builtin_bit_cast(float, raw.z << 16), __builtin_bit_cast(float, raw.z & 0xffff0000u), __builtin_bit_cast(float, raw.w << 16), __builtin_bit_cast(float, raw.w & 0xffff0000u)}; }
;                 }
; #pragma unroll
;                 for (int bj = 0; bj < 2; ++bj) {
;                     f32x4 v0 = v[bj][0] + acc[ai][bj][m][0] * alpha, v1 = v[bj][1] + acc[ai][bj][m][1] * alpha;
;                     if (HAS_BIAS) { v0 += bv[bj][0]; v1 += bv[bj][1]; }
;                     if (outf) { *(f32x4*)(outf + off + bj * HALF) = v0; *(f32x4*)(outf + off + bj * HALF + 4) = v1; }
;                     else *(u32x4*)(xb + off + bj * HALF) = pack8(v0, v1);
;                     q += (v0[0] * v0[0] + v0[1] * v0[1]) + (v0[2] * v0[2] + v0[3] * v0[3]) + (v1[0] * v1[0] + v1[1] * v1[1]) + (v1[2] * v1[2] + v1[3] * v1[3]); }
;                 q += __shfl_xor(q, 16); q += __shfl_xor(q, 32);
;                 if (fq == 0) ssp[(size_t)row * 16 + u.pn * 4 + wc] = q;
.LBB0_336:
	s_or_b64 exec, exec, s[2:3]
	v_add_u32_e32 v96, 48, v176
	s_waitcnt lgkmcnt(0)
	v_ashrrev_i32_e32 v97, 31, v96
	v_lshlrev_b64 v[98:99], 11, v[96:97]
	v_lshl_add_u64 v[98:99], s[16:17], 0, v[98:99]
	v_lshl_add_u64 v[106:107], v[174:175], 1, v[98:99]
	global_load_dwordx4 v[98:101], v[106:107], off
	global_load_dwordx4 v[102:105], v[106:107], off offset:256
	s_waitcnt vmcnt(1)
	v_lshlrev_b32_e32 v108, 16, v98
	v_and_b32_e32 v109, 0xffff0000, v98
	v_lshlrev_b32_e32 v98, 16, v99
	v_and_b32_e32 v99, 0xffff0000, v99
	s_waitcnt vmcnt(0)
	v_lshlrev_b32_e32 v112, 16, v102
	v_and_b32_e32 v113, 0xffff0000, v102
	v_lshlrev_b32_e32 v102, 16, v103
	v_and_b32_e32 v103, 0xffff0000, v103
	v_lshlrev_b32_e32 v110, 16, v100
	v_and_b32_e32 v111, 0xffff0000, v100
	v_lshlrev_b32_e32 v114, 16, v104
	v_and_b32_e32 v115, 0xffff0000, v104
	v_lshlrev_b32_e32 v104, 16, v105
	v_and_b32_e32 v105, 0xffff0000, v105
	v_pk_add_f32 v[92:93], v[92:93], v[108:109]
	v_pk_add_f32 v[94:95], v[94:95], v[98:99]
	v_pk_add_f32 v[84:85], v[84:85], v[112:113]
	v_pk_add_f32 v[86:87], v[86:87], v[102:103]
	v_lshlrev_b32_e32 v100, 16, v101
	v_and_b32_e32 v101, 0xffff0000, v101
	v_pk_add_f32 v[88:89], v[88:89], v[110:111]
	v_pk_add_f32 v[64:65], v[64:65], v[114:115]
	v_pk_add_f32 v[66:67], v[66:67], v[104:105]
	v_pk_add_f32 v[94:95], v[82:83], v[94:95]
	v_pk_add_f32 v[92:93], v[80:81], v[92:93]
	v_pk_add_f32 v[86:87], v[78:79], v[86:87]
	v_pk_add_f32 v[84:85], v[76:77], v[84:85]
	v_pk_add_f32 v[90:91], v[90:91], v[100:101]
	v_pk_add_f32 v[88:89], v[72:73], v[88:89]
	v_pk_add_f32 v[98:99], v[70:71], v[66:67]
	v_pk_add_f32 v[100:101], v[68:69], v[64:65]
	v_mul_f32_e32 v66, v92, v92
	v_mul_f32_e32 v67, v94, v94
	v_mul_f32_e32 v102, v84, v84
	v_mul_f32_e32 v103, v86, v86
	v_pk_add_f32 v[90:91], v[74:75], v[90:91]
	v_cvt_pk_bf16_f32 v64, v92, v93
	v_mul_f32_e32 v92, v88, v88
	v_mul_f32_e32 v104, v100, v100
	v_fmac_f32_e32 v66, v93, v93
	v_fmac_f32_e32 v67, v95, v95
	v_fmac_f32_e32 v102, v85, v85
	v_fmac_f32_e32 v103, v87, v87
	v_cvt_pk_bf16_f32 v65, v94, v95
	v_mul_f32_e32 v94, v91, v91
	v_mul_f32_e32 v105, v98, v98
	v_fmac_f32_e32 v92, v89, v89
	v_fmac_f32_e32 v104, v101, v101
	v_add_f32_e32 v66, v67, v66
	v_add_f32_e32 v67, v103, v102
	v_fmac_f32_e32 v94, v90, v90
	v_fmac_f32_e32 v105, v99, v99
	v_add_f32_e32 v66, v92, v66
	v_add_f32_e32 v67, v104, v67
	v_add_f32_e32 v66, v94, v66
	v_add_f32_e32 v67, v105, v67
	v_add_f32_e32 v92, v66, v67
	v_mov_b32_e32 v93, v92
	s_nop 1
	v_permlane16_swap_b32_e32 v93, v92
	v_cvt_pk_bf16_f32 v66, v88, v89
	v_cvt_pk_bf16_f32 v67, v90, v91
	global_store_dwordx4 v[106:107], v[64:67], off
	v_cvt_pk_bf16_f32 v84, v84, v85
	v_cvt_pk_bf16_f32 v85, v86, v87
	v_cvt_pk_bf16_f32 v86, v100, v101
	v_cvt_pk_bf16_f32 v87, v98, v99
	global_store_dwordx4 v[106:107], v[84:87], off offset:256
	s_waitcnt lgkmcnt(0)
	v_add_f32_e32 v64, v92, v93
	v_mov_b32_e32 v65, v64
	s_nop 1
	v_permlane32_swap_b32_e32 v65, v64
	s_and_saveexec_b64 s[2:3], vcc
	s_cbranch_execz .LBB0_338
	v_lshlrev_b64 v[66:67], 6, v[96:97]
	v_lshl_add_u64 v[66:67], s[18:19], 0, v[66:67]
	v_lshl_add_u64 v[66:67], s[0:1], 2, v[66:67]
	s_lshl_b32 s88, s42, 2
	v_lshl_add_u64 v[66:67], v[66:67], 0, s[88:89]
	s_waitcnt lgkmcnt(0)
	v_add_f32_e32 v64, v64, v65
	global_store_dword v[66:67], v64, off
.LBB0_338:
	s_or_b64 exec, exec, s[2:3]
	v_add_u32_e32 v64, 0x80, v176
	s_waitcnt lgkmcnt(0)
	v_ashrrev_i32_e32 v65, 31, v64
	v_lshlrev_b64 v[66:67], 11, v[64:65]
	v_lshl_add_u64 v[66:67], s[16:17], 0, v[66:67]
	v_lshl_add_u64 v[66:67], v[174:175], 1, v[66:67]
	global_load_dwordx4 v[84:87], v[66:67], off
	global_load_dwordx4 v[88:91], v[66:67], off offset:256
	s_waitcnt vmcnt(1)
	v_lshlrev_b32_e32 v92, 16, v84
	v_and_b32_e32 v93, 0xffff0000, v84
	v_lshlrev_b32_e32 v84, 16, v85
	v_and_b32_e32 v85, 0xffff0000, v85
	s_waitcnt vmcnt(0)
	v_lshlrev_b32_e32 v96, 16, v88
	v_and_b32_e32 v97, 0xffff0000, v88
	v_lshlrev_b32_e32 v88, 16, v89
	v_and_b32_e32 v89, 0xffff0000, v89
	v_lshlrev_b32_e32 v94, 16, v86
	v_and_b32_e32 v95, 0xffff0000, v86
	v_lshlrev_b32_e32 v98, 16, v90
	v_and_b32_e32 v99, 0xffff0000, v90
	v_lshlrev_b32_e32 v90, 16, v91
	v_and_b32_e32 v91, 0xffff0000, v91
	v_pk_add_f32 v[60:61], v[60:61], v[92:93]
	v_pk_add_f32 v[62:63], v[62:63], v[84:85]
	v_pk_add_f32 v[52:53], v[52:53], v[96:97]
	v_pk_add_f32 v[54:55], v[54:55], v[88:89]
	v_lshlrev_b32_e32 v86, 16, v87
	v_and_b32_e32 v87, 0xffff0000, v87
	v_pk_add_f32 v[56:57], v[56:57], v[94:95]
	v_pk_add_f32 v[48:49], v[48:49], v[98:99]
	v_pk_add_f32 v[50:51], v[50:51], v[90:91]
	v_pk_add_f32 v[62:63], v[82:83], v[62:63]
	v_pk_add_f32 v[60:61], v[80:81], v[60:61]
	v_pk_add_f32 v[54:55], v[78:79], v[54:55]
	v_pk_add_f32 v[52:53], v[76:77], v[52:53]
	v_pk_add_f32 v[58:59], v[58:59], v[86:87]
	v_pk_add_f32 v[56:57], v[72:73], v[56:57]
	v_pk_add_f32 v[84:85], v[70:71], v[50:51]
	v_pk_add_f32 v[86:87], v[68:69], v[48:49]
	v_mul_f32_e32 v50, v60, v60
	v_mul_f32_e32 v51, v62, v62
	v_mul_f32_e32 v88, v52, v52
	v_mul_f32_e32 v89, v54, v54
	v_pk_add_f32 v[58:59], v[74:75], v[58:59]
	v_cvt_pk_bf16_f32 v48, v60, v61
	v_mul_f32_e32 v60, v56, v56
	v_mul_f32_e32 v90, v86, v86
	v_fmac_f32_e32 v50, v61, v61
	v_fmac_f32_e32 v51, v63, v63
	v_fmac_f32_e32 v88, v53, v53
	v_fmac_f32_e32 v89, v55, v55
	v_cvt_pk_bf16_f32 v49, v62, v63
	v_mul_f32_e32 v62, v59, v59
	v_mul_f32_e32 v91, v84, v84
	v_fmac_f32_e32 v60, v57, v57
	v_fmac_f32_e32 v90, v87, v87
	v_add_f32_e32 v50, v51, v50
	v_add_f32_e32 v51, v89, v88
	v_fmac_f32_e32 v62, v58, v58
	v_fmac_f32_e32 v91, v85, v85
	v_add_f32_e32 v50, v60, v50
	v_add_f32_e32 v51, v90, v51
	v_add_f32_e32 v50, v62, v50
	v_add_f32_e32 v51, v91, v51
	v_add_f32_e32 v60, v50, v51
	v_mov_b32_e32 v61, v60
	s_nop 1
	v_permlane16_swap_b32_e32 v61, v60
	v_cvt_pk_bf16_f32 v50, v56, v57
	v_cvt_pk_bf16_f32 v51, v58, v59
	global_store_dwordx4 v[66:67], v[48:51], off
	s_waitcnt lgkmcnt(0)
	s_nop 0
	v_add_f32_e32 v48, v60, v61
	v_mov_b32_e32 v49, v48
	s_nop 1
	v_permlane32_swap_b32_e32 v49, v48
	v_cvt_pk_bf16_f32 v50, v52, v53
	v_cvt_pk_bf16_f32 v51, v54, v55
	v_cvt_pk_bf16_f32 v52, v86, v87
	v_cvt_pk_bf16_f32 v53, v84, v85
	global_store_dwordx4 v[66:67], v[50:53], off offset:256
	s_and_saveexec_b64 s[2:3], vcc
	s_cbranch_execz .LBB0_340
	v_lshlrev_b64 v[50:51], 6, v[64:65]
	v_lshl_add_u64 v[50:51], s[18:19], 0, v[50:51]
	v_lshl_add_u64 v[50:51], s[0:1], 2, v[50:51]
	s_lshl_b32 s88, s42, 2
	v_lshl_add_u64 v[50:51], v[50:51], 0, s[88:89]
	s_waitcnt lgkmcnt(0)
	v_add_f32_e32 v48, v48, v49
	global_store_dword v[50:51], v48, off
; __device__ __forceinline__ u32x4 pack8(const f32x4& a, const f32x4& b) { u32x4 w; w.x = cvt_pk_bf16(a[0], a[1]); w.y = cvt_pk_bf16(a[2], a[3]); w.z = cvt_pk_bf16(b[0], b[1]); w.w = cvt_pk_bf16(b[2], b[3]); return w; }
;     __device__ __forceinline__ void operator()(const f32x4 (&acc)[2][2][4][2], const Unit& u, int ui, int wr, int wc, int fr, int fq) const {
;     ...
;             for (int m = 0; m < 4; ++m) { const int row = row0 + ai * HALF + m * 16; const size_t off = (size_t)row * 1024 + col0; float q = 0.f;
;                 f32x4 v[2][2];
;                 if (basef) {
; #pragma unroll
;                     for (int bj = 0; bj < 2; ++bj) { v[bj][0] = *(const f32x4*)(basef + off + bj * HALF); v[bj][1] = *(const f32x4*)(basef + off + bj * HALF + 4); }
;                 } else {
; #pragma unroll
;                     for (int bj = 0; bj < 2; ++bj) { const u32x4 raw = *(const u32x4*)(xb + off + bj * HALF);
;                         v[bj][0] = (f32x4){__builtin_bit_cast(float, raw.x << 16), __builtin_bit_cast(float, raw.x & 0xffff0000u), __builtin_bit_cast(float, raw.y << 16), __builtin_bit_cast(float, raw.y & 0xffff0000u)};
;                         v[bj][1] = (f32x4){__builtin_bit_cast(float, raw.z << 16), __builtin_bit_cast(float, raw.z & 0xffff0000u), __builtin_bit_cast(float, raw.w << 16), __builtin_bit_cast(float, raw.w & 0xffff0000u)}; }
;                 }
; #pragma unroll
;                 for (int bj = 0; bj < 2; ++bj) {
;                     f32x4 v0 = v[bj][0] + acc[ai][bj][m][0] * alpha, v1 = v[bj][1] + acc[ai][bj][m][1] * alpha;
;                     if (HAS_BIAS) { v0 += bv[bj][0]; v1 += bv[bj][1]; }
;                     if (outf) { *(f32x4*)(outf + off + bj * HALF) = v0; *(f32x4*)(outf + off + bj * HALF + 4) = v1; }
;                     else *(u32x4*)(xb + off + bj * HALF) = pack8(v0, v1);
;                     q += (v0[0] * v0[0] + v0[1] * v0[1]) + (v0[2] * v0[2] + v0[3] * v0[3]) + (v1[0] * v1[0] + v1[1] * v1[1]) + (v1[2] * v1[2] + v1[3] * v1[3]); }
;                 q += __shfl_xor(q, 16); q += __shfl_xor(q, 32);
;                 if (fq == 0) ssp[(size_t)row * 16 + u.pn * 4 + wc] = q;
.LBB0_340:
	s_or_b64 exec, exec, s[2:3]
	v_add_u32_e32 v48, 0x90, v176
	s_waitcnt lgkmcnt(0)
	v_ashrrev_i32_e32 v49, 31, v48
	v_lshlrev_b64 v[50:51], 11, v[48:49]
	v_lshl_add_u64 v[50:51], s[16:17], 0, v[50:51]
	v_lshl_add_u64 v[58:59], v[174:175], 1, v[50:51]
	global_load_dwordx4 v[50:53], v[58:59], off
	global_load_dwordx4 v[54:57], v[58:59], off offset:256
	s_waitcnt vmcnt(1)
	v_lshlrev_b32_e32 v60, 16, v50
	v_and_b32_e32 v61, 0xffff0000, v50
	v_lshlrev_b32_e32 v50, 16, v51
	v_and_b32_e32 v51, 0xffff0000, v51
	s_waitcnt vmcnt(0)
	v_lshlrev_b32_e32 v64, 16, v54
	v_and_b32_e32 v65, 0xffff0000, v54
	v_lshlrev_b32_e32 v54, 16, v55
	v_and_b32_e32 v55, 0xffff0000, v55
	v_lshlrev_b32_e32 v62, 16, v52
	v_and_b32_e32 v63, 0xffff0000, v52
	v_lshlrev_b32_e32 v66, 16, v56
	v_and_b32_e32 v67, 0xffff0000, v56
	v_lshlrev_b32_e32 v56, 16, v57
	v_and_b32_e32 v57, 0xffff0000, v57
	v_pk_add_f32 v[44:45], v[44:45], v[60:61]
	v_pk_add_f32 v[46:47], v[46:47], v[50:51]
	v_pk_add_f32 v[36:37], v[36:37], v[64:65]
	v_pk_add_f32 v[38:39], v[38:39], v[54:55]
	v_lshlrev_b32_e32 v52, 16, v53
	v_and_b32_e32 v53, 0xffff0000, v53
	v_pk_add_f32 v[40:41], v[40:41], v[62:63]
	v_pk_add_f32 v[32:33], v[32:33], v[66:67]
	v_pk_add_f32 v[34:35], v[34:35], v[56:57]
	v_pk_add_f32 v[46:47], v[82:83], v[46:47]
	v_pk_add_f32 v[44:45], v[80:81], v[44:45]
	v_pk_add_f32 v[38:39], v[78:79], v[38:39]
	v_pk_add_f32 v[36:37], v[76:77], v[36:37]
	v_pk_add_f32 v[42:43], v[42:43], v[52:53]
	v_pk_add_f32 v[40:41], v[72:73], v[40:41]
	v_pk_add_f32 v[50:51], v[70:71], v[34:35]
	v_pk_add_f32 v[52:53], v[68:69], v[32:33]
	v_mul_f32_e32 v34, v44, v44
	v_mul_f32_e32 v35, v46, v46
	v_mul_f32_e32 v54, v36, v36
	v_mul_f32_e32 v55, v38, v38
	v_pk_add_f32 v[42:43], v[74:75], v[42:43]
	v_cvt_pk_bf16_f32 v32, v44, v45
	v_mul_f32_e32 v44, v40, v40
	v_mul_f32_e32 v56, v52, v52
	v_fmac_f32_e32 v34, v45, v45
	v_fmac_f32_e32 v35, v47, v47
	v_fmac_f32_e32 v54, v37, v37
	v_fmac_f32_e32 v55, v39, v39
	v_cvt_pk_bf16_f32 v33, v46, v47
	v_mul_f32_e32 v46, v43, v43
	v_mul_f32_e32 v57, v50, v50
	v_fmac_f32_e32 v44, v41, v41
	v_fmac_f32_e32 v56, v53, v53
	v_add_f32_e32 v34, v35, v34
	v_add_f32_e32 v35, v55, v54
	v_fmac_f32_e32 v46, v42, v42
	v_fmac_f32_e32 v57, v51, v51
	v_add_f32_e32 v34, v44, v34
	v_add_f32_e32 v35, v56, v35
	v_add_f32_e32 v34, v46, v34
	v_add_f32_e32 v35, v57, v35
	v_add_f32_e32 v44, v34, v35
	v_mov_b32_e32 v45, v44
	s_nop 1
	v_permlane16_swap_b32_e32 v45, v44
	v_cvt_pk_bf16_f32 v34, v40, v41
	v_cvt_pk_bf16_f32 v35, v42, v43
	global_store_dwordx4 v[58:59], v[32:35], off
	s_waitcnt lgkmcnt(0)
	s_nop 0
	v_add_f32_e32 v32, v44, v45
	v_mov_b32_e32 v33, v32
	s_nop 1
	v_permlane32_swap_b32_e32 v33, v32
	v_cvt_pk_bf16_f32 v34, v36, v37
	v_cvt_pk_bf16_f32 v35, v38, v39
	v_cvt_pk_bf16_f32 v36, v52, v53
	v_cvt_pk_bf16_f32 v37, v50, v51
	global_store_dwordx4 v[58:59], v[34:37], off offset:256
	s_and_saveexec_b64 s[2:3], vcc
	s_cbranch_execz .LBB0_342
	v_lshlrev_b64 v[34:35], 6, v[48:49]
	v_lshl_add_u64 v[34:35], s[18:19], 0, v[34:35]
	v_lshl_add_u64 v[34:35], s[0:1], 2, v[34:35]
	s_lshl_b32 s88, s42, 2
	v_lshl_add_u64 v[34:35], v[34:35], 0, s[88:89]
	s_waitcnt lgkmcnt(0)
	v_add_f32_e32 v32, v32, v33
	global_store_dword v[34:35], v32, off
; __device__ __forceinline__ u32x4 pack8(const f32x4& a, const f32x4& b) { u32x4 w; w.x = cvt_pk_bf16(a[0], a[1]); w.y = cvt_pk_bf16(a[2], a[3]); w.z = cvt_pk_bf16(b[0], b[1]); w.w = cvt_pk_bf16(b[2], b[3]); return w; }
;     __device__ __forceinline__ void operator()(const f32x4 (&acc)[2][2][4][2], const Unit& u, int ui, int wr, int wc, int fr, int fq) const {
;     ...
;             for (int m = 0; m < 4; ++m) { const int row = row0 + ai * HALF + m * 16; const size_t off = (size_t)row * 1024 + col0; float q = 0.f;
;                 f32x4 v[2][2];
;                 if (basef) {
; #pragma unroll
;                     for (int bj = 0; bj < 2; ++bj) { v[bj][0] = *(const f32x4*)(basef + off + bj * HALF); v[bj][1] = *(const f32x4*)(basef + off + bj * HALF + 4); }
;                 } else {
; #pragma unroll
;                     for (int bj = 0; bj < 2; ++bj) { const u32x4 raw = *(const u32x4*)(xb + off + bj * HALF);
;                         v[bj][0] = (f32x4){__builtin_bit_cast(float, raw.x << 16), __builtin_bit_cast(float, raw.x & 0xffff0000u), __builtin_bit_cast(float, raw.y << 16), __builtin_bit_cast(float, raw.y & 0xffff0000u)};
;                         v[bj][1] = (f32x4){__builtin_bit_cast(float, raw.z << 16), __builtin_bit_cast(float, raw.z & 0xffff0000u), __builtin_bit_cast(float, raw.w << 16), __builtin_bit_cast(float, raw.w & 0xffff0000u)}; }
;                 }
; #pragma unroll
;                 for (int bj = 0; bj < 2; ++bj) {
;                     f32x4 v0 = v[bj][0] + acc[ai][bj][m][0] * alpha, v1 = v[bj][1] + acc[ai][bj][m][1] * alpha;
;                     if (HAS_BIAS) { v0 += bv[bj][0]; v1 += bv[bj][1]; }
;                     if (outf) { *(f32x4*)(outf + off + bj * HALF) = v0; *(f32x4*)(outf + off + bj * HALF + 4) = v1; }
;                     else *(u32x4*)(xb + off + bj * HALF) = pack8(v0, v1);
;                     q += (v0[0] * v0[0] + v0[1] * v0[1]) + (v0[2] * v0[2] + v0[3] * v0[3]) + (v1[0] * v1[0] + v1[1] * v1[1]) + (v1[2] * v1[2] + v1[3] * v1[3]); }
;                 q += __shfl_xor(q, 16); q += __shfl_xor(q, 32);
;                 if (fq == 0) ssp[(size_t)row * 16 + u.pn * 4 + wc] = q;
.LBB0_342:
	s_or_b64 exec, exec, s[2:3]
	v_add_u32_e32 v32, 0xa0, v176
	s_waitcnt lgkmcnt(0)
	v_ashrrev_i32_e32 v33, 31, v32
	v_lshlrev_b64 v[34:35], 11, v[32:33]
	v_lshl_add_u64 v[34:35], s[16:17], 0, v[34:35]
	v_lshl_add_u64 v[42:43], v[174:175], 1, v[34:35]
	global_load_dwordx4 v[34:37], v[42:43], off
	global_load_dwordx4 v[38:41], v[42:43], off offset:256
	s_waitcnt vmcnt(1)
	v_lshlrev_b32_e32 v44, 16, v34
	v_and_b32_e32 v45, 0xffff0000, v34
	v_lshlrev_b32_e32 v34, 16, v35
	v_and_b32_e32 v35, 0xffff0000, v35
	s_waitcnt vmcnt(0)
	v_lshlrev_b32_e32 v48, 16, v38
	v_and_b32_e32 v49, 0xffff0000, v38
	v_lshlrev_b32_e32 v38, 16, v39
	v_and_b32_e32 v39, 0xffff0000, v39
	v_lshlrev_b32_e32 v46, 16, v36
	v_and_b32_e32 v47, 0xffff0000, v36
	v_lshlrev_b32_e32 v50, 16, v40
	v_and_b32_e32 v51, 0xffff0000, v40
	v_lshlrev_b32_e32 v40, 16, v41
	v_and_b32_e32 v41, 0xffff0000, v41
	v_pk_add_f32 v[28:29], v[28:29], v[44:45]
	v_pk_add_f32 v[30:31], v[30:31], v[34:35]
	v_pk_add_f32 v[20:21], v[20:21], v[48:49]
	v_pk_add_f32 v[22:23], v[22:23], v[38:39]
	v_lshlrev_b32_e32 v36, 16, v37
	v_and_b32_e32 v37, 0xffff0000, v37
	v_pk_add_f32 v[24:25], v[24:25], v[46:47]
	v_pk_add_f32 v[16:17], v[16:17], v[50:51]
	v_pk_add_f32 v[18:19], v[18:19], v[40:41]
	v_pk_add_f32 v[30:31], v[82:83], v[30:31]
	v_pk_add_f32 v[28:29], v[80:81], v[28:29]
	v_pk_add_f32 v[22:23], v[78:79], v[22:23]
	v_pk_add_f32 v[20:21], v[76:77], v[20:21]
	v_pk_add_f32 v[26:27], v[26:27], v[36:37]
	v_pk_add_f32 v[24:25], v[72:73], v[24:25]
	v_pk_add_f32 v[34:35], v[70:71], v[18:19]
	v_pk_add_f32 v[36:37], v[68:69], v[16:17]
	v_mul_f32_e32 v18, v28, v28
	v_mul_f32_e32 v19, v30, v30
	v_mul_f32_e32 v38, v20, v20
	v_mul_f32_e32 v39, v22, v22
	v_pk_add_f32 v[26:27], v[74:75], v[26:27]
	v_cvt_pk_bf16_f32 v16, v28, v29
	v_mul_f32_e32 v28, v24, v24
	v_mul_f32_e32 v40, v36, v36
	v_fmac_f32_e32 v18, v29, v29
	v_fmac_f32_e32 v19, v31, v31
	v_fmac_f32_e32 v38, v21, v21
	v_fmac_f32_e32 v39, v23, v23
	v_cvt_pk_bf16_f32 v17, v30, v31
	v_mul_f32_e32 v30, v27, v27
	v_mul_f32_e32 v41, v34, v34
	v_fmac_f32_e32 v28, v25, v25
	v_fmac_f32_e32 v40, v37, v37
	v_add_f32_e32 v18, v19, v18
	v_add_f32_e32 v19, v39, v38
	v_fmac_f32_e32 v30, v26, v26
	v_fmac_f32_e32 v41, v35, v35
	v_add_f32_e32 v18, v28, v18
	v_add_f32_e32 v19, v40, v19
	v_add_f32_e32 v18, v30, v18
	v_add_f32_e32 v19, v41, v19
	v_add_f32_e32 v28, v18, v19
	v_mov_b32_e32 v29, v28
	s_nop 1
	v_permlane16_swap_b32_e32 v29, v28
	v_cvt_pk_bf16_f32 v18, v24, v25
	v_cvt_pk_bf16_f32 v19, v26, v27
	global_store_dwordx4 v[42:43], v[16:19], off
	s_waitcnt lgkmcnt(0)
	s_nop 0
	v_add_f32_e32 v16, v28, v29
	v_mov_b32_e32 v17, v16
	s_nop 1
	v_permlane32_swap_b32_e32 v17, v16
	v_cvt_pk_bf16_f32 v18, v20, v21
	v_cvt_pk_bf16_f32 v19, v22, v23
	v_cvt_pk_bf16_f32 v20, v36, v37
	v_cvt_pk_bf16_f32 v21, v34, v35
	global_store_dwordx4 v[42:43], v[18:21], off offset:256
	s_and_saveexec_b64 s[2:3], vcc
	s_cbranch_execz .LBB0_344
	v_lshlrev_b64 v[18:19], 6, v[32:33]
	v_lshl_add_u64 v[18:19], s[18:19], 0, v[18:19]
	v_lshl_add_u64 v[18:19], s[0:1], 2, v[18:19]
	s_lshl_b32 s88, s42, 2
	v_lshl_add_u64 v[18:19], v[18:19], 0, s[88:89]
	s_waitcnt lgkmcnt(0)
	v_add_f32_e32 v16, v16, v17
	global_store_dword v[18:19], v16, off
.LBB0_344:
	s_or_b64 exec, exec, s[2:3]
	v_add_u32_e32 v16, 0xb0, v176
	s_waitcnt lgkmcnt(0)
	v_ashrrev_i32_e32 v17, 31, v16
	v_lshlrev_b64 v[18:19], 11, v[16:17]
	v_lshl_add_u64 v[18:19], s[16:17], 0, v[18:19]
	v_lshl_add_u64 v[26:27], v[174:175], 1, v[18:19]
	global_load_dwordx4 v[18:21], v[26:27], off
	global_load_dwordx4 v[22:25], v[26:27], off offset:256
	s_waitcnt vmcnt(1)
	v_lshlrev_b32_e32 v28, 16, v18
	v_and_b32_e32 v29, 0xffff0000, v18
	v_lshlrev_b32_e32 v18, 16, v19
	v_and_b32_e32 v19, 0xffff0000, v19
	s_waitcnt vmcnt(0)
	v_lshlrev_b32_e32 v32, 16, v22
	v_and_b32_e32 v33, 0xffff0000, v22
	v_lshlrev_b32_e32 v22, 16, v23
	v_and_b32_e32 v23, 0xffff0000, v23
	v_lshlrev_b32_e32 v30, 16, v20
	v_and_b32_e32 v31, 0xffff0000, v20
	v_lshlrev_b32_e32 v34, 16, v24
	v_and_b32_e32 v35, 0xffff0000, v24
	v_lshlrev_b32_e32 v24, 16, v25
	v_and_b32_e32 v25, 0xffff0000, v25
	v_pk_add_f32 v[12:13], v[12:13], v[28:29]
	v_pk_add_f32 v[14:15], v[14:15], v[18:19]
	v_pk_add_f32 v[4:5], v[4:5], v[32:33]
	v_pk_add_f32 v[6:7], v[6:7], v[22:23]
	v_lshlrev_b32_e32 v20, 16, v21
	v_and_b32_e32 v21, 0xffff0000, v21
	v_pk_add_f32 v[8:9], v[8:9], v[30:31]
	v_pk_add_f32 v[0:1], v[0:1], v[34:35]
	v_pk_add_f32 v[2:3], v[2:3], v[24:25]
	v_pk_add_f32 v[14:15], v[82:83], v[14:15]
	v_pk_add_f32 v[12:13], v[80:81], v[12:13]
	v_pk_add_f32 v[6:7], v[78:79], v[6:7]
	v_pk_add_f32 v[4:5], v[76:77], v[4:5]
	v_pk_add_f32 v[10:11], v[10:11], v[20:21]
	v_pk_add_f32 v[8:9], v[72:73], v[8:9]
	v_pk_add_f32 v[18:19], v[70:71], v[2:3]
	v_pk_add_f32 v[20:21], v[68:69], v[0:1]
	v_mul_f32_e32 v2, v12, v12
	v_mul_f32_e32 v3, v14, v14
	v_mul_f32_e32 v22, v4, v4
	v_mul_f32_e32 v23, v6, v6
	v_pk_add_f32 v[10:11], v[74:75], v[10:11]
	v_cvt_pk_bf16_f32 v0, v12, v13
	v_mul_f32_e32 v12, v8, v8
	v_mul_f32_e32 v24, v20, v20
	v_fmac_f32_e32 v2, v13, v13
	v_fmac_f32_e32 v3, v15, v15
	v_fmac_f32_e32 v22, v5, v5
	v_fmac_f32_e32 v23, v7, v7
	v_cvt_pk_bf16_f32 v1, v14, v15
	v_mul_f32_e32 v14, v11, v11
	v_mul_f32_e32 v25, v18, v18
	v_fmac_f32_e32 v12, v9, v9
	v_fmac_f32_e32 v24, v21, v21
	v_add_f32_e32 v2, v3, v2
	v_add_f32_e32 v3, v23, v22
	v_fmac_f32_e32 v14, v10, v10
	v_fmac_f32_e32 v25, v19, v19
	v_add_f32_e32 v2, v12, v2
	v_add_f32_e32 v3, v24, v3
	v_add_f32_e32 v2, v14, v2
	v_add_f32_e32 v3, v25, v3
	v_add_f32_e32 v12, v2, v3
	v_mov_b32_e32 v13, v12
	s_nop 1
	v_permlane16_swap_b32_e32 v13, v12
	v_cvt_pk_bf16_f32 v2, v8, v9
	v_cvt_pk_bf16_f32 v3, v10, v11
	global_store_dwordx4 v[26:27], v[0:3], off
	s_waitcnt lgkmcnt(0)
	s_nop 0
	v_add_f32_e32 v0, v12, v13
	v_mov_b32_e32 v1, v0
	s_nop 1
	v_permlane32_swap_b32_e32 v1, v0
	v_cvt_pk_bf16_f32 v2, v4, v5
	v_cvt_pk_bf16_f32 v3, v6, v7
	v_cvt_pk_bf16_f32 v4, v20, v21
	v_cvt_pk_bf16_f32 v5, v18, v19
	global_store_dwordx4 v[26:27], v[2:5], off offset:256
	s_and_saveexec_b64 s[2:3], vcc
	s_cbranch_execz .LBB0_346
	v_lshlrev_b64 v[2:3], 6, v[16:17]
	v_lshl_add_u64 v[2:3], s[18:19], 0, v[2:3]
	v_lshl_add_u64 v[2:3], s[0:1], 2, v[2:3]
	s_lshl_b32 s88, s42, 2
	v_lshl_add_u64 v[2:3], v[2:3], 0, s[88:89]
	s_waitcnt lgkmcnt(0)
	v_add_f32_e32 v0, v0, v1
	global_store_dword v[2:3], v0, off

; __device__ __forceinline__ u32x4 pack8(const f32x4& a, const f32x4& b) { u32x4 w; w.x = cvt_pk_bf16(a[0], a[1]); w.y = cvt_pk_bf16(a[2], a[3]); w.z = cvt_pk_bf16(b[0], b[1]); w.w = cvt_pk_bf16(b[2], b[3]); return w; }
;     __device__ __forceinline__ void operator()(const f32x4 (&acc)[2][2][4][2], const Unit& u, int ui, int wr, int wc, int fr, int fq) const {
;     ...
;             for (int m = 0; m < 4; ++m) { const int row = row0 + ai * HALF + m * 16; const size_t off = (size_t)row * 1024 + col0; float q = 0.f;
;                 f32x4 v[2][2];
;                 if (basef) {
; #pragma unroll
;                     for (int bj = 0; bj < 2; ++bj) { v[bj][0] = *(const f32x4*)(basef + off + bj * HALF); v[bj][1] = *(const f32x4*)(basef + off + bj * HALF + 4); }
;                 } else {
; #pragma unroll
;                     for (int bj = 0; bj < 2; ++bj) { const u32x4 raw = *(const u32x4*)(xb + off + bj * HALF);
;                         v[bj][0] = (f32x4){__builtin_bit_cast(float, raw.x << 16), __builtin_bit_cast(float, raw.x & 0xffff0000u), __builtin_bit_cast(float, raw.y << 16), __builtin_bit_cast(float, raw.y & 0xffff0000u)};
;                         v[bj][1] = (f32x4){__builtin_bit_cast(float, raw.z << 16), __builtin_bit_cast(float, raw.z & 0xffff0000u), __builtin_bit_cast(float, raw.w << 16), __builtin_bit_cast(float, raw.w & 0xffff0000u)}; }
;                 }
; #pragma unroll
;                 for (int bj = 0; bj < 2; ++bj) {
;                     f32x4 v0 = v[bj][0] + acc[ai][bj][m][0] * alpha, v1 = v[bj][1] + acc[ai][bj][m][1] * alpha;
;                     if (HAS_BIAS) { v0 += bv[bj][0]; v1 += bv[bj][1]; }
;                     if (outf) { *(f32x4*)(outf + off + bj * HALF) = v0; *(f32x4*)(outf + off + bj * HALF + 4) = v1; }
;                     else *(u32x4*)(xb + off + bj * HALF) = pack8(v0, v1);
;                     q += (v0[0] * v0[0] + v0[1] * v0[1]) + (v0[2] * v0[2] + v0[3] * v0[3]) + (v1[0] * v1[0] + v1[1] * v1[1]) + (v1[2] * v1[2] + v1[3] * v1[3]); }
;                 q += __shfl_xor(q, 16); q += __shfl_xor(q, 32);
;                 if (fq == 0) ssp[(size_t)row * 16 + u.pn * 4 + wc] = q;
.LBB0_551:
	s_waitcnt vmcnt(0)
	v_pk_fma_f32 v[124:125], v[124:125], 0.5, v[140:141] op_sel_hi:[1,0,1]
	v_pk_fma_f32 v[126:127], v[126:127], 0.5, v[142:143] op_sel_hi:[1,0,1]
	v_pk_fma_f32 v[138:139], v[122:123], 0.5, v[138:139] op_sel_hi:[1,0,1]
	v_pk_fma_f32 v[122:123], v[120:121], 0.5, v[136:137] op_sel_hi:[1,0,1]
	v_cvt_pk_bf16_f32 v120, v124, v125
	v_mul_f32_e32 v124, v124, v124
	v_fmac_f32_e32 v124, v125, v125
	v_mul_f32_e32 v125, v126, v126
	v_fmac_f32_e32 v125, v127, v127
	v_add_f32_e32 v124, v125, v124
	v_mul_f32_e32 v125, v122, v122
	v_pk_fma_f32 v[118:119], v[118:119], 0.5, v[134:135] op_sel_hi:[1,0,1]
	v_pk_fma_f32 v[116:117], v[116:117], 0.5, v[132:133] op_sel_hi:[1,0,1]
	v_cvt_pk_bf16_f32 v121, v126, v127
	v_fmac_f32_e32 v125, v123, v123
	v_pk_fma_f32 v[126:127], v[112:113], 0.5, v[128:129] op_sel_hi:[1,0,1]
	v_mul_f32_e32 v112, v116, v116
	v_mul_f32_e32 v113, v118, v118
	v_add_f32_e32 v124, v125, v124
	v_mul_f32_e32 v125, v139, v139
	v_fmac_f32_e32 v112, v117, v117
	v_fmac_f32_e32 v113, v119, v119
	v_fmac_f32_e32 v125, v138, v138
	v_add_f32_e32 v112, v113, v112
	v_mul_f32_e32 v113, v126, v126
	v_add_f32_e32 v136, v125, v124
	v_pk_fma_f32 v[124:125], v[114:115], 0.5, v[130:131] op_sel_hi:[1,0,1]
	v_fmac_f32_e32 v113, v127, v127
	v_add_f32_e32 v112, v113, v112
	v_mul_f32_e32 v113, v124, v124
	v_fmac_f32_e32 v113, v125, v125
	v_and_b32_e32 v114, 64, v192
	v_add_f32_e32 v112, v113, v112
	v_xor_b32_e32 v113, 16, v192
	v_add_u32_e32 v115, 64, v114
	v_cmp_lt_i32_e32 vcc, v113, v115
	v_add_f32_e32 v112, v136, v112
	s_lshl_b32 s0, s56, 2
	v_cndmask_b32_e32 v113, v192, v113, vcc
	v_lshlrev_b32_e32 v132, 2, v113
	v_mov_b32_e32 v113, v112
	s_nop 1
	v_permlane16_swap_b32_e32 v113, v112
	v_cmp_eq_u32_e64 s[10:11], 0, v183
	s_ashr_i32 s1, s0, 31
	v_cvt_pk_bf16_f32 v122, v122, v123
	v_cvt_pk_bf16_f32 v123, v138, v139
	s_waitcnt lgkmcnt(0)
	v_add_f32_e32 v112, v112, v113
	v_xor_b32_e32 v113, 32, v192
	v_cmp_lt_i32_e32 vcc, v113, v115
	global_store_dwordx4 v[178:179], v[120:123], off
	v_cvt_pk_bf16_f32 v114, v116, v117
	v_cvt_pk_bf16_f32 v115, v118, v119
	v_cvt_pk_bf16_f32 v116, v126, v127
	v_cvt_pk_bf16_f32 v117, v124, v125
	s_nop 0
	v_cndmask_b32_e32 v113, v192, v113, vcc
	v_lshlrev_b32_e32 v133, 2, v113
	v_mov_b32_e32 v113, v112
	s_nop 1
	v_permlane32_swap_b32_e32 v113, v112
	global_store_dwordx4 v[178:179], v[114:117], off offset:256
	s_and_saveexec_b64 s[2:3], s[10:11]
	s_cbranch_execz .LBB0_553
	v_lshlrev_b64 v[114:115], 6, v[176:177]
	v_lshl_add_u64 v[114:115], s[20:21], 0, v[114:115]
	v_lshl_add_u64 v[114:115], s[0:1], 2, v[114:115]
	s_lshl_b32 s88, s44, 2
	v_lshl_add_u64 v[114:115], v[114:115], 0, s[88:89]
	s_waitcnt lgkmcnt(0)
	v_add_f32_e32 v112, v112, v113
	global_store_dword v[114:115], v112, off

; __device__ __forceinline__ u32x4 pack8(const f32x4& a, const f32x4& b) { u32x4 w; w.x = cvt_pk_bf16(a[0], a[1]); w.y = cvt_pk_bf16(a[2], a[3]); w.z = cvt_pk_bf16(b[0], b[1]); w.w = cvt_pk_bf16(b[2], b[3]); return w; }
;     __device__ __forceinline__ void operator()(const f32x4 (&acc)[2][2][4][2], const Unit& u, int ui, int wr, int wc, int fr, int fq) const {
;     ...
;             for (int m = 0; m < 4; ++m) { const int row = row0 + ai * HALF + m * 16; const size_t off = (size_t)row * 1024 + col0; float q = 0.f;
;                 f32x4 v[2][2];
;                 if (basef) {
; #pragma unroll
;                     for (int bj = 0; bj < 2; ++bj) { v[bj][0] = *(const f32x4*)(basef + off + bj * HALF); v[bj][1] = *(const f32x4*)(basef + off + bj * HALF + 4); }
;                 } else {
; #pragma unroll
;                     for (int bj = 0; bj < 2; ++bj) { const u32x4 raw = *(const u32x4*)(xb + off + bj * HALF);
;                         v[bj][0] = (f32x4){__builtin_bit_cast(float, raw.x << 16), __builtin_bit_cast(float, raw.x & 0xffff0000u), __builtin_bit_cast(float, raw.y << 16), __builtin_bit_cast(float, raw.y & 0xffff0000u)};
;                         v[bj][1] = (f32x4){__builtin_bit_cast(float, raw.z << 16), __builtin_bit_cast(float, raw.z & 0xffff0000u), __builtin_bit_cast(float, raw.w << 16), __builtin_bit_cast(float, raw.w & 0xffff0000u)}; }
;                 }
; #pragma unroll
;                 for (int bj = 0; bj < 2; ++bj) {
;                     f32x4 v0 = v[bj][0] + acc[ai][bj][m][0] * alpha, v1 = v[bj][1] + acc[ai][bj][m][1] * alpha;
;                     if (HAS_BIAS) { v0 += bv[bj][0]; v1 += bv[bj][1]; }
;                     if (outf) { *(f32x4*)(outf + off + bj * HALF) = v0; *(f32x4*)(outf + off + bj * HALF + 4) = v1; }
;                     else *(u32x4*)(xb + off + bj * HALF) = pack8(v0, v1);
;                     q += (v0[0] * v0[0] + v0[1] * v0[1]) + (v0[2] * v0[2] + v0[3] * v0[3]) + (v1[0] * v1[0] + v1[1] * v1[1]) + (v1[2] * v1[2] + v1[3] * v1[3]); }
;                 q += __shfl_xor(q, 16); q += __shfl_xor(q, 32);
;                 if (fq == 0) ssp[(size_t)row * 16 + u.pn * 4 + wc] = q;
.LBB0_556:
	s_waitcnt vmcnt(3)
	v_pk_fma_f32 v[108:109], v[108:109], 0.5, v[124:125] op_sel_hi:[1,0,1]
	v_pk_fma_f32 v[110:111], v[110:111], 0.5, v[126:127] op_sel_hi:[1,0,1]
	s_waitcnt vmcnt(2)
	v_pk_fma_f32 v[122:123], v[106:107], 0.5, v[122:123] op_sel_hi:[1,0,1]
	v_pk_fma_f32 v[106:107], v[104:105], 0.5, v[120:121] op_sel_hi:[1,0,1]
	v_cvt_pk_bf16_f32 v104, v108, v109
	v_mul_f32_e32 v108, v108, v108
	v_fmac_f32_e32 v108, v109, v109
	v_mul_f32_e32 v109, v110, v110
	v_fmac_f32_e32 v109, v111, v111
	v_add_f32_e32 v108, v109, v108
	v_mul_f32_e32 v109, v106, v106
	s_waitcnt vmcnt(1)
	v_pk_fma_f32 v[102:103], v[102:103], 0.5, v[118:119] op_sel_hi:[1,0,1]
	v_pk_fma_f32 v[100:101], v[100:101], 0.5, v[116:117] op_sel_hi:[1,0,1]
	v_cvt_pk_bf16_f32 v105, v110, v111
	v_fmac_f32_e32 v109, v107, v107
	s_waitcnt vmcnt(0)
	v_pk_fma_f32 v[110:111], v[96:97], 0.5, v[112:113] op_sel_hi:[1,0,1]
	v_mul_f32_e32 v96, v100, v100
	v_mul_f32_e32 v97, v102, v102
	v_add_f32_e32 v108, v109, v108
	v_mul_f32_e32 v109, v123, v123
	v_fmac_f32_e32 v96, v101, v101
	v_fmac_f32_e32 v97, v103, v103
	v_fmac_f32_e32 v109, v122, v122
	v_add_f32_e32 v96, v97, v96
	v_mul_f32_e32 v97, v110, v110
	v_add_f32_e32 v120, v109, v108
	v_pk_fma_f32 v[108:109], v[98:99], 0.5, v[114:115] op_sel_hi:[1,0,1]
	v_fmac_f32_e32 v97, v111, v111
	v_add_f32_e32 v96, v97, v96
	v_mul_f32_e32 v97, v108, v108
	v_fmac_f32_e32 v97, v109, v109
	v_add_f32_e32 v96, v97, v96
	v_add_f32_e32 v96, v120, v96
	v_mov_b32_e32 v97, v96
	s_nop 1
	v_permlane16_swap_b32_e32 v97, v96
	v_cvt_pk_bf16_f32 v106, v106, v107
	v_cvt_pk_bf16_f32 v107, v122, v123
	global_store_dwordx4 v[130:131], v[104:107], off
	v_cvt_pk_bf16_f32 v98, v100, v101
	s_waitcnt lgkmcnt(0)
	v_add_f32_e32 v96, v96, v97
	v_mov_b32_e32 v97, v96
	s_nop 1
	v_permlane32_swap_b32_e32 v97, v96
	v_cvt_pk_bf16_f32 v99, v102, v103
	v_cvt_pk_bf16_f32 v100, v110, v111
	v_cvt_pk_bf16_f32 v101, v108, v109
	global_store_dwordx4 v[130:131], v[98:101], off offset:256
	s_and_saveexec_b64 s[2:3], s[10:11]
	s_cbranch_execz .LBB0_558
	v_lshlrev_b64 v[98:99], 6, v[128:129]
	v_lshl_add_u64 v[98:99], s[20:21], 0, v[98:99]
	v_lshl_add_u64 v[98:99], s[0:1], 2, v[98:99]
	s_lshl_b32 s88, s44, 2
	v_lshl_add_u64 v[98:99], v[98:99], 0, s[88:89]
	s_waitcnt lgkmcnt(0)
	v_add_f32_e32 v96, v96, v97
	global_store_dword v[98:99], v96, off

; __device__ __forceinline__ u32x4 pack8(const f32x4& a, const f32x4& b) { u32x4 w; w.x = cvt_pk_bf16(a[0], a[1]); w.y = cvt_pk_bf16(a[2], a[3]); w.z = cvt_pk_bf16(b[0], b[1]); w.w = cvt_pk_bf16(b[2], b[3]); return w; }
;     __device__ __forceinline__ void operator()(const f32x4 (&acc)[2][2][4][2], const Unit& u, int ui, int wr, int wc, int fr, int fq) const {
;     ...
;             for (int m = 0; m < 4; ++m) { const int row = row0 + ai * HALF + m * 16; const size_t off = (size_t)row * 1024 + col0; float q = 0.f;
;                 f32x4 v[2][2];
;                 if (basef) {
; #pragma unroll
;                     for (int bj = 0; bj < 2; ++bj) { v[bj][0] = *(const f32x4*)(basef + off + bj * HALF); v[bj][1] = *(const f32x4*)(basef + off + bj * HALF + 4); }
;                 } else {
; #pragma unroll
;                     for (int bj = 0; bj < 2; ++bj) { const u32x4 raw = *(const u32x4*)(xb + off + bj * HALF);
;                         v[bj][0] = (f32x4){__builtin_bit_cast(float, raw.x << 16), __builtin_bit_cast(float, raw.x & 0xffff0000u), __builtin_bit_cast(float, raw.y << 16), __builtin_bit_cast(float, raw.y & 0xffff0000u)};
;                         v[bj][1] = (f32x4){__builtin_bit_cast(float, raw.z << 16), __builtin_bit_cast(float, raw.z & 0xffff0000u), __builtin_bit_cast(float, raw.w << 16), __builtin_bit_cast(float, raw.w & 0xffff0000u)}; }
;                 }
; #pragma unroll
;                 for (int bj = 0; bj < 2; ++bj) {
;                     f32x4 v0 = v[bj][0] + acc[ai][bj][m][0] * alpha, v1 = v[bj][1] + acc[ai][bj][m][1] * alpha;
;                     if (HAS_BIAS) { v0 += bv[bj][0]; v1 += bv[bj][1]; }
;                     if (outf) { *(f32x4*)(outf + off + bj * HALF) = v0; *(f32x4*)(outf + off + bj * HALF + 4) = v1; }
;                     else *(u32x4*)(xb + off + bj * HALF) = pack8(v0, v1);
;                     q += (v0[0] * v0[0] + v0[1] * v0[1]) + (v0[2] * v0[2] + v0[3] * v0[3]) + (v1[0] * v1[0] + v1[1] * v1[1]) + (v1[2] * v1[2] + v1[3] * v1[3]); }
;                 q += __shfl_xor(q, 16); q += __shfl_xor(q, 32);
;                 if (fq == 0) ssp[(size_t)row * 16 + u.pn * 4 + wc] = q;
.LBB0_561:
	s_waitcnt vmcnt(3)
	v_pk_fma_f32 v[92:93], v[92:93], 0.5, v[108:109] op_sel_hi:[1,0,1]
	v_pk_fma_f32 v[94:95], v[94:95], 0.5, v[110:111] op_sel_hi:[1,0,1]
	s_waitcnt vmcnt(2)
	v_pk_fma_f32 v[106:107], v[90:91], 0.5, v[106:107] op_sel_hi:[1,0,1]
	v_pk_fma_f32 v[90:91], v[88:89], 0.5, v[104:105] op_sel_hi:[1,0,1]
	v_cvt_pk_bf16_f32 v88, v92, v93
	v_mul_f32_e32 v92, v92, v92
	v_fmac_f32_e32 v92, v93, v93
	v_mul_f32_e32 v93, v94, v94
	v_fmac_f32_e32 v93, v95, v95
	v_add_f32_e32 v92, v93, v92
	v_mul_f32_e32 v93, v90, v90
	s_waitcnt vmcnt(1)
	v_pk_fma_f32 v[86:87], v[86:87], 0.5, v[102:103] op_sel_hi:[1,0,1]
	v_pk_fma_f32 v[84:85], v[84:85], 0.5, v[100:101] op_sel_hi:[1,0,1]
	v_cvt_pk_bf16_f32 v89, v94, v95
	v_fmac_f32_e32 v93, v91, v91
	s_waitcnt vmcnt(0)
	v_pk_fma_f32 v[94:95], v[80:81], 0.5, v[96:97] op_sel_hi:[1,0,1]
	v_mul_f32_e32 v80, v84, v84
	v_mul_f32_e32 v81, v86, v86
	v_add_f32_e32 v92, v93, v92
	v_mul_f32_e32 v93, v107, v107
	v_fmac_f32_e32 v80, v85, v85
	v_fmac_f32_e32 v81, v87, v87
	v_fmac_f32_e32 v93, v106, v106
	v_add_f32_e32 v80, v81, v80
	v_mul_f32_e32 v81, v94, v94
	v_add_f32_e32 v104, v93, v92
	v_pk_fma_f32 v[92:93], v[82:83], 0.5, v[98:99] op_sel_hi:[1,0,1]
	v_fmac_f32_e32 v81, v95, v95
	v_add_f32_e32 v80, v81, v80
	v_mul_f32_e32 v81, v92, v92
	v_fmac_f32_e32 v81, v93, v93
	v_add_f32_e32 v80, v81, v80
	v_add_f32_e32 v80, v104, v80
	v_mov_b32_e32 v81, v80
	s_nop 1
	v_permlane16_swap_b32_e32 v81, v80
	v_cvt_pk_bf16_f32 v90, v90, v91
	v_cvt_pk_bf16_f32 v91, v106, v107
	global_store_dwordx4 v[114:115], v[88:91], off
	v_cvt_pk_bf16_f32 v82, v84, v85
	s_waitcnt lgkmcnt(0)
	v_add_f32_e32 v80, v80, v81
	v_mov_b32_e32 v81, v80
	s_nop 1
	v_permlane32_swap_b32_e32 v81, v80
	v_cvt_pk_bf16_f32 v83, v86, v87
	v_cvt_pk_bf16_f32 v84, v94, v95
	v_cvt_pk_bf16_f32 v85, v92, v93
	global_store_dwordx4 v[114:115], v[82:85], off offset:256
	s_and_saveexec_b64 s[2:3], s[10:11]
	s_cbranch_execz .LBB0_563
	v_lshlrev_b64 v[82:83], 6, v[112:113]
	v_lshl_add_u64 v[82:83], s[20:21], 0, v[82:83]
	v_lshl_add_u64 v[82:83], s[0:1], 2, v[82:83]
	s_lshl_b32 s88, s44, 2
	v_lshl_add_u64 v[82:83], v[82:83], 0, s[88:89]
	s_waitcnt lgkmcnt(0)
	v_add_f32_e32 v80, v80, v81
	global_store_dword v[82:83], v80, off

; __device__ __forceinline__ u32x4 pack8(const f32x4& a, const f32x4& b) { u32x4 w; w.x = cvt_pk_bf16(a[0], a[1]); w.y = cvt_pk_bf16(a[2], a[3]); w.z = cvt_pk_bf16(b[0], b[1]); w.w = cvt_pk_bf16(b[2], b[3]); return w; }
;     __device__ __forceinline__ void operator()(const f32x4 (&acc)[2][2][4][2], const Unit& u, int ui, int wr, int wc, int fr, int fq) const {
;     ...
;             for (int m = 0; m < 4; ++m) { const int row = row0 + ai * HALF + m * 16; const size_t off = (size_t)row * 1024 + col0; float q = 0.f;
;                 f32x4 v[2][2];
;                 if (basef) {
; #pragma unroll
;                     for (int bj = 0; bj < 2; ++bj) { v[bj][0] = *(const f32x4*)(basef + off + bj * HALF); v[bj][1] = *(const f32x4*)(basef + off + bj * HALF + 4); }
;                 } else {
; #pragma unroll
;                     for (int bj = 0; bj < 2; ++bj) { const u32x4 raw = *(const u32x4*)(xb + off + bj * HALF);
;                         v[bj][0] = (f32x4){__builtin_bit_cast(float, raw.x << 16), __builtin_bit_cast(float, raw.x & 0xffff0000u), __builtin_bit_cast(float, raw.y << 16), __builtin_bit_cast(float, raw.y & 0xffff0000u)};
;                         v[bj][1] = (f32x4){__builtin_bit_cast(float, raw.z << 16), __builtin_bit_cast(float, raw.z & 0xffff0000u), __builtin_bit_cast(float, raw.w << 16), __builtin_bit_cast(float, raw.w & 0xffff0000u)}; }
;                 }
; #pragma unroll
;                 for (int bj = 0; bj < 2; ++bj) {
;                     f32x4 v0 = v[bj][0] + acc[ai][bj][m][0] * alpha, v1 = v[bj][1] + acc[ai][bj][m][1] * alpha;
;                     if (HAS_BIAS) { v0 += bv[bj][0]; v1 += bv[bj][1]; }
;                     if (outf) { *(f32x4*)(outf + off + bj * HALF) = v0; *(f32x4*)(outf + off + bj * HALF + 4) = v1; }
;                     else *(u32x4*)(xb + off + bj * HALF) = pack8(v0, v1);
;                     q += (v0[0] * v0[0] + v0[1] * v0[1]) + (v0[2] * v0[2] + v0[3] * v0[3]) + (v1[0] * v1[0] + v1[1] * v1[1]) + (v1[2] * v1[2] + v1[3] * v1[3]); }
;                 q += __shfl_xor(q, 16); q += __shfl_xor(q, 32);
;                 if (fq == 0) ssp[(size_t)row * 16 + u.pn * 4 + wc] = q;
.LBB0_566:
	s_waitcnt vmcnt(3)
	v_pk_fma_f32 v[76:77], v[76:77], 0.5, v[92:93] op_sel_hi:[1,0,1]
	v_pk_fma_f32 v[78:79], v[78:79], 0.5, v[94:95] op_sel_hi:[1,0,1]
	s_waitcnt vmcnt(2)
	v_pk_fma_f32 v[90:91], v[74:75], 0.5, v[90:91] op_sel_hi:[1,0,1]
	v_pk_fma_f32 v[74:75], v[72:73], 0.5, v[88:89] op_sel_hi:[1,0,1]
	v_cvt_pk_bf16_f32 v72, v76, v77
	v_mul_f32_e32 v76, v76, v76
	v_fmac_f32_e32 v76, v77, v77
	v_mul_f32_e32 v77, v78, v78
	v_fmac_f32_e32 v77, v79, v79
	v_add_f32_e32 v76, v77, v76
	v_mul_f32_e32 v77, v74, v74
	s_waitcnt vmcnt(1)
	v_pk_fma_f32 v[70:71], v[70:71], 0.5, v[86:87] op_sel_hi:[1,0,1]
	v_pk_fma_f32 v[68:69], v[68:69], 0.5, v[84:85] op_sel_hi:[1,0,1]
	v_cvt_pk_bf16_f32 v73, v78, v79
	v_fmac_f32_e32 v77, v75, v75
	s_waitcnt vmcnt(0)
	v_pk_fma_f32 v[78:79], v[64:65], 0.5, v[80:81] op_sel_hi:[1,0,1]
	v_mul_f32_e32 v64, v68, v68
	v_mul_f32_e32 v65, v70, v70
	v_add_f32_e32 v76, v77, v76
	v_mul_f32_e32 v77, v91, v91
	v_fmac_f32_e32 v64, v69, v69
	v_fmac_f32_e32 v65, v71, v71
	v_fmac_f32_e32 v77, v90, v90
	v_add_f32_e32 v64, v65, v64
	v_mul_f32_e32 v65, v78, v78
	v_add_f32_e32 v88, v77, v76
	v_pk_fma_f32 v[76:77], v[66:67], 0.5, v[82:83] op_sel_hi:[1,0,1]
	v_fmac_f32_e32 v65, v79, v79
	v_add_f32_e32 v64, v65, v64
	v_mul_f32_e32 v65, v76, v76
	v_fmac_f32_e32 v65, v77, v77
	v_add_f32_e32 v64, v65, v64
	v_add_f32_e32 v64, v88, v64
	v_mov_b32_e32 v65, v64
	s_nop 1
	v_permlane16_swap_b32_e32 v65, v64
	v_cvt_pk_bf16_f32 v74, v74, v75
	v_cvt_pk_bf16_f32 v75, v90, v91
	global_store_dwordx4 v[98:99], v[72:75], off
	v_cvt_pk_bf16_f32 v66, v68, v69
	s_waitcnt lgkmcnt(0)
	v_add_f32_e32 v64, v64, v65
	v_mov_b32_e32 v65, v64
	s_nop 1
	v_permlane32_swap_b32_e32 v65, v64
	v_cvt_pk_bf16_f32 v67, v70, v71
	v_cvt_pk_bf16_f32 v68, v78, v79
	v_cvt_pk_bf16_f32 v69, v76, v77
	global_store_dwordx4 v[98:99], v[66:69], off offset:256
	s_and_saveexec_b64 s[2:3], s[10:11]
	s_cbranch_execz .LBB0_568
	v_lshlrev_b64 v[66:67], 6, v[96:97]
	v_lshl_add_u64 v[66:67], s[20:21], 0, v[66:67]
	v_lshl_add_u64 v[66:67], s[0:1], 2, v[66:67]
	s_lshl_b32 s88, s44, 2
	v_lshl_add_u64 v[66:67], v[66:67], 0, s[88:89]
	s_waitcnt lgkmcnt(0)
	v_add_f32_e32 v64, v64, v65
	global_store_dword v[66:67], v64, off

; __device__ __forceinline__ u32x4 pack8(const f32x4& a, const f32x4& b) { u32x4 w; w.x = cvt_pk_bf16(a[0], a[1]); w.y = cvt_pk_bf16(a[2], a[3]); w.z = cvt_pk_bf16(b[0], b[1]); w.w = cvt_pk_bf16(b[2], b[3]); return w; }
;     __device__ __forceinline__ void operator()(const f32x4 (&acc)[2][2][4][2], const Unit& u, int ui, int wr, int wc, int fr, int fq) const {
;     ...
;             for (int m = 0; m < 4; ++m) { const int row = row0 + ai * HALF + m * 16; const size_t off = (size_t)row * 1024 + col0; float q = 0.f;
;                 f32x4 v[2][2];
;                 if (basef) {
; #pragma unroll
;                     for (int bj = 0; bj < 2; ++bj) { v[bj][0] = *(const f32x4*)(basef + off + bj * HALF); v[bj][1] = *(const f32x4*)(basef + off + bj * HALF + 4); }
;                 } else {
; #pragma unroll
;                     for (int bj = 0; bj < 2; ++bj) { const u32x4 raw = *(const u32x4*)(xb + off + bj * HALF);
;                         v[bj][0] = (f32x4){__builtin_bit_cast(float, raw.x << 16), __builtin_bit_cast(float, raw.x & 0xffff0000u), __builtin_bit_cast(float, raw.y << 16), __builtin_bit_cast(float, raw.y & 0xffff0000u)};
;                         v[bj][1] = (f32x4){__builtin_bit_cast(float, raw.z << 16), __builtin_bit_cast(float, raw.z & 0xffff0000u), __builtin_bit_cast(float, raw.w << 16), __builtin_bit_cast(float, raw.w & 0xffff0000u)}; }
;                 }
; #pragma unroll
;                 for (int bj = 0; bj < 2; ++bj) {
;                     f32x4 v0 = v[bj][0] + acc[ai][bj][m][0] * alpha, v1 = v[bj][1] + acc[ai][bj][m][1] * alpha;
;                     if (HAS_BIAS) { v0 += bv[bj][0]; v1 += bv[bj][1]; }
;                     if (outf) { *(f32x4*)(outf + off + bj * HALF) = v0; *(f32x4*)(outf + off + bj * HALF + 4) = v1; }
;                     else *(u32x4*)(xb + off + bj * HALF) = pack8(v0, v1);
;                     q += (v0[0] * v0[0] + v0[1] * v0[1]) + (v0[2] * v0[2] + v0[3] * v0[3]) + (v1[0] * v1[0] + v1[1] * v1[1]) + (v1[2] * v1[2] + v1[3] * v1[3]); }
;                 q += __shfl_xor(q, 16); q += __shfl_xor(q, 32);
;                 if (fq == 0) ssp[(size_t)row * 16 + u.pn * 4 + wc] = q;
.LBB0_571:
	s_waitcnt vmcnt(3)
	v_pk_fma_f32 v[60:61], v[60:61], 0.5, v[76:77] op_sel_hi:[1,0,1]
	v_pk_fma_f32 v[62:63], v[62:63], 0.5, v[78:79] op_sel_hi:[1,0,1]
	s_waitcnt vmcnt(2)
	v_pk_fma_f32 v[74:75], v[58:59], 0.5, v[74:75] op_sel_hi:[1,0,1]
	v_pk_fma_f32 v[58:59], v[56:57], 0.5, v[72:73] op_sel_hi:[1,0,1]
	v_cvt_pk_bf16_f32 v56, v60, v61
	v_mul_f32_e32 v60, v60, v60
	v_fmac_f32_e32 v60, v61, v61
	v_mul_f32_e32 v61, v62, v62
	v_fmac_f32_e32 v61, v63, v63
	v_add_f32_e32 v60, v61, v60
	v_mul_f32_e32 v61, v58, v58
	s_waitcnt vmcnt(1)
	v_pk_fma_f32 v[54:55], v[54:55], 0.5, v[70:71] op_sel_hi:[1,0,1]
	v_pk_fma_f32 v[52:53], v[52:53], 0.5, v[68:69] op_sel_hi:[1,0,1]
	v_cvt_pk_bf16_f32 v57, v62, v63
	v_fmac_f32_e32 v61, v59, v59
	s_waitcnt vmcnt(0)
	v_pk_fma_f32 v[62:63], v[48:49], 0.5, v[64:65] op_sel_hi:[1,0,1]
	v_mul_f32_e32 v48, v52, v52
	v_mul_f32_e32 v49, v54, v54
	v_add_f32_e32 v60, v61, v60
	v_mul_f32_e32 v61, v75, v75
	v_fmac_f32_e32 v48, v53, v53
	v_fmac_f32_e32 v49, v55, v55
	v_fmac_f32_e32 v61, v74, v74
	v_add_f32_e32 v48, v49, v48
	v_mul_f32_e32 v49, v62, v62
	v_add_f32_e32 v72, v61, v60
	v_pk_fma_f32 v[60:61], v[50:51], 0.5, v[66:67] op_sel_hi:[1,0,1]
	v_fmac_f32_e32 v49, v63, v63
	v_add_f32_e32 v48, v49, v48
	v_mul_f32_e32 v49, v60, v60
	v_fmac_f32_e32 v49, v61, v61
	v_add_f32_e32 v48, v49, v48
	v_add_f32_e32 v48, v72, v48
	v_mov_b32_e32 v49, v48
	s_nop 1
	v_permlane16_swap_b32_e32 v49, v48
	v_cvt_pk_bf16_f32 v58, v58, v59
	v_cvt_pk_bf16_f32 v59, v74, v75
	global_store_dwordx4 v[82:83], v[56:59], off
	v_cvt_pk_bf16_f32 v50, v52, v53
	s_waitcnt lgkmcnt(0)
	v_add_f32_e32 v48, v48, v49
	v_mov_b32_e32 v49, v48
	s_nop 1
	v_permlane32_swap_b32_e32 v49, v48
	v_cvt_pk_bf16_f32 v51, v54, v55
	v_cvt_pk_bf16_f32 v52, v62, v63
	v_cvt_pk_bf16_f32 v53, v60, v61
	global_store_dwordx4 v[82:83], v[50:53], off offset:256
	s_and_saveexec_b64 s[2:3], s[10:11]
	s_cbranch_execz .LBB0_573
	v_lshlrev_b64 v[50:51], 6, v[80:81]
	v_lshl_add_u64 v[50:51], s[20:21], 0, v[50:51]
	v_lshl_add_u64 v[50:51], s[0:1], 2, v[50:51]
	s_lshl_b32 s88, s44, 2
	v_lshl_add_u64 v[50:51], v[50:51], 0, s[88:89]
	s_waitcnt lgkmcnt(0)
	v_add_f32_e32 v48, v48, v49
	global_store_dword v[50:51], v48, off

; __device__ __forceinline__ u32x4 pack8(const f32x4& a, const f32x4& b) { u32x4 w; w.x = cvt_pk_bf16(a[0], a[1]); w.y = cvt_pk_bf16(a[2], a[3]); w.z = cvt_pk_bf16(b[0], b[1]); w.w = cvt_pk_bf16(b[2], b[3]); return w; }
;     __device__ __forceinline__ void operator()(const f32x4 (&acc)[2][2][4][2], const Unit& u, int ui, int wr, int wc, int fr, int fq) const {
;     ...
;             for (int m = 0; m < 4; ++m) { const int row = row0 + ai * HALF + m * 16; const size_t off = (size_t)row * 1024 + col0; float q = 0.f;
;                 f32x4 v[2][2];
;                 if (basef) {
; #pragma unroll
;                     for (int bj = 0; bj < 2; ++bj) { v[bj][0] = *(const f32x4*)(basef + off + bj * HALF); v[bj][1] = *(const f32x4*)(basef + off + bj * HALF + 4); }
;                 } else {
; #pragma unroll
;                     for (int bj = 0; bj < 2; ++bj) { const u32x4 raw = *(const u32x4*)(xb + off + bj * HALF);
;                         v[bj][0] = (f32x4){__builtin_bit_cast(float, raw.x << 16), __builtin_bit_cast(float, raw.x & 0xffff0000u), __builtin_bit_cast(float, raw.y << 16), __builtin_bit_cast(float, raw.y & 0xffff0000u)};
;                         v[bj][1] = (f32x4){__builtin_bit_cast(float, raw.z << 16), __builtin_bit_cast(float, raw.z & 0xffff0000u), __builtin_bit_cast(float, raw.w << 16), __builtin_bit_cast(float, raw.w & 0xffff0000u)}; }
;                 }
; #pragma unroll
;                 for (int bj = 0; bj < 2; ++bj) {
;                     f32x4 v0 = v[bj][0] + acc[ai][bj][m][0] * alpha, v1 = v[bj][1] + acc[ai][bj][m][1] * alpha;
;                     if (HAS_BIAS) { v0 += bv[bj][0]; v1 += bv[bj][1]; }
;                     if (outf) { *(f32x4*)(outf + off + bj * HALF) = v0; *(f32x4*)(outf + off + bj * HALF + 4) = v1; }
;                     else *(u32x4*)(xb + off + bj * HALF) = pack8(v0, v1);
;                     q += (v0[0] * v0[0] + v0[1] * v0[1]) + (v0[2] * v0[2] + v0[3] * v0[3]) + (v1[0] * v1[0] + v1[1] * v1[1]) + (v1[2] * v1[2] + v1[3] * v1[3]); }
;                 q += __shfl_xor(q, 16); q += __shfl_xor(q, 32);
;                 if (fq == 0) ssp[(size_t)row * 16 + u.pn * 4 + wc] = q;
.LBB0_576:
	s_waitcnt vmcnt(3)
	v_pk_fma_f32 v[44:45], v[44:45], 0.5, v[60:61] op_sel_hi:[1,0,1]
	v_pk_fma_f32 v[46:47], v[46:47], 0.5, v[62:63] op_sel_hi:[1,0,1]
	s_waitcnt vmcnt(2)
	v_pk_fma_f32 v[58:59], v[42:43], 0.5, v[58:59] op_sel_hi:[1,0,1]
	v_pk_fma_f32 v[42:43], v[40:41], 0.5, v[56:57] op_sel_hi:[1,0,1]
	v_cvt_pk_bf16_f32 v40, v44, v45
	v_mul_f32_e32 v44, v44, v44
	v_fmac_f32_e32 v44, v45, v45
	v_mul_f32_e32 v45, v46, v46
	v_fmac_f32_e32 v45, v47, v47
	v_add_f32_e32 v44, v45, v44
	v_mul_f32_e32 v45, v42, v42
	s_waitcnt vmcnt(1)
	v_pk_fma_f32 v[38:39], v[38:39], 0.5, v[54:55] op_sel_hi:[1,0,1]
	v_pk_fma_f32 v[36:37], v[36:37], 0.5, v[52:53] op_sel_hi:[1,0,1]
	v_cvt_pk_bf16_f32 v41, v46, v47
	v_fmac_f32_e32 v45, v43, v43
	s_waitcnt vmcnt(0)
	v_pk_fma_f32 v[46:47], v[32:33], 0.5, v[48:49] op_sel_hi:[1,0,1]
	v_mul_f32_e32 v32, v36, v36
	v_mul_f32_e32 v33, v38, v38
	v_add_f32_e32 v44, v45, v44
	v_mul_f32_e32 v45, v59, v59
	v_fmac_f32_e32 v32, v37, v37
	v_fmac_f32_e32 v33, v39, v39
	v_fmac_f32_e32 v45, v58, v58
	v_add_f32_e32 v32, v33, v32
	v_mul_f32_e32 v33, v46, v46
	v_add_f32_e32 v56, v45, v44
	v_pk_fma_f32 v[44:45], v[34:35], 0.5, v[50:51] op_sel_hi:[1,0,1]
	v_fmac_f32_e32 v33, v47, v47
	v_add_f32_e32 v32, v33, v32
	v_mul_f32_e32 v33, v44, v44
	v_fmac_f32_e32 v33, v45, v45
	v_add_f32_e32 v32, v33, v32
	v_add_f32_e32 v32, v56, v32
	v_mov_b32_e32 v33, v32
	s_nop 1
	v_permlane16_swap_b32_e32 v33, v32
	v_cvt_pk_bf16_f32 v42, v42, v43
	v_cvt_pk_bf16_f32 v43, v58, v59
	global_store_dwordx4 v[66:67], v[40:43], off
	v_cvt_pk_bf16_f32 v34, v36, v37
	s_waitcnt lgkmcnt(0)
	v_add_f32_e32 v32, v32, v33
	v_mov_b32_e32 v33, v32
	s_nop 1
	v_permlane32_swap_b32_e32 v33, v32
	v_cvt_pk_bf16_f32 v35, v38, v39
	v_cvt_pk_bf16_f32 v36, v46, v47
	v_cvt_pk_bf16_f32 v37, v44, v45
	global_store_dwordx4 v[66:67], v[34:37], off offset:256
	s_and_saveexec_b64 s[2:3], s[10:11]
	s_cbranch_execz .LBB0_578
	v_lshlrev_b64 v[34:35], 6, v[64:65]
	v_lshl_add_u64 v[34:35], s[20:21], 0, v[34:35]
	v_lshl_add_u64 v[34:35], s[0:1], 2, v[34:35]
	s_lshl_b32 s88, s44, 2
	v_lshl_add_u64 v[34:35], v[34:35], 0, s[88:89]
	s_waitcnt lgkmcnt(0)
	v_add_f32_e32 v32, v32, v33
	global_store_dword v[34:35], v32, off

; __device__ __forceinline__ u32x4 pack8(const f32x4& a, const f32x4& b) { u32x4 w; w.x = cvt_pk_bf16(a[0], a[1]); w.y = cvt_pk_bf16(a[2], a[3]); w.z = cvt_pk_bf16(b[0], b[1]); w.w = cvt_pk_bf16(b[2], b[3]); return w; }
;     __device__ __forceinline__ void operator()(const f32x4 (&acc)[2][2][4][2], const Unit& u, int ui, int wr, int wc, int fr, int fq) const {
;     ...
;             for (int m = 0; m < 4; ++m) { const int row = row0 + ai * HALF + m * 16; const size_t off = (size_t)row * 1024 + col0; float q = 0.f;
;                 f32x4 v[2][2];
;                 if (basef) {
; #pragma unroll
;                     for (int bj = 0; bj < 2; ++bj) { v[bj][0] = *(const f32x4*)(basef + off + bj * HALF); v[bj][1] = *(const f32x4*)(basef + off + bj * HALF + 4); }
;                 } else {
; #pragma unroll
;                     for (int bj = 0; bj < 2; ++bj) { const u32x4 raw = *(const u32x4*)(xb + off + bj * HALF);
;                         v[bj][0] = (f32x4){__builtin_bit_cast(float, raw.x << 16), __builtin_bit_cast(float, raw.x & 0xffff0000u), __builtin_bit_cast(float, raw.y << 16), __builtin_bit_cast(float, raw.y & 0xffff0000u)};
;                         v[bj][1] = (f32x4){__builtin_bit_cast(float, raw.z << 16), __builtin_bit_cast(float, raw.z & 0xffff0000u), __builtin_bit_cast(float, raw.w << 16), __builtin_bit_cast(float, raw.w & 0xffff0000u)}; }
;                 }
; #pragma unroll
;                 for (int bj = 0; bj < 2; ++bj) {
;                     f32x4 v0 = v[bj][0] + acc[ai][bj][m][0] * alpha, v1 = v[bj][1] + acc[ai][bj][m][1] * alpha;
;                     if (HAS_BIAS) { v0 += bv[bj][0]; v1 += bv[bj][1]; }
;                     if (outf) { *(f32x4*)(outf + off + bj * HALF) = v0; *(f32x4*)(outf + off + bj * HALF + 4) = v1; }
;                     else *(u32x4*)(xb + off + bj * HALF) = pack8(v0, v1);
;                     q += (v0[0] * v0[0] + v0[1] * v0[1]) + (v0[2] * v0[2] + v0[3] * v0[3]) + (v1[0] * v1[0] + v1[1] * v1[1]) + (v1[2] * v1[2] + v1[3] * v1[3]); }
;                 q += __shfl_xor(q, 16); q += __shfl_xor(q, 32);
;                 if (fq == 0) ssp[(size_t)row * 16 + u.pn * 4 + wc] = q;
.LBB0_581:
	s_waitcnt vmcnt(3)
	v_pk_fma_f32 v[28:29], v[28:29], 0.5, v[44:45] op_sel_hi:[1,0,1]
	v_pk_fma_f32 v[30:31], v[30:31], 0.5, v[46:47] op_sel_hi:[1,0,1]
	s_waitcnt vmcnt(2)
	v_pk_fma_f32 v[42:43], v[26:27], 0.5, v[42:43] op_sel_hi:[1,0,1]
	v_pk_fma_f32 v[26:27], v[24:25], 0.5, v[40:41] op_sel_hi:[1,0,1]
	v_cvt_pk_bf16_f32 v24, v28, v29
	v_mul_f32_e32 v28, v28, v28
	v_fmac_f32_e32 v28, v29, v29
	v_mul_f32_e32 v29, v30, v30
	v_fmac_f32_e32 v29, v31, v31
	v_add_f32_e32 v28, v29, v28
	v_mul_f32_e32 v29, v26, v26
	s_waitcnt vmcnt(1)
	v_pk_fma_f32 v[22:23], v[22:23], 0.5, v[38:39] op_sel_hi:[1,0,1]
	v_pk_fma_f32 v[20:21], v[20:21], 0.5, v[36:37] op_sel_hi:[1,0,1]
	v_cvt_pk_bf16_f32 v25, v30, v31
	v_fmac_f32_e32 v29, v27, v27
	s_waitcnt vmcnt(0)
	v_pk_fma_f32 v[30:31], v[16:17], 0.5, v[32:33] op_sel_hi:[1,0,1]
	v_mul_f32_e32 v16, v20, v20
	v_mul_f32_e32 v17, v22, v22
	v_add_f32_e32 v28, v29, v28
	v_mul_f32_e32 v29, v43, v43
	v_fmac_f32_e32 v16, v21, v21
	v_fmac_f32_e32 v17, v23, v23
	v_fmac_f32_e32 v29, v42, v42
	v_add_f32_e32 v16, v17, v16
	v_mul_f32_e32 v17, v30, v30
	v_add_f32_e32 v40, v29, v28
	v_pk_fma_f32 v[28:29], v[18:19], 0.5, v[34:35] op_sel_hi:[1,0,1]
	v_fmac_f32_e32 v17, v31, v31
	v_add_f32_e32 v16, v17, v16
	v_mul_f32_e32 v17, v28, v28
	v_fmac_f32_e32 v17, v29, v29
	v_add_f32_e32 v16, v17, v16
	v_add_f32_e32 v16, v40, v16
	v_mov_b32_e32 v17, v16
	s_nop 1
	v_permlane16_swap_b32_e32 v17, v16
	v_cvt_pk_bf16_f32 v26, v26, v27
	v_cvt_pk_bf16_f32 v27, v42, v43
	global_store_dwordx4 v[50:51], v[24:27], off
	v_cvt_pk_bf16_f32 v18, v20, v21
	s_waitcnt lgkmcnt(0)
	v_add_f32_e32 v16, v16, v17
	v_mov_b32_e32 v17, v16
	s_nop 1
	v_permlane32_swap_b32_e32 v17, v16
	v_cvt_pk_bf16_f32 v19, v22, v23
	v_cvt_pk_bf16_f32 v20, v30, v31
	v_cvt_pk_bf16_f32 v21, v28, v29
	global_store_dwordx4 v[50:51], v[18:21], off offset:256
	s_and_saveexec_b64 s[2:3], s[10:11]
	s_cbranch_execz .LBB0_583
	v_lshlrev_b64 v[18:19], 6, v[48:49]
	v_lshl_add_u64 v[18:19], s[20:21], 0, v[18:19]
	v_lshl_add_u64 v[18:19], s[0:1], 2, v[18:19]
	s_lshl_b32 s88, s44, 2
	v_lshl_add_u64 v[18:19], v[18:19], 0, s[88:89]
	s_waitcnt lgkmcnt(0)
	v_add_f32_e32 v16, v16, v17
	global_store_dword v[18:19], v16, off

; __device__ __forceinline__ u32x4 pack8(const f32x4& a, const f32x4& b) { u32x4 w; w.x = cvt_pk_bf16(a[0], a[1]); w.y = cvt_pk_bf16(a[2], a[3]); w.z = cvt_pk_bf16(b[0], b[1]); w.w = cvt_pk_bf16(b[2], b[3]); return w; }
;     __device__ __forceinline__ void operator()(const f32x4 (&acc)[2][2][4][2], const Unit& u, int ui, int wr, int wc, int fr, int fq) const {
;     ...
; #pragma unroll
;                 for (int bj = 0; bj < 2; ++bj) {
;                     f32x4 v0 = v[bj][0] + acc[ai][bj][m][0] * alpha, v1 = v[bj][1] + acc[ai][bj][m][1] * alpha;
;                     if (HAS_BIAS) { v0 += bv[bj][0]; v1 += bv[bj][1]; }
;                     if (outf) { *(f32x4*)(outf + off + bj * HALF) = v0; *(f32x4*)(outf + off + bj * HALF + 4) = v1; }
;                     else *(u32x4*)(xb + off + bj * HALF) = pack8(v0, v1);
;                     q += (v0[0] * v0[0] + v0[1] * v0[1]) + (v0[2] * v0[2] + v0[3] * v0[3]) + (v1[0] * v1[0] + v1[1] * v1[1]) + (v1[2] * v1[2] + v1[3] * v1[3]); }
;                 q += __shfl_xor(q, 16); q += __shfl_xor(q, 32);
;                 if (fq == 0) ssp[(size_t)row * 16 + u.pn * 4 + wc] = q;
.LBB0_586:
	s_waitcnt vmcnt(3)
	v_pk_fma_f32 v[12:13], v[12:13], 0.5, v[28:29] op_sel_hi:[1,0,1]
	v_pk_fma_f32 v[14:15], v[14:15], 0.5, v[30:31] op_sel_hi:[1,0,1]
	s_waitcnt vmcnt(2)
	v_pk_fma_f32 v[26:27], v[10:11], 0.5, v[26:27] op_sel_hi:[1,0,1]
	v_pk_fma_f32 v[10:11], v[8:9], 0.5, v[24:25] op_sel_hi:[1,0,1]
	v_cvt_pk_bf16_f32 v8, v12, v13
	v_mul_f32_e32 v12, v12, v12
	v_fmac_f32_e32 v12, v13, v13
	v_mul_f32_e32 v13, v14, v14
	v_fmac_f32_e32 v13, v15, v15
	v_add_f32_e32 v12, v13, v12
	v_mul_f32_e32 v13, v10, v10
	s_waitcnt vmcnt(1)
	v_pk_fma_f32 v[6:7], v[6:7], 0.5, v[22:23] op_sel_hi:[1,0,1]
	v_pk_fma_f32 v[4:5], v[4:5], 0.5, v[20:21] op_sel_hi:[1,0,1]
	v_cvt_pk_bf16_f32 v9, v14, v15
	v_fmac_f32_e32 v13, v11, v11
	s_waitcnt vmcnt(0)
	v_pk_fma_f32 v[14:15], v[0:1], 0.5, v[16:17] op_sel_hi:[1,0,1]
	v_mul_f32_e32 v0, v4, v4
	v_mul_f32_e32 v1, v6, v6
	v_add_f32_e32 v12, v13, v12
	v_mul_f32_e32 v13, v27, v27
	v_fmac_f32_e32 v0, v5, v5
	v_fmac_f32_e32 v1, v7, v7
	v_fmac_f32_e32 v13, v26, v26
	v_add_f32_e32 v0, v1, v0
	v_mul_f32_e32 v1, v14, v14
	v_add_f32_e32 v24, v13, v12
	v_pk_fma_f32 v[12:13], v[2:3], 0.5, v[18:19] op_sel_hi:[1,0,1]
	v_fmac_f32_e32 v1, v15, v15
	v_add_f32_e32 v0, v1, v0
	v_mul_f32_e32 v1, v12, v12
	v_fmac_f32_e32 v1, v13, v13
	v_add_f32_e32 v0, v1, v0
	v_add_f32_e32 v0, v24, v0
	v_mov_b32_e32 v1, v0
	s_nop 1
	v_permlane16_swap_b32_e32 v1, v0
	v_cvt_pk_bf16_f32 v10, v10, v11
	v_cvt_pk_bf16_f32 v11, v26, v27
	global_store_dwordx4 v[34:35], v[8:11], off
	v_cvt_pk_bf16_f32 v2, v4, v5
	s_waitcnt lgkmcnt(0)
	v_add_f32_e32 v0, v0, v1
	v_mov_b32_e32 v1, v0
	s_nop 1
	v_permlane32_swap_b32_e32 v1, v0
	v_cvt_pk_bf16_f32 v3, v6, v7
	v_cvt_pk_bf16_f32 v4, v14, v15
	v_cvt_pk_bf16_f32 v5, v12, v13
	global_store_dwordx4 v[34:35], v[2:5], off offset:256
	s_and_saveexec_b64 s[2:3], s[10:11]
	s_cbranch_execz .LBB0_588
	v_lshlrev_b64 v[2:3], 6, v[32:33]
	v_lshl_add_u64 v[2:3], s[20:21], 0, v[2:3]
	v_lshl_add_u64 v[2:3], s[0:1], 2, v[2:3]
	s_lshl_b32 s88, s44, 2
	v_lshl_add_u64 v[2:3], v[2:3], 0, s[88:89]
	s_waitcnt lgkmcnt(0)
	v_add_f32_e32 v0, v0, v1
	global_store_dword v[2:3], v0, off

; __device__ __forceinline__ u32x4 pack8(const f32x4& a, const f32x4& b) { u32x4 w; w.x = cvt_pk_bf16(a[0], a[1]); w.y = cvt_pk_bf16(a[2], a[3]); w.z = cvt_pk_bf16(b[0], b[1]); w.w = cvt_pk_bf16(b[2], b[3]); return w; }
; __device__ __forceinline__ f32x2 gelu_pk(f32x2 v) {
;     const f32x2 av = __builtin_elementwise_abs(v), d = av * 0.2316418882f + 1.0f;
;     f32x2 t; t.x = __builtin_amdgcn_rcpf(d.x); t.y = __builtin_amdgcn_rcpf(d.y);
;     f32x2 q = t * 0.5307027145f + (-0.7265760135f); q = q * t + 0.7107068705f; q = q * t + (-0.142248368f); q = q * t + 0.127414796f; q = q * t;
;     const f32x2 s = (v * v) * (-0.72134752044f);
;     f32x2 e; e.x = __builtin_amdgcn_exp2f(s.x); e.y = __builtin_amdgcn_exp2f(s.y);
;     const f32x2 m = v * (q * e), r = v - m;
;     f32x2 o; o.x = v.x < 0.f ? m.x : r.x; o.y = v.y < 0.f ? m.y : r.y; return o;
;     __device__ __forceinline__ void operator()(const f32x4 (&acc)[2][2][4][2], const Unit& u, int ui, int wr, int wc, int fr, int fq) const {
;     ...
;         float rs[2][4];
; #pragma unroll
;         for (int ai = 0; ai < 2; ++ai)
; #pragma unroll
;             for (int m = 0; m < 4; ++m) rs[ai][m] = row_rstd(lds, ui, ai * HALF + wr * 64 + m * 16 + fr);
; #pragma unroll
;         for (int ai = 0; ai < 2; ++ai)
; #pragma unroll
;             for (int m = 0; m < 4; ++m) { const float r = rs[ai][m]; const int row = row0 + ai * HALF + m * 16; bf16_t* rowp = Z + (size_t)row * 2048 + col0; float s1 = 0.f, s2 = 0.f;
; #pragma unroll
;                 for (int bj = 0; bj < 2; ++bj) { const f32x4 v0 = acc[ai][bj][m][0] * r, v1 = acc[ai][bj][m][1] * r;
;                     const f32x2 a = gelu_pk((f32x2){v0[0], v0[1]}), b = gelu_pk((f32x2){v0[2], v0[3]}), c = gelu_pk((f32x2){v1[0], v1[1]}), d = gelu_pk((f32x2){v1[2], v1[3]});
;                     const f32x4 z0 = (f32x4){a.x, a.y, b.x, b.y}, z1 = (f32x4){c.x, c.y, d.x, d.y};
;                     *(u32x4*)(rowp + bj * HALF) = pack8(z0, z1);
.LBB0_752:
	v_mov_b32_e32 v140, v176
	v_mov_b32_e32 v141, v177
	s_lshl_b32 s0, s10, 8
	v_add_u32_e32 v142, s45, v140
	v_lshl_add_u32 v140, s11, 8, v142
	v_lshlrev_b32_e32 v142, 2, v142
	v_lshl_add_u32 v142, s12, 10, v142
	v_add_u32_e32 v142, 0x20400, v142
	ds_read2_b32 v[168:169], v142 offset1:16
	ds_read2_b32 v[166:167], v142 offset0:32 offset1:48
	ds_read2_b32 v[164:165], v142 offset0:128 offset1:144
	ds_read2_b32 v[142:143], v142 offset0:160 offset1:176
	s_mov_b32 s56, 0x3e6d3388
	s_waitcnt lgkmcnt(0)
	v_pk_mul_f32 v[172:173], v[124:125], v[168:169] op_sel_hi:[1,0]
	s_or_b32 s0, s0, s47
	v_and_b32_e32 v125, 0x7fffffff, v173
	v_and_b32_e32 v124, 0x7fffffff, v172
	v_pk_fma_f32 v[124:125], v[124:125], s[56:57], 1.0 op_sel_hi:[1,0,0]
	s_cmp_gt_i32 s10, 3
	v_rcp_f32_e32 v174, v124
	v_rcp_f32_e32 v175, v125
	v_lshl_add_u32 v162, v141, 3, s0
	s_cselect_b64 s[0:1], -1, 0
	s_lshl_b32 s2, s10, 2
	s_add_i32 s38, s2, -16
	s_mov_b32 s2, 0xbf3a00e3
	v_mov_b64_e32 v[124:125], s[2:3]
	s_mov_b32 s2, 0x3f07dc22
	v_pk_mul_f32 v[182:183], v[120:121], v[168:169] op_sel_hi:[1,0]
	v_pk_fma_f32 v[120:121], v[174:175], s[2:3], v[124:125] op_sel_hi:[1,0,0]
	s_mov_b32 s4, 0x3f35f0e3
	v_pk_fma_f32 v[120:121], v[174:175], v[120:121], s[4:5] op_sel_hi:[1,1,0]
	s_mov_b32 s12, 0xbe11a98e
	v_pk_fma_f32 v[120:121], v[174:175], v[120:121], s[12:13] op_sel_hi:[1,1,0]
	s_mov_b32 s88, 0x3e027906
	v_pk_fma_f32 v[120:121], v[174:175], v[120:121], s[88:89] op_sel_hi:[1,1,0]
	v_pk_mul_f32 v[126:127], v[126:127], v[168:169] op_sel_hi:[1,0]
	v_pk_mul_f32 v[120:121], v[174:175], v[120:121]
	v_pk_mul_f32 v[174:175], v[172:173], v[172:173]
	s_mov_b32 s86, 0xbf38aa3b
	v_pk_mul_f32 v[174:175], v[174:175], s[86:87] op_sel_hi:[1,0]
	v_and_b32_e32 v181, 0x7fffffff, v127
	v_and_b32_e32 v180, 0x7fffffff, v126
	v_exp_f32_e32 v174, v174
	v_exp_f32_e32 v175, v175
	v_pk_fma_f32 v[180:181], v[180:181], s[56:57], 1.0 op_sel_hi:[1,0,0]
	v_pk_mul_f32 v[184:185], v[122:123], v[168:169] op_sel_hi:[1,0]
	v_rcp_f32_e32 v180, v180
	v_rcp_f32_e32 v181, v181
	v_pk_mul_f32 v[122:123], v[126:127], v[126:127]
	v_pk_mul_f32 v[120:121], v[174:175], v[120:121]
	v_pk_mul_f32 v[122:123], v[122:123], s[86:87] op_sel_hi:[1,0]
	v_pk_mul_f32 v[174:175], v[172:173], v[120:121]
	v_pk_fma_f32 v[186:187], v[172:173], v[120:121], v[172:173] neg_lo:[1,0,0] neg_hi:[1,0,0]
	v_pk_fma_f32 v[120:121], v[180:181], s[2:3], v[124:125] op_sel_hi:[1,0,0]
	v_exp_f32_e32 v122, v122
	v_pk_fma_f32 v[120:121], v[180:181], v[120:121], s[4:5] op_sel_hi:[1,1,0]
	v_exp_f32_e32 v123, v123
	v_pk_fma_f32 v[120:121], v[180:181], v[120:121], s[12:13] op_sel_hi:[1,1,0]
	v_and_b32_e32 v189, 0x7fffffff, v183
	v_pk_fma_f32 v[120:121], v[180:181], v[120:121], s[88:89] op_sel_hi:[1,1,0]
	v_and_b32_e32 v188, 0x7fffffff, v182
	v_pk_mul_f32 v[120:121], v[180:181], v[120:121]
	v_cmp_gt_f32_e32 vcc, 0, v126
	v_pk_mul_f32 v[120:121], v[122:123], v[120:121]
	v_pk_fma_f32 v[188:189], v[188:189], s[56:57], 1.0 op_sel_hi:[1,0,0]
	v_pk_mul_f32 v[122:123], v[126:127], v[120:121]
	v_pk_fma_f32 v[180:181], v[126:127], v[120:121], v[126:127] neg_lo:[1,0,0] neg_hi:[1,0,0]
	v_rcp_f32_e32 v188, v188
	v_cndmask_b32_e32 v121, v180, v122, vcc
	v_cmp_gt_f32_e32 vcc, 0, v172
	v_rcp_f32_e32 v189, v189
	v_and_b32_e32 v180, 0x7fffffff, v184
	v_cndmask_b32_e32 v120, v186, v174, vcc
	v_cmp_gt_f32_e32 vcc, 0, v127
	v_pk_fma_f32 v[126:127], v[188:189], s[2:3], v[124:125] op_sel_hi:[1,0,0]
	v_pk_mul_f32 v[116:117], v[116:117], v[168:169] op_sel_hi:[1,0]
	v_cndmask_b32_e32 v123, v181, v123, vcc
	v_cmp_gt_f32_e32 vcc, 0, v173
	v_and_b32_e32 v181, 0x7fffffff, v185
	v_pk_fma_f32 v[126:127], v[188:189], v[126:127], s[4:5] op_sel_hi:[1,1,0]
	v_cndmask_b32_e32 v122, v187, v175, vcc
	v_pk_mul_f32 v[174:175], v[182:183], v[182:183]
	v_pk_fma_f32 v[180:181], v[180:181], s[56:57], 1.0 op_sel_hi:[1,0,0]
	v_pk_mul_f32 v[174:175], v[174:175], s[86:87] op_sel_hi:[1,0]
	v_pk_fma_f32 v[126:127], v[188:189], v[126:127], s[12:13] op_sel_hi:[1,1,0]
	v_exp_f32_e32 v174, v174
	v_exp_f32_e32 v175, v175
	v_rcp_f32_e32 v180, v180
	v_rcp_f32_e32 v181, v181
	v_pk_fma_f32 v[126:127], v[188:189], v[126:127], s[88:89] op_sel_hi:[1,1,0]
	v_pk_mul_f32 v[172:173], v[184:185], v[184:185]
	v_pk_mul_f32 v[126:127], v[188:189], v[126:127]
	v_pk_mul_f32 v[172:173], v[172:173], s[86:87] op_sel_hi:[1,0]
	v_pk_mul_f32 v[126:127], v[174:175], v[126:127]
	v_exp_f32_e32 v172, v172
	v_pk_mul_f32 v[174:175], v[182:183], v[126:127]
	v_pk_fma_f32 v[186:187], v[182:183], v[126:127], v[182:183] neg_lo:[1,0,0] neg_hi:[1,0,0]
	v_pk_fma_f32 v[126:127], v[180:181], s[2:3], v[124:125] op_sel_hi:[1,0,0]
	v_exp_f32_e32 v173, v173
	v_pk_fma_f32 v[126:127], v[180:181], v[126:127], s[4:5] op_sel_hi:[1,1,0]
	v_pk_mul_f32 v[210:211], v[112:113], v[168:169] op_sel_hi:[1,0]
	v_pk_fma_f32 v[126:127], v[180:181], v[126:127], s[12:13] op_sel_hi:[1,1,0]
	v_pk_mul_f32 v[118:119], v[118:119], v[168:169] op_sel_hi:[1,0]
	v_pk_fma_f32 v[126:127], v[180:181], v[126:127], s[88:89] op_sel_hi:[1,1,0]
	v_and_b32_e32 v213, 0x7fffffff, v119
	v_pk_mul_f32 v[126:127], v[180:181], v[126:127]
	v_and_b32_e32 v212, 0x7fffffff, v118
	v_pk_mul_f32 v[126:127], v[172:173], v[126:127]
	v_and_b32_e32 v173, 0x7fffffff, v117
	v_and_b32_e32 v172, 0x7fffffff, v116
	v_pk_fma_f32 v[172:173], v[172:173], s[56:57], 1.0 op_sel_hi:[1,0,0]
	v_pk_fma_f32 v[212:213], v[212:213], s[56:57], 1.0 op_sel_hi:[1,0,0]
	v_rcp_f32_e32 v172, v172
	v_rcp_f32_e32 v173, v173
	v_rcp_f32_e32 v212, v212
	v_rcp_f32_e32 v213, v213
	v_pk_mul_f32 v[208:209], v[114:115], v[168:169] op_sel_hi:[1,0]
	v_pk_fma_f32 v[112:113], v[172:173], s[2:3], v[124:125] op_sel_hi:[1,0,0]
	v_pk_mul_f32 v[114:115], v[118:119], v[118:119]
; __device__ __forceinline__ u32x4 pack8(const f32x4& a, const f32x4& b) { u32x4 w; w.x = cvt_pk_bf16(a[0], a[1]); w.y = cvt_pk_bf16(a[2], a[3]); w.z = cvt_pk_bf16(b[0], b[1]); w.w = cvt_pk_bf16(b[2], b[3]); return w; }
; __device__ __forceinline__ f32x2 gelu_pk(f32x2 v) {
;     const f32x2 av = __builtin_elementwise_abs(v), d = av * 0.2316418882f + 1.0f;
;     f32x2 t; t.x = __builtin_amdgcn_rcpf(d.x); t.y = __builtin_amdgcn_rcpf(d.y);
;     f32x2 q = t * 0.5307027145f + (-0.7265760135f); q = q * t + 0.7107068705f; q = q * t + (-0.142248368f); q = q * t + 0.127414796f; q = q * t;
;     const f32x2 s = (v * v) * (-0.72134752044f);
;     f32x2 e; e.x = __builtin_amdgcn_exp2f(s.x); e.y = __builtin_amdgcn_exp2f(s.y);
;     const f32x2 m = v * (q * e), r = v - m;
;     f32x2 o; o.x = v.x < 0.f ? m.x : r.x; o.y = v.y < 0.f ? m.y : r.y; return o;
;     __device__ __forceinline__ void operator()(const f32x4 (&acc)[2][2][4][2], const Unit& u, int ui, int wr, int wc, int fr, int fq) const {
;     ...
;             for (int m = 0; m < 4; ++m) { const float r = rs[ai][m]; const int row = row0 + ai * HALF + m * 16; bf16_t* rowp = Z + (size_t)row * 2048 + col0; float s1 = 0.f, s2 = 0.f;
; #pragma unroll
;                 for (int bj = 0; bj < 2; ++bj) { const f32x4 v0 = acc[ai][bj][m][0] * r, v1 = acc[ai][bj][m][1] * r;
;                     const f32x2 a = gelu_pk((f32x2){v0[0], v0[1]}), b = gelu_pk((f32x2){v0[2], v0[3]}), c = gelu_pk((f32x2){v1[0], v1[1]}), d = gelu_pk((f32x2){v1[2], v1[3]});
;                     const f32x4 z0 = (f32x4){a.x, a.y, b.x, b.y}, z1 = (f32x4){c.x, c.y, d.x, d.y};
;                     *(u32x4*)(rowp + bj * HALF) = pack8(z0, z1);
;                     s1 += (z0[0] + z0[1]) + (z0[2] + z0[3]) + (z1[0] + z1[1]) + (z1[2] + z1[3]);
;                     s2 += (z0[0] * z0[0] + z0[1] * z0[1]) + (z0[2] * z0[2] + z0[3] * z0[3]) + (z1[0] * z1[0] + z1[1] * z1[1]) + (z1[2] * z1[2] + z1[3] * z1[3]); }
;                 if (u.pn >= 4) { s1 += __shfl_xor(s1, 16); s1 += __shfl_xor(s1, 32); s2 += __shfl_xor(s2, 16); s2 += __shfl_xor(s2, 32);
	v_pk_fma_f32 v[112:113], v[172:173], v[112:113], s[4:5] op_sel_hi:[1,1,0]
	v_pk_mul_f32 v[114:115], v[114:115], s[86:87] op_sel_hi:[1,0]
	v_pk_fma_f32 v[112:113], v[172:173], v[112:113], s[12:13] op_sel_hi:[1,1,0]
	v_exp_f32_e32 v114, v114
	v_pk_fma_f32 v[112:113], v[172:173], v[112:113], s[88:89] op_sel_hi:[1,1,0]
	v_exp_f32_e32 v115, v115
	v_pk_mul_f32 v[112:113], v[172:173], v[112:113]
	v_pk_mul_f32 v[172:173], v[116:117], v[116:117]
	v_and_b32_e32 v217, 0x7fffffff, v211
	v_pk_mul_f32 v[172:173], v[172:173], s[86:87] op_sel_hi:[1,0]
	v_and_b32_e32 v216, 0x7fffffff, v210
	v_exp_f32_e32 v172, v172
	v_exp_f32_e32 v173, v173
	v_pk_fma_f32 v[216:217], v[216:217], s[56:57], 1.0 op_sel_hi:[1,0,0]
	v_pk_mul_f32 v[188:189], v[184:185], v[126:127]
	v_pk_fma_f32 v[190:191], v[184:185], v[126:127], v[184:185] neg_lo:[1,0,0] neg_hi:[1,0,0]
	v_pk_mul_f32 v[112:113], v[172:173], v[112:113]
	v_cmp_gt_f32_e32 vcc, 0, v185
	v_pk_mul_f32 v[172:173], v[116:117], v[112:113]
	v_pk_fma_f32 v[214:215], v[116:117], v[112:113], v[116:117] neg_lo:[1,0,0] neg_hi:[1,0,0]
	v_pk_fma_f32 v[112:113], v[212:213], s[2:3], v[124:125] op_sel_hi:[1,0,0]
	v_rcp_f32_e32 v216, v216
	v_pk_fma_f32 v[112:113], v[212:213], v[112:113], s[4:5] op_sel_hi:[1,1,0]
	v_rcp_f32_e32 v217, v217
	v_pk_fma_f32 v[112:113], v[212:213], v[112:113], s[12:13] op_sel_hi:[1,1,0]
	v_cndmask_b32_e32 v126, v191, v189, vcc
	v_pk_fma_f32 v[112:113], v[212:213], v[112:113], s[88:89] op_sel_hi:[1,1,0]
	v_cmp_gt_f32_e32 vcc, 0, v118
	v_pk_mul_f32 v[112:113], v[212:213], v[112:113]
	s_ashr_i32 s39, s38, 31
	v_pk_mul_f32 v[112:113], v[114:115], v[112:113]
	s_cmp_lt_i32 s10, 4
	v_pk_mul_f32 v[114:115], v[118:119], v[112:113]
	v_pk_fma_f32 v[212:213], v[118:119], v[112:113], v[118:119] neg_lo:[1,0,0] neg_hi:[1,0,0]
	v_cmp_eq_u32_e64 s[10:11], 0, v141
	v_cndmask_b32_e32 v113, v212, v114, vcc
	v_cmp_gt_f32_e32 vcc, 0, v116
	v_ashrrev_i32_e32 v141, 31, v140
	v_lshlrev_b64 v[170:171], 12, v[140:141]
	v_cndmask_b32_e32 v112, v214, v172, vcc
	v_cmp_gt_f32_e32 vcc, 0, v119
	v_pk_mul_f32 v[118:119], v[210:211], v[210:211]
	v_ashrrev_i32_e32 v163, 31, v162
	v_cndmask_b32_e32 v115, v213, v115, vcc
	v_cmp_gt_f32_e32 vcc, 0, v117
	v_pk_fma_f32 v[116:117], v[216:217], s[2:3], v[124:125] op_sel_hi:[1,0,0]
	v_pk_mul_f32 v[118:119], v[118:119], s[86:87] op_sel_hi:[1,0]
	v_pk_fma_f32 v[116:117], v[216:217], v[116:117], s[4:5] op_sel_hi:[1,1,0]
	v_exp_f32_e32 v118, v118
	v_exp_f32_e32 v119, v119
	v_pk_fma_f32 v[116:117], v[216:217], v[116:117], s[12:13] op_sel_hi:[1,1,0]
	v_cndmask_b32_e32 v114, v215, v173, vcc
	v_pk_fma_f32 v[116:117], v[216:217], v[116:117], s[88:89] op_sel_hi:[1,1,0]
	v_cmp_gt_f32_e32 vcc, 0, v182
	v_pk_mul_f32 v[116:117], v[216:217], v[116:117]
	v_lshl_add_u64 v[170:171], s[20:21], 0, v[170:171]
	v_pk_mul_f32 v[116:117], v[118:119], v[116:117]
	v_cndmask_b32_e32 v118, v186, v174, vcc
	v_pk_mul_f32 v[172:173], v[210:211], v[116:117]
	v_pk_fma_f32 v[214:215], v[210:211], v[116:117], v[210:211] neg_lo:[1,0,0] neg_hi:[1,0,0]
	v_cmp_gt_f32_e32 vcc, 0, v210
	v_and_b32_e32 v174, 0x7fffffff, v208
	v_lshl_add_u64 v[170:171], v[162:163], 1, v[170:171]
	v_cndmask_b32_e32 v119, v214, v172, vcc
	v_cmp_gt_f32_e32 vcc, 0, v183
	v_cvt_pk_bf16_f32 v180, v120, v122
	v_cvt_pk_bf16_f32 v181, v121, v123
	v_pk_mul_f32 v[212:213], v[208:209], v[208:209]
	s_nop 0
	v_cndmask_b32_e32 v172, v187, v175, vcc
	v_and_b32_e32 v175, 0x7fffffff, v209
	v_pk_fma_f32 v[174:175], v[174:175], s[56:57], 1.0 op_sel_hi:[1,0,0]
	v_cmp_gt_f32_e32 vcc, 0, v184
	v_rcp_f32_e32 v184, v174
	v_rcp_f32_e32 v185, v175
	v_cvt_pk_bf16_f32 v182, v118, v172
	v_cndmask_b32_e32 v117, v190, v188, vcc
	v_cvt_pk_bf16_f32 v183, v117, v126
	global_store_dwordx4 v[170:171], v[180:183], off
	v_pk_fma_f32 v[124:125], v[184:185], s[2:3], v[124:125] op_sel_hi:[1,0,0]
	v_cmp_gt_f32_e32 vcc, 0, v211
	v_pk_mul_f32 v[180:181], v[212:213], s[86:87] op_sel_hi:[1,0]
	v_pk_fma_f32 v[124:125], v[184:185], v[124:125], s[4:5] op_sel_hi:[1,1,0]
	v_exp_f32_e32 v180, v180
	v_exp_f32_e32 v181, v181
	v_pk_fma_f32 v[124:125], v[184:185], v[124:125], s[12:13] op_sel_hi:[1,1,0]
	v_cndmask_b32_e32 v174, v215, v173, vcc
	v_pk_fma_f32 v[124:125], v[184:185], v[124:125], s[88:89] op_sel_hi:[1,1,0]
	v_cmp_gt_f32_e32 vcc, 0, v209
	v_pk_mul_f32 v[124:125], v[184:185], v[124:125]
	s_nop 0
	v_pk_mul_f32 v[124:125], v[180:181], v[124:125]
	s_nop 0
	v_pk_mul_f32 v[180:181], v[208:209], v[124:125]
	v_pk_fma_f32 v[124:125], v[208:209], v[124:125], v[208:209] neg_lo:[1,0,0] neg_hi:[1,0,0]
	s_nop 0
	v_cndmask_b32_e32 v125, v125, v181, vcc
	v_cmp_gt_f32_e32 vcc, 0, v208
	s_nop 1
	v_cndmask_b32_e32 v124, v124, v180, vcc
	v_cvt_pk_bf16_f32 v180, v112, v114
	v_cvt_pk_bf16_f32 v181, v113, v115
	v_cvt_pk_bf16_f32 v182, v119, v174
	v_cvt_pk_bf16_f32 v183, v124, v125
	global_store_dwordx4 v[170:171], v[180:183], off offset:256
	s_cbranch_scc1 .LBB0_756
;     __device__ __forceinline__ void operator()(const f32x4 (&acc)[2][2][4][2], const Unit& u, int ui, int wr, int wc, int fr, int fq) const {
;     ...
;                     s1 += (z0[0] + z0[1]) + (z0[2] + z0[3]) + (z1[0] + z1[1]) + (z1[2] + z1[3]);
;                     s2 += (z0[0] * z0[0] + z0[1] * z0[1]) + (z0[2] * z0[2] + z0[3] * z0[3]) + (z1[0] * z1[0] + z1[1] * z1[1]) + (z1[2] * z1[2] + z1[3] * z1[3]); }
;                 if (u.pn >= 4) { s1 += __shfl_xor(s1, 16); s1 += __shfl_xor(s1, 32); s2 += __shfl_xor(s2, 16); s2 += __shfl_xor(s2, 32);
;                     if (fq == 0) vst[(size_t)row * 16 + (u.pn - 4) * 4 + wc] = (f32x2){s1, s2}; } }
	v_mov_b32_e32 v116, v119
	v_mov_b32_e32 v175, v117
	v_pk_add_f32 v[170:171], v[116:117], v[174:175]
	v_pk_mul_f32 v[180:181], v[116:117], v[174:175]
	v_mov_b32_e32 v182, v118
	v_mov_b32_e32 v183, v172
	v_mul_f32_e32 v116, v118, v118
	v_mov_b32_e32 v173, v119
	v_pk_fma_f32 v[182:183], v[182:183], v[182:183], v[116:117] op_sel_hi:[1,1,0]
	v_mul_f32_e32 v116, v124, v124
	v_pk_fma_f32 v[184:185], v[124:125], v[124:125], v[116:117] op_sel_hi:[1,1,0]
	v_mov_b32_e32 v186, v112
	v_mov_b32_e32 v187, v114
	v_mul_f32_e32 v116, v112, v112
	v_pk_add_f32 v[190:191], v[118:119], v[172:173]
	v_pk_mul_f32 v[118:119], v[118:119], v[172:173]
	v_mov_b32_e32 v171, v181
	v_pk_mul_f32 v[180:181], v[122:123], v[122:123]
	v_pk_fma_f32 v[186:187], v[186:187], v[186:187], v[116:117] op_sel_hi:[1,1,0]
	v_mov_b32_e32 v188, v113
	v_mov_b32_e32 v189, v115
	v_mul_f32_e32 v116, v113, v113
	v_mov_b32_e32 v191, v119
	v_pk_mul_f32 v[118:119], v[174:175], v[174:175]
	v_pk_add_f32 v[112:113], v[112:113], v[114:115]
	v_and_b32_e32 v115, 64, v192
	v_pk_fma_f32 v[180:181], v[120:121], v[120:121], v[180:181]
	v_pk_add_f32 v[120:121], v[120:121], v[122:123]
	v_xor_b32_e32 v114, 16, v192
	v_add_u32_e32 v119, 64, v115
	v_pk_fma_f32 v[188:189], v[188:189], v[188:189], v[116:117] op_sel_hi:[1,1,0]
	v_pk_add_f32 v[120:121], v[120:121], v[120:121] op_sel:[0,1] op_sel_hi:[1,0]
	v_cmp_lt_i32_e32 vcc, v114, v119
	v_mul_f32_e32 v168, v126, v126
	v_pk_add_f32 v[180:181], v[180:181], v[180:181] op_sel_hi:[0,1]
	v_cndmask_b32_e32 v114, v192, v114, vcc
	v_mov_b32_e32 v186, v117
	v_mov_b32_e32 v127, v189
	v_mov_b32_e32 v121, v118
	v_pk_add_f32 v[112:113], v[112:113], v[112:113] op_sel:[0,1] op_sel_hi:[1,0]
	v_lshlrev_b32_e32 v122, 2, v114
	v_pk_add_f32 v[114:115], v[186:187], v[126:127]
	v_pk_add_f32 v[116:117], v[190:191], v[120:121]
	v_mov_b32_e32 v182, v124
	v_mov_b32_e32 v180, v125
	v_mov_b32_e32 v113, v168
	v_pk_add_f32 v[114:115], v[116:117], v[114:115]
	v_mov_b32_e32 v147, v185
	v_pk_add_f32 v[116:117], v[182:183], v[180:181]
	v_pk_add_f32 v[112:113], v[170:171], v[112:113]
	v_pk_add_f32 v[114:115], v[114:115], v[146:147]
	v_pk_add_f32 v[112:113], v[112:113], v[116:117]
	v_xor_b32_e32 v116, 32, v192
	v_pk_add_f32 v[112:113], v[112:113], v[114:115]
	ds_bpermute_b32 v114, v122, v112
	ds_bpermute_b32 v115, v122, v113
	v_cmp_lt_i32_e32 vcc, v116, v119
	s_waitcnt lgkmcnt(0)
	v_pk_add_f32 v[112:113], v[112:113], v[114:115]
	v_cndmask_b32_e32 v116, v192, v116, vcc
	v_lshlrev_b32_e32 v116, 2, v116
	v_mov_b32_e32 v114, v112
	s_nop 1
	v_permlane32_swap_b32_e32 v114, v112
	v_mov_b32_e32 v115, v113
	s_nop 1
	v_permlane32_swap_b32_e32 v115, v113
	s_and_saveexec_b64 s[2:3], s[10:11]
	s_cbranch_execz .LBB0_755
	s_waitcnt lgkmcnt(0)
	v_pk_add_f32 v[112:113], v[112:113], v[114:115]
	v_lshlrev_b64 v[114:115], 7, v[140:141]
	v_lshl_add_u64 v[114:115], s[16:17], 0, v[114:115]
	v_lshl_add_u64 v[114:115], s[38:39], 3, v[114:115]
	s_lshl_b32 s88, s44, 3
	v_lshl_add_u64 v[114:115], v[114:115], 0, s[88:89]
	global_store_dwordx2 v[114:115], v[112:113], off

; __device__ __forceinline__ u32x4 pack8(const f32x4& a, const f32x4& b) { u32x4 w; w.x = cvt_pk_bf16(a[0], a[1]); w.y = cvt_pk_bf16(a[2], a[3]); w.z = cvt_pk_bf16(b[0], b[1]); w.w = cvt_pk_bf16(b[2], b[3]); return w; }
; __device__ __forceinline__ f32x2 gelu_pk(f32x2 v) {
;     const f32x2 av = __builtin_elementwise_abs(v), d = av * 0.2316418882f + 1.0f;
;     f32x2 t; t.x = __builtin_amdgcn_rcpf(d.x); t.y = __builtin_amdgcn_rcpf(d.y);
;     f32x2 q = t * 0.5307027145f + (-0.7265760135f); q = q * t + 0.7107068705f; q = q * t + (-0.142248368f); q = q * t + 0.127414796f; q = q * t;
;     const f32x2 s = (v * v) * (-0.72134752044f);
;     f32x2 e; e.x = __builtin_amdgcn_exp2f(s.x); e.y = __builtin_amdgcn_exp2f(s.y);
;     const f32x2 m = v * (q * e), r = v - m;
;     f32x2 o; o.x = v.x < 0.f ? m.x : r.x; o.y = v.y < 0.f ? m.y : r.y; return o;
;     __device__ __forceinline__ void operator()(const f32x4 (&acc)[2][2][4][2], const Unit& u, int ui, int wr, int wc, int fr, int fq) const {
;     ...
;             for (int m = 0; m < 4; ++m) { const float r = rs[ai][m]; const int row = row0 + ai * HALF + m * 16; bf16_t* rowp = Z + (size_t)row * 2048 + col0; float s1 = 0.f, s2 = 0.f;
; #pragma unroll
;                 for (int bj = 0; bj < 2; ++bj) { const f32x4 v0 = acc[ai][bj][m][0] * r, v1 = acc[ai][bj][m][1] * r;
;                     const f32x2 a = gelu_pk((f32x2){v0[0], v0[1]}), b = gelu_pk((f32x2){v0[2], v0[3]}), c = gelu_pk((f32x2){v1[0], v1[1]}), d = gelu_pk((f32x2){v1[2], v1[3]});
;                     const f32x4 z0 = (f32x4){a.x, a.y, b.x, b.y}, z1 = (f32x4){c.x, c.y, d.x, d.y};
;                     *(u32x4*)(rowp + bj * HALF) = pack8(z0, z1);
.LBB0_756:
	v_mov_b32_e32 v116, v169
	v_pk_mul_f32 v[118:119], v[108:109], v[116:117] op_sel_hi:[1,0]
	s_mov_b32 s2, 0xbf3a00e3
	v_and_b32_e32 v109, 0x7fffffff, v119
	v_and_b32_e32 v108, 0x7fffffff, v118
	v_pk_fma_f32 v[108:109], v[108:109], s[56:57], 1.0 op_sel_hi:[1,0,0]
	v_pk_mul_f32 v[122:123], v[104:105], v[116:117] op_sel_hi:[1,0]
	v_rcp_f32_e32 v120, v108
	v_rcp_f32_e32 v121, v109
	v_mov_b64_e32 v[108:109], s[2:3]
	s_mov_b32 s2, 0x3f07dc22
	s_mov_b32 s88, 0x3e027906
	v_pk_fma_f32 v[104:105], v[120:121], s[2:3], v[108:109] op_sel_hi:[1,0,0]
	v_pk_mul_f32 v[110:111], v[110:111], v[116:117] op_sel_hi:[1,0]
	v_pk_fma_f32 v[104:105], v[120:121], v[104:105], s[4:5] op_sel_hi:[1,1,0]
	v_and_b32_e32 v127, 0x7fffffff, v111
	v_pk_fma_f32 v[104:105], v[120:121], v[104:105], s[12:13] op_sel_hi:[1,1,0]
	v_and_b32_e32 v126, 0x7fffffff, v110
	v_pk_fma_f32 v[104:105], v[120:121], v[104:105], s[88:89] op_sel_hi:[1,1,0]
	v_pk_fma_f32 v[126:127], v[126:127], s[56:57], 1.0 op_sel_hi:[1,0,0]
	v_pk_mul_f32 v[104:105], v[120:121], v[104:105]
	v_pk_mul_f32 v[120:121], v[118:119], v[118:119]
	v_rcp_f32_e32 v126, v126
	v_pk_mul_f32 v[120:121], v[120:121], s[86:87] op_sel_hi:[1,0]
	v_rcp_f32_e32 v127, v127
	v_exp_f32_e32 v120, v120
	v_exp_f32_e32 v121, v121
	v_pk_mul_f32 v[124:125], v[106:107], v[116:117] op_sel_hi:[1,0]
	v_pk_mul_f32 v[106:107], v[110:111], v[110:111]
	v_pk_mul_f32 v[100:101], v[100:101], v[116:117] op_sel_hi:[1,0]
	v_pk_mul_f32 v[104:105], v[120:121], v[104:105]
	v_pk_mul_f32 v[106:107], v[106:107], s[86:87] op_sel_hi:[1,0]
	v_pk_mul_f32 v[120:121], v[118:119], v[104:105]
	v_pk_fma_f32 v[168:169], v[118:119], v[104:105], v[118:119] neg_lo:[1,0,0] neg_hi:[1,0,0]
	v_pk_fma_f32 v[104:105], v[126:127], s[2:3], v[108:109] op_sel_hi:[1,0,0]
	v_exp_f32_e32 v106, v106
	v_pk_fma_f32 v[104:105], v[126:127], v[104:105], s[4:5] op_sel_hi:[1,1,0]
	v_exp_f32_e32 v107, v107
	v_and_b32_e32 v173, 0x7fffffff, v101
	v_and_b32_e32 v172, 0x7fffffff, v100
	v_pk_fma_f32 v[104:105], v[126:127], v[104:105], s[12:13] op_sel_hi:[1,1,0]
	v_pk_fma_f32 v[172:173], v[172:173], s[56:57], 1.0 op_sel_hi:[1,0,0]
	v_pk_fma_f32 v[104:105], v[126:127], v[104:105], s[88:89] op_sel_hi:[1,1,0]
	v_rcp_f32_e32 v172, v172
	v_rcp_f32_e32 v173, v173
	v_pk_mul_f32 v[104:105], v[126:127], v[104:105]
	v_and_b32_e32 v171, 0x7fffffff, v123
	v_pk_mul_f32 v[104:105], v[106:107], v[104:105]
	v_and_b32_e32 v170, 0x7fffffff, v122
	v_pk_mul_f32 v[106:107], v[110:111], v[104:105]
	v_pk_fma_f32 v[126:127], v[110:111], v[104:105], v[110:111] neg_lo:[1,0,0] neg_hi:[1,0,0]
	v_cmp_gt_f32_e32 vcc, 0, v110
	v_pk_fma_f32 v[170:171], v[170:171], s[56:57], 1.0 op_sel_hi:[1,0,0]
	v_pk_mul_f32 v[102:103], v[102:103], v[116:117] op_sel_hi:[1,0]
	v_cndmask_b32_e32 v105, v126, v106, vcc
	v_cmp_gt_f32_e32 vcc, 0, v118
	v_rcp_f32_e32 v170, v170
	v_rcp_f32_e32 v171, v171
	v_pk_mul_f32 v[174:175], v[98:99], v[116:117] op_sel_hi:[1,0]
	v_pk_mul_f32 v[116:117], v[96:97], v[116:117] op_sel_hi:[1,0]
	v_pk_fma_f32 v[96:97], v[172:173], s[2:3], v[108:109] op_sel_hi:[1,0,0]
	v_cndmask_b32_e32 v104, v168, v120, vcc
	v_cmp_gt_f32_e32 vcc, 0, v111
	v_pk_fma_f32 v[96:97], v[172:173], v[96:97], s[4:5] op_sel_hi:[1,1,0]
	v_pk_fma_f32 v[110:111], v[170:171], s[2:3], v[108:109] op_sel_hi:[1,0,0]
	v_cndmask_b32_e32 v107, v127, v107, vcc
	v_cmp_gt_f32_e32 vcc, 0, v119
	v_pk_fma_f32 v[96:97], v[172:173], v[96:97], s[12:13] op_sel_hi:[1,1,0]
	v_and_b32_e32 v127, 0x7fffffff, v125
	v_cndmask_b32_e32 v106, v169, v121, vcc
	v_pk_mul_f32 v[120:121], v[122:123], v[122:123]
	v_pk_fma_f32 v[96:97], v[172:173], v[96:97], s[88:89] op_sel_hi:[1,1,0]
	v_pk_mul_f32 v[120:121], v[120:121], s[86:87] op_sel_hi:[1,0]
	v_and_b32_e32 v126, 0x7fffffff, v124
	v_pk_mul_f32 v[96:97], v[172:173], v[96:97]
	v_pk_mul_f32 v[172:173], v[100:101], v[100:101]
	v_pk_fma_f32 v[110:111], v[170:171], v[110:111], s[4:5] op_sel_hi:[1,1,0]
	v_exp_f32_e32 v120, v120
	v_exp_f32_e32 v121, v121
	v_pk_fma_f32 v[126:127], v[126:127], s[56:57], 1.0 op_sel_hi:[1,0,0]
	v_pk_mul_f32 v[172:173], v[172:173], s[86:87] op_sel_hi:[1,0]
	v_and_b32_e32 v181, 0x7fffffff, v103
	v_and_b32_e32 v180, 0x7fffffff, v102
	v_pk_fma_f32 v[110:111], v[170:171], v[110:111], s[12:13] op_sel_hi:[1,1,0]
	v_rcp_f32_e32 v126, v126
	v_rcp_f32_e32 v127, v127
	v_exp_f32_e32 v172, v172
	v_exp_f32_e32 v173, v173
	v_pk_fma_f32 v[180:181], v[180:181], s[56:57], 1.0 op_sel_hi:[1,0,0]
	v_pk_fma_f32 v[110:111], v[170:171], v[110:111], s[88:89] op_sel_hi:[1,1,0]
	v_rcp_f32_e32 v180, v180
	v_rcp_f32_e32 v181, v181
	v_pk_mul_f32 v[110:111], v[170:171], v[110:111]
	v_pk_mul_f32 v[118:119], v[124:125], v[124:125]
	v_pk_mul_f32 v[110:111], v[120:121], v[110:111]
	v_pk_mul_f32 v[118:119], v[118:119], s[86:87] op_sel_hi:[1,0]
	v_pk_mul_f32 v[168:169], v[122:123], v[110:111]
	v_pk_fma_f32 v[170:171], v[122:123], v[110:111], v[122:123] neg_lo:[1,0,0] neg_hi:[1,0,0]
	v_pk_fma_f32 v[110:111], v[126:127], s[2:3], v[108:109] op_sel_hi:[1,0,0]
	v_pk_mul_f32 v[98:99], v[102:103], v[102:103]
	v_pk_mul_f32 v[96:97], v[172:173], v[96:97]
	v_pk_fma_f32 v[110:111], v[126:127], v[110:111], s[4:5] op_sel_hi:[1,1,0]
	v_exp_f32_e32 v118, v118
	v_exp_f32_e32 v119, v119
	v_pk_mul_f32 v[172:173], v[100:101], v[96:97]
	v_pk_fma_f32 v[182:183], v[100:101], v[96:97], v[100:101] neg_lo:[1,0,0] neg_hi:[1,0,0]
	v_pk_fma_f32 v[96:97], v[180:181], s[2:3], v[108:109] op_sel_hi:[1,0,0]
	v_pk_mul_f32 v[98:99], v[98:99], s[86:87] op_sel_hi:[1,0]
	v_pk_fma_f32 v[110:111], v[126:127], v[110:111], s[12:13] op_sel_hi:[1,1,0]
	v_pk_fma_f32 v[96:97], v[180:181], v[96:97], s[4:5] op_sel_hi:[1,1,0]
	v_exp_f32_e32 v98, v98
	v_exp_f32_e32 v99, v99
	v_pk_fma_f32 v[110:111], v[126:127], v[110:111], s[88:89] op_sel_hi:[1,1,0]
	v_pk_fma_f32 v[96:97], v[180:181], v[96:97], s[12:13] op_sel_hi:[1,1,0]
	v_pk_mul_f32 v[110:111], v[126:127], v[110:111]
	v_pk_fma_f32 v[96:97], v[180:181], v[96:97], s[88:89] op_sel_hi:[1,1,0]
	v_and_b32_e32 v185, 0x7fffffff, v117
	v_and_b32_e32 v184, 0x7fffffff, v116
	v_pk_mul_f32 v[110:111], v[118:119], v[110:111]
	v_pk_mul_f32 v[96:97], v[180:181], v[96:97]
	v_pk_fma_f32 v[184:185], v[184:185], s[56:57], 1.0 op_sel_hi:[1,0,0]
	v_pk_mul_f32 v[118:119], v[124:125], v[110:111]
	v_pk_fma_f32 v[126:127], v[124:125], v[110:111], v[124:125] neg_lo:[1,0,0] neg_hi:[1,0,0]
	v_cmp_gt_f32_e32 vcc, 0, v125
	v_pk_mul_f32 v[96:97], v[98:99], v[96:97]
	v_rcp_f32_e32 v184, v184
	v_rcp_f32_e32 v185, v185
	v_cndmask_b32_e32 v110, v127, v119, vcc
	v_pk_mul_f32 v[98:99], v[102:103], v[96:97]
	v_pk_fma_f32 v[180:181], v[102:103], v[96:97], v[102:103] neg_lo:[1,0,0] neg_hi:[1,0,0]
	v_cmp_gt_f32_e32 vcc, 0, v102
	v_and_b32_e32 v119, 0x7fffffff, v175
	v_add_u32_e32 v112, 16, v140
	v_cndmask_b32_e32 v97, v180, v98, vcc
	v_cmp_gt_f32_e32 vcc, 0, v100
	v_ashrrev_i32_e32 v113, 31, v112
	s_waitcnt lgkmcnt(0)
; __device__ __forceinline__ u32x4 pack8(const f32x4& a, const f32x4& b) { u32x4 w; w.x = cvt_pk_bf16(a[0], a[1]); w.y = cvt_pk_bf16(a[2], a[3]); w.z = cvt_pk_bf16(b[0], b[1]); w.w = cvt_pk_bf16(b[2], b[3]); return w; }
;     __device__ __forceinline__ void operator()(const f32x4 (&acc)[2][2][4][2], const Unit& u, int ui, int wr, int wc, int fr, int fq) const {
;     ...
;             for (int m = 0; m < 4; ++m) { const float r = rs[ai][m]; const int row = row0 + ai * HALF + m * 16; bf16_t* rowp = Z + (size_t)row * 2048 + col0; float s1 = 0.f, s2 = 0.f;
; #pragma unroll
;                 for (int bj = 0; bj < 2; ++bj) { const f32x4 v0 = acc[ai][bj][m][0] * r, v1 = acc[ai][bj][m][1] * r;
;                     const f32x2 a = gelu_pk((f32x2){v0[0], v0[1]}), b = gelu_pk((f32x2){v0[2], v0[3]}), c = gelu_pk((f32x2){v1[0], v1[1]}), d = gelu_pk((f32x2){v1[2], v1[3]});
;                     const f32x4 z0 = (f32x4){a.x, a.y, b.x, b.y}, z1 = (f32x4){c.x, c.y, d.x, d.y};
;                     *(u32x4*)(rowp + bj * HALF) = pack8(z0, z1);
;                     s1 += (z0[0] + z0[1]) + (z0[2] + z0[3]) + (z1[0] + z1[1]) + (z1[2] + z1[3]);
;                     s2 += (z0[0] * z0[0] + z0[1] * z0[1]) + (z0[2] * z0[2] + z0[3] * z0[3]) + (z1[0] * z1[0] + z1[1] * z1[1]) + (z1[2] * z1[2] + z1[3] * z1[3]); }
;                 if (u.pn >= 4) { s1 += __shfl_xor(s1, 16); s1 += __shfl_xor(s1, 32); s2 += __shfl_xor(s2, 16); s2 += __shfl_xor(s2, 32);
;                     if (fq == 0) vst[(size_t)row * 16 + (u.pn - 4) * 4 + wc] = (f32x2){s1, s2}; } }
	v_lshlrev_b64 v[114:115], 12, v[112:113]
	v_cndmask_b32_e32 v96, v182, v172, vcc
	v_cmp_gt_f32_e32 vcc, 0, v103
	v_pk_mul_f32 v[102:103], v[116:117], v[116:117]
	v_lshl_add_u64 v[114:115], s[20:21], 0, v[114:115]
	v_cndmask_b32_e32 v99, v181, v99, vcc
	v_cmp_gt_f32_e32 vcc, 0, v101
	v_pk_fma_f32 v[100:101], v[184:185], s[2:3], v[108:109] op_sel_hi:[1,0,0]
	v_pk_mul_f32 v[102:103], v[102:103], s[86:87] op_sel_hi:[1,0]
	v_pk_fma_f32 v[100:101], v[184:185], v[100:101], s[4:5] op_sel_hi:[1,1,0]
	v_exp_f32_e32 v102, v102
	v_exp_f32_e32 v103, v103
	v_pk_fma_f32 v[100:101], v[184:185], v[100:101], s[12:13] op_sel_hi:[1,1,0]
	v_cndmask_b32_e32 v98, v183, v173, vcc
	v_pk_fma_f32 v[100:101], v[184:185], v[100:101], s[88:89] op_sel_hi:[1,1,0]
	v_cmp_gt_f32_e32 vcc, 0, v122
	v_pk_mul_f32 v[100:101], v[184:185], v[100:101]
	v_lshl_add_u64 v[114:115], v[162:163], 1, v[114:115]
	v_pk_mul_f32 v[100:101], v[102:103], v[100:101]
	v_cndmask_b32_e32 v102, v170, v168, vcc
	v_pk_mul_f32 v[180:181], v[116:117], v[100:101]
	v_pk_fma_f32 v[182:183], v[116:117], v[100:101], v[116:117] neg_lo:[1,0,0] neg_hi:[1,0,0]
	v_cmp_gt_f32_e32 vcc, 0, v116
	v_cvt_pk_bf16_f32 v120, v104, v106
	v_cvt_pk_bf16_f32 v121, v105, v107
	v_pk_mul_f32 v[172:173], v[174:175], v[174:175]
	v_cndmask_b32_e64 v100, 0, 1, s[0:1]
	v_cndmask_b32_e32 v103, v182, v180, vcc
	v_cmp_gt_f32_e32 vcc, 0, v123
	s_nop 1
	v_cndmask_b32_e32 v116, v171, v169, vcc
	v_cmp_gt_f32_e32 vcc, 0, v124
	v_cvt_pk_bf16_f32 v122, v102, v116
	s_nop 1
	v_cndmask_b32_e32 v101, v126, v118, vcc
	v_and_b32_e32 v118, 0x7fffffff, v174
	v_pk_fma_f32 v[118:119], v[118:119], s[56:57], 1.0 op_sel_hi:[1,0,0]
	v_cvt_pk_bf16_f32 v123, v101, v110
	global_store_dwordx4 v[114:115], v[120:123], off
	v_rcp_f32_e32 v124, v118
	v_rcp_f32_e32 v125, v119
	v_pk_mul_f32 v[120:121], v[172:173], s[86:87] op_sel_hi:[1,0]
	v_cmp_gt_f32_e32 vcc, 0, v117
	v_exp_f32_e32 v120, v120
	v_pk_fma_f32 v[108:109], v[124:125], s[2:3], v[108:109] op_sel_hi:[1,0,0]
	v_exp_f32_e32 v121, v121
	v_pk_fma_f32 v[108:109], v[124:125], v[108:109], s[4:5] op_sel_hi:[1,1,0]
	v_cndmask_b32_e32 v118, v183, v181, vcc
	v_pk_fma_f32 v[108:109], v[124:125], v[108:109], s[12:13] op_sel_hi:[1,1,0]
	v_cmp_gt_f32_e32 vcc, 0, v175
	v_pk_fma_f32 v[108:109], v[124:125], v[108:109], s[88:89] op_sel_hi:[1,1,0]
	v_cmp_ne_u32_e64 s[12:13], 1, v100
	v_pk_mul_f32 v[108:109], v[124:125], v[108:109]
	s_nop 0
	v_pk_mul_f32 v[108:109], v[120:121], v[108:109]
	s_nop 0
	v_pk_mul_f32 v[120:121], v[174:175], v[108:109]
	v_pk_fma_f32 v[108:109], v[174:175], v[108:109], v[174:175] neg_lo:[1,0,0] neg_hi:[1,0,0]
	s_nop 0
	v_cndmask_b32_e32 v109, v109, v121, vcc
	v_cmp_gt_f32_e32 vcc, 0, v174
	s_nop 1
	v_cndmask_b32_e32 v108, v108, v120, vcc
	s_andn2_b64 vcc, exec, s[0:1]
	v_cvt_pk_bf16_f32 v120, v96, v98
	v_cvt_pk_bf16_f32 v121, v97, v99
	v_cvt_pk_bf16_f32 v122, v103, v118
	v_cvt_pk_bf16_f32 v123, v108, v109
	global_store_dwordx4 v[114:115], v[120:123], off offset:256
	s_cbranch_vccnz .LBB0_760
	v_mov_b32_e32 v100, v103
	v_mov_b32_e32 v119, v101
	v_pk_add_f32 v[114:115], v[100:101], v[118:119]
	v_pk_mul_f32 v[120:121], v[100:101], v[118:119]
	v_mov_b32_e32 v122, v102
	v_mov_b32_e32 v123, v116
	v_mul_f32_e32 v100, v102, v102
	v_mov_b32_e32 v117, v103
	v_pk_fma_f32 v[122:123], v[122:123], v[122:123], v[100:101] op_sel_hi:[1,1,0]
	v_mul_f32_e32 v100, v108, v108
	v_pk_fma_f32 v[124:125], v[108:109], v[108:109], v[100:101] op_sel_hi:[1,1,0]
	v_mov_b32_e32 v126, v96
	v_mov_b32_e32 v127, v98
	v_mul_f32_e32 v100, v96, v96
	v_pk_add_f32 v[170:171], v[102:103], v[116:117]
	v_pk_mul_f32 v[102:103], v[102:103], v[116:117]
	v_mov_b32_e32 v115, v121
	v_pk_mul_f32 v[120:121], v[106:107], v[106:107]
	v_pk_fma_f32 v[126:127], v[126:127], v[126:127], v[100:101] op_sel_hi:[1,1,0]
	v_mov_b32_e32 v168, v97
	v_mov_b32_e32 v169, v99
	v_mul_f32_e32 v100, v97, v97
	v_mov_b32_e32 v171, v103
	v_pk_mul_f32 v[102:103], v[118:119], v[118:119]
	v_pk_add_f32 v[96:97], v[96:97], v[98:99]
	v_and_b32_e32 v99, 64, v192
	v_pk_fma_f32 v[120:121], v[104:105], v[104:105], v[120:121]
	v_pk_add_f32 v[104:105], v[104:105], v[106:107]
	v_xor_b32_e32 v98, 16, v192
	v_add_u32_e32 v103, 64, v99
	v_pk_fma_f32 v[168:169], v[168:169], v[168:169], v[100:101] op_sel_hi:[1,1,0]
	v_pk_add_f32 v[104:105], v[104:105], v[104:105] op_sel:[0,1] op_sel_hi:[1,0]
	v_cmp_lt_i32_e32 vcc, v98, v103
	v_mul_f32_e32 v141, v110, v110
	v_pk_add_f32 v[120:121], v[120:121], v[120:121] op_sel_hi:[0,1]
	v_cndmask_b32_e32 v98, v192, v98, vcc
	v_mov_b32_e32 v126, v101
	v_mov_b32_e32 v111, v169
	v_mov_b32_e32 v105, v102
	v_pk_add_f32 v[96:97], v[96:97], v[96:97] op_sel:[0,1] op_sel_hi:[1,0]
	v_lshlrev_b32_e32 v106, 2, v98
	v_pk_add_f32 v[98:99], v[126:127], v[110:111]
	v_pk_add_f32 v[100:101], v[170:171], v[104:105]
	v_mov_b32_e32 v122, v108
	v_mov_b32_e32 v120, v109
	v_mov_b32_e32 v97, v141
	v_pk_add_f32 v[98:99], v[100:101], v[98:99]
	v_mov_b32_e32 v147, v125
	v_pk_add_f32 v[100:101], v[122:123], v[120:121]
	v_pk_add_f32 v[96:97], v[114:115], v[96:97]
	v_pk_add_f32 v[98:99], v[98:99], v[146:147]
	v_pk_add_f32 v[96:97], v[96:97], v[100:101]
	v_xor_b32_e32 v100, 32, v192
	v_pk_add_f32 v[96:97], v[96:97], v[98:99]
	ds_bpermute_b32 v98, v106, v96
	ds_bpermute_b32 v99, v106, v97
	v_cmp_lt_i32_e32 vcc, v100, v103
	s_waitcnt lgkmcnt(0)
	v_pk_add_f32 v[96:97], v[96:97], v[98:99]
	v_cndmask_b32_e32 v100, v192, v100, vcc
	v_lshlrev_b32_e32 v100, 2, v100
	v_mov_b32_e32 v98, v96
	s_nop 1
	v_permlane32_swap_b32_e32 v98, v96
	v_mov_b32_e32 v99, v97
	s_nop 1
	v_permlane32_swap_b32_e32 v99, v97
	s_and_saveexec_b64 s[0:1], s[10:11]
	s_cbranch_execz .LBB0_759
	s_waitcnt lgkmcnt(0)
	v_pk_add_f32 v[96:97], v[96:97], v[98:99]
	v_lshlrev_b64 v[98:99], 7, v[112:113]
	v_lshl_add_u64 v[98:99], s[16:17], 0, v[98:99]
	v_lshl_add_u64 v[98:99], s[38:39], 3, v[98:99]
	s_lshl_b32 s88, s44, 3
	v_lshl_add_u64 v[98:99], v[98:99], 0, s[88:89]
	global_store_dwordx2 v[98:99], v[96:97], off

; __device__ __forceinline__ u32x4 pack8(const f32x4& a, const f32x4& b) { u32x4 w; w.x = cvt_pk_bf16(a[0], a[1]); w.y = cvt_pk_bf16(a[2], a[3]); w.z = cvt_pk_bf16(b[0], b[1]); w.w = cvt_pk_bf16(b[2], b[3]); return w; }
; __device__ __forceinline__ f32x2 gelu_pk(f32x2 v) {
;     const f32x2 av = __builtin_elementwise_abs(v), d = av * 0.2316418882f + 1.0f;
;     f32x2 t; t.x = __builtin_amdgcn_rcpf(d.x); t.y = __builtin_amdgcn_rcpf(d.y);
;     f32x2 q = t * 0.5307027145f + (-0.7265760135f); q = q * t + 0.7107068705f; q = q * t + (-0.142248368f); q = q * t + 0.127414796f; q = q * t;
;     const f32x2 s = (v * v) * (-0.72134752044f);
;     f32x2 e; e.x = __builtin_amdgcn_exp2f(s.x); e.y = __builtin_amdgcn_exp2f(s.y);
;     const f32x2 m = v * (q * e), r = v - m;
;     f32x2 o; o.x = v.x < 0.f ? m.x : r.x; o.y = v.y < 0.f ? m.y : r.y; return o;
;     __device__ __forceinline__ void operator()(const f32x4 (&acc)[2][2][4][2], const Unit& u, int ui, int wr, int wc, int fr, int fq) const {
;     ...
;             for (int m = 0; m < 4; ++m) { const float r = rs[ai][m]; const int row = row0 + ai * HALF + m * 16; bf16_t* rowp = Z + (size_t)row * 2048 + col0; float s1 = 0.f, s2 = 0.f;
; #pragma unroll
;                 for (int bj = 0; bj < 2; ++bj) { const f32x4 v0 = acc[ai][bj][m][0] * r, v1 = acc[ai][bj][m][1] * r;
;                     const f32x2 a = gelu_pk((f32x2){v0[0], v0[1]}), b = gelu_pk((f32x2){v0[2], v0[3]}), c = gelu_pk((f32x2){v1[0], v1[1]}), d = gelu_pk((f32x2){v1[2], v1[3]});
;                     const f32x4 z0 = (f32x4){a.x, a.y, b.x, b.y}, z1 = (f32x4){c.x, c.y, d.x, d.y};
;                     *(u32x4*)(rowp + bj * HALF) = pack8(z0, z1);
.LBB0_760:
	v_pk_mul_f32 v[100:101], v[92:93], v[166:167] op_sel_hi:[1,0]
	s_mov_b32 s0, 0xbf3a00e3
	v_and_b32_e32 v93, 0x7fffffff, v101
	v_and_b32_e32 v92, 0x7fffffff, v100
	v_pk_fma_f32 v[92:93], v[92:93], s[56:57], 1.0 op_sel_hi:[1,0,0]
	v_pk_mul_f32 v[106:107], v[88:89], v[166:167] op_sel_hi:[1,0]
	v_rcp_f32_e32 v102, v92
	v_rcp_f32_e32 v103, v93
	v_mov_b64_e32 v[92:93], s[0:1]
	s_mov_b32 s0, 0x3f07dc22
	s_mov_b32 s2, 0x3f35f0e3
	v_pk_fma_f32 v[88:89], v[102:103], s[0:1], v[92:93] op_sel_hi:[1,0,0]
	s_mov_b32 s4, 0xbe11a98e
	v_pk_fma_f32 v[88:89], v[102:103], v[88:89], s[2:3] op_sel_hi:[1,1,0]
	s_mov_b32 s88, 0x3e027906
	v_pk_fma_f32 v[88:89], v[102:103], v[88:89], s[4:5] op_sel_hi:[1,1,0]
	v_pk_mul_f32 v[94:95], v[94:95], v[166:167] op_sel_hi:[1,0]
	v_pk_fma_f32 v[88:89], v[102:103], v[88:89], s[88:89] op_sel_hi:[1,1,0]
	v_and_b32_e32 v105, 0x7fffffff, v95
	v_pk_mul_f32 v[88:89], v[102:103], v[88:89]
	v_pk_mul_f32 v[102:103], v[100:101], v[100:101]
	v_and_b32_e32 v104, 0x7fffffff, v94
	v_pk_mul_f32 v[102:103], v[102:103], s[86:87] op_sel_hi:[1,0]
	v_pk_fma_f32 v[104:105], v[104:105], s[56:57], 1.0 op_sel_hi:[1,0,0]
	v_exp_f32_e32 v102, v102
	v_exp_f32_e32 v103, v103
	v_rcp_f32_e32 v104, v104
	v_rcp_f32_e32 v105, v105
	v_pk_mul_f32 v[108:109], v[90:91], v[166:167] op_sel_hi:[1,0]
	v_pk_mul_f32 v[90:91], v[94:95], v[94:95]
	v_pk_mul_f32 v[88:89], v[102:103], v[88:89]
	v_pk_mul_f32 v[90:91], v[90:91], s[86:87] op_sel_hi:[1,0]
	v_pk_mul_f32 v[102:103], v[100:101], v[88:89]
	v_pk_fma_f32 v[110:111], v[100:101], v[88:89], v[100:101] neg_lo:[1,0,0] neg_hi:[1,0,0]
	v_pk_fma_f32 v[88:89], v[104:105], s[0:1], v[92:93] op_sel_hi:[1,0,0]
	v_exp_f32_e32 v90, v90
	v_pk_fma_f32 v[88:89], v[104:105], v[88:89], s[2:3] op_sel_hi:[1,1,0]
	v_exp_f32_e32 v91, v91
	v_pk_fma_f32 v[88:89], v[104:105], v[88:89], s[4:5] op_sel_hi:[1,1,0]
	v_and_b32_e32 v113, 0x7fffffff, v107
	v_pk_fma_f32 v[88:89], v[104:105], v[88:89], s[88:89] op_sel_hi:[1,1,0]
	v_and_b32_e32 v112, 0x7fffffff, v106
	v_pk_mul_f32 v[88:89], v[104:105], v[88:89]
	v_cmp_gt_f32_e32 vcc, 0, v94
	v_pk_mul_f32 v[88:89], v[90:91], v[88:89]
	v_pk_fma_f32 v[112:113], v[112:113], s[56:57], 1.0 op_sel_hi:[1,0,0]
	v_pk_mul_f32 v[90:91], v[94:95], v[88:89]
	v_pk_fma_f32 v[104:105], v[94:95], v[88:89], v[94:95] neg_lo:[1,0,0] neg_hi:[1,0,0]
	v_rcp_f32_e32 v112, v112
	v_cndmask_b32_e32 v89, v104, v90, vcc
	v_cmp_gt_f32_e32 vcc, 0, v100
	v_rcp_f32_e32 v113, v113
	v_and_b32_e32 v104, 0x7fffffff, v108
	v_cndmask_b32_e32 v88, v110, v102, vcc
	v_cmp_gt_f32_e32 vcc, 0, v95
	v_pk_fma_f32 v[94:95], v[112:113], s[0:1], v[92:93] op_sel_hi:[1,0,0]
	v_pk_mul_f32 v[84:85], v[84:85], v[166:167] op_sel_hi:[1,0]
	v_cndmask_b32_e32 v91, v105, v91, vcc
	v_cmp_gt_f32_e32 vcc, 0, v101
	v_and_b32_e32 v105, 0x7fffffff, v109
	v_pk_fma_f32 v[94:95], v[112:113], v[94:95], s[2:3] op_sel_hi:[1,1,0]
	v_cndmask_b32_e32 v90, v111, v103, vcc
	v_pk_mul_f32 v[102:103], v[106:107], v[106:107]
	v_pk_fma_f32 v[104:105], v[104:105], s[56:57], 1.0 op_sel_hi:[1,0,0]
	v_pk_mul_f32 v[102:103], v[102:103], s[86:87] op_sel_hi:[1,0]
	v_pk_fma_f32 v[94:95], v[112:113], v[94:95], s[4:5] op_sel_hi:[1,1,0]
	v_exp_f32_e32 v102, v102
	v_exp_f32_e32 v103, v103
	v_rcp_f32_e32 v104, v104
	v_rcp_f32_e32 v105, v105
	v_pk_fma_f32 v[94:95], v[112:113], v[94:95], s[88:89] op_sel_hi:[1,1,0]
	v_pk_mul_f32 v[100:101], v[108:109], v[108:109]
	v_pk_mul_f32 v[94:95], v[112:113], v[94:95]
	v_pk_mul_f32 v[100:101], v[100:101], s[86:87] op_sel_hi:[1,0]
	v_pk_mul_f32 v[94:95], v[102:103], v[94:95]
	v_exp_f32_e32 v100, v100
	v_pk_mul_f32 v[102:103], v[106:107], v[94:95]
	v_pk_fma_f32 v[110:111], v[106:107], v[94:95], v[106:107] neg_lo:[1,0,0] neg_hi:[1,0,0]
	v_pk_fma_f32 v[94:95], v[104:105], s[0:1], v[92:93] op_sel_hi:[1,0,0]
	v_exp_f32_e32 v101, v101
	v_pk_fma_f32 v[94:95], v[104:105], v[94:95], s[2:3] op_sel_hi:[1,1,0]
	v_pk_mul_f32 v[118:119], v[80:81], v[166:167] op_sel_hi:[1,0]
	v_pk_fma_f32 v[94:95], v[104:105], v[94:95], s[4:5] op_sel_hi:[1,1,0]
	v_pk_mul_f32 v[86:87], v[86:87], v[166:167] op_sel_hi:[1,0]
	v_pk_fma_f32 v[94:95], v[104:105], v[94:95], s[88:89] op_sel_hi:[1,1,0]
	v_and_b32_e32 v121, 0x7fffffff, v87
	v_pk_mul_f32 v[94:95], v[104:105], v[94:95]
	v_and_b32_e32 v120, 0x7fffffff, v86
	v_pk_mul_f32 v[94:95], v[100:101], v[94:95]
	v_and_b32_e32 v101, 0x7fffffff, v85
	v_and_b32_e32 v100, 0x7fffffff, v84
	v_pk_fma_f32 v[100:101], v[100:101], s[56:57], 1.0 op_sel_hi:[1,0,0]
	v_pk_fma_f32 v[120:121], v[120:121], s[56:57], 1.0 op_sel_hi:[1,0,0]
	v_rcp_f32_e32 v100, v100
	v_rcp_f32_e32 v101, v101
	v_rcp_f32_e32 v120, v120
	v_rcp_f32_e32 v121, v121
	v_pk_mul_f32 v[116:117], v[82:83], v[166:167] op_sel_hi:[1,0]
	v_pk_fma_f32 v[80:81], v[100:101], s[0:1], v[92:93] op_sel_hi:[1,0,0]
	v_pk_mul_f32 v[82:83], v[86:87], v[86:87]
	v_pk_fma_f32 v[80:81], v[100:101], v[80:81], s[2:3] op_sel_hi:[1,1,0]
	v_pk_mul_f32 v[82:83], v[82:83], s[86:87] op_sel_hi:[1,0]
	v_pk_fma_f32 v[80:81], v[100:101], v[80:81], s[4:5] op_sel_hi:[1,1,0]
	v_exp_f32_e32 v82, v82
	v_pk_fma_f32 v[80:81], v[100:101], v[80:81], s[88:89] op_sel_hi:[1,1,0]
	v_exp_f32_e32 v83, v83
	v_pk_mul_f32 v[80:81], v[100:101], v[80:81]
	v_pk_mul_f32 v[100:101], v[84:85], v[84:85]
	v_and_b32_e32 v125, 0x7fffffff, v119
	v_pk_mul_f32 v[100:101], v[100:101], s[86:87] op_sel_hi:[1,0]
	v_and_b32_e32 v124, 0x7fffffff, v118
	v_exp_f32_e32 v100, v100
	v_exp_f32_e32 v101, v101
	v_pk_fma_f32 v[124:125], v[124:125], s[56:57], 1.0 op_sel_hi:[1,0,0]
	v_pk_mul_f32 v[112:113], v[108:109], v[94:95]
	v_pk_fma_f32 v[114:115], v[108:109], v[94:95], v[108:109] neg_lo:[1,0,0] neg_hi:[1,0,0]
	v_pk_mul_f32 v[80:81], v[100:101], v[80:81]
	v_cmp_gt_f32_e32 vcc, 0, v109
	v_pk_mul_f32 v[100:101], v[84:85], v[80:81]
	v_pk_fma_f32 v[122:123], v[84:85], v[80:81], v[84:85] neg_lo:[1,0,0] neg_hi:[1,0,0]
	v_pk_fma_f32 v[80:81], v[120:121], s[0:1], v[92:93] op_sel_hi:[1,0,0]
	v_rcp_f32_e32 v124, v124
	v_pk_fma_f32 v[80:81], v[120:121], v[80:81], s[2:3] op_sel_hi:[1,1,0]
	v_rcp_f32_e32 v125, v125
	v_pk_fma_f32 v[80:81], v[120:121], v[80:81], s[4:5] op_sel_hi:[1,1,0]
	v_cndmask_b32_e32 v94, v115, v113, vcc
	v_pk_fma_f32 v[80:81], v[120:121], v[80:81], s[88:89] op_sel_hi:[1,1,0]
	v_cmp_gt_f32_e32 vcc, 0, v86
	v_pk_mul_f32 v[80:81], v[120:121], v[80:81]
	v_add_u32_e32 v96, 32, v140
	v_pk_mul_f32 v[80:81], v[82:83], v[80:81]
	v_ashrrev_i32_e32 v97, 31, v96
	v_pk_mul_f32 v[82:83], v[86:87], v[80:81]
	v_pk_fma_f32 v[120:121], v[86:87], v[80:81], v[86:87] neg_lo:[1,0,0] neg_hi:[1,0,0]
	s_waitcnt lgkmcnt(0)
; __device__ __forceinline__ u32x4 pack8(const f32x4& a, const f32x4& b) { u32x4 w; w.x = cvt_pk_bf16(a[0], a[1]); w.y = cvt_pk_bf16(a[2], a[3]); w.z = cvt_pk_bf16(b[0], b[1]); w.w = cvt_pk_bf16(b[2], b[3]); return w; }
;     __device__ __forceinline__ void operator()(const f32x4 (&acc)[2][2][4][2], const Unit& u, int ui, int wr, int wc, int fr, int fq) const {
;     ...
;             for (int m = 0; m < 4; ++m) { const float r = rs[ai][m]; const int row = row0 + ai * HALF + m * 16; bf16_t* rowp = Z + (size_t)row * 2048 + col0; float s1 = 0.f, s2 = 0.f;
; #pragma unroll
;                 for (int bj = 0; bj < 2; ++bj) { const f32x4 v0 = acc[ai][bj][m][0] * r, v1 = acc[ai][bj][m][1] * r;
;                     const f32x2 a = gelu_pk((f32x2){v0[0], v0[1]}), b = gelu_pk((f32x2){v0[2], v0[3]}), c = gelu_pk((f32x2){v1[0], v1[1]}), d = gelu_pk((f32x2){v1[2], v1[3]});
;                     const f32x4 z0 = (f32x4){a.x, a.y, b.x, b.y}, z1 = (f32x4){c.x, c.y, d.x, d.y};
;                     *(u32x4*)(rowp + bj * HALF) = pack8(z0, z1);
;                     s1 += (z0[0] + z0[1]) + (z0[2] + z0[3]) + (z1[0] + z1[1]) + (z1[2] + z1[3]);
;                     s2 += (z0[0] * z0[0] + z0[1] * z0[1]) + (z0[2] * z0[2] + z0[3] * z0[3]) + (z1[0] * z1[0] + z1[1] * z1[1]) + (z1[2] * z1[2] + z1[3] * z1[3]); }
;                 if (u.pn >= 4) { s1 += __shfl_xor(s1, 16); s1 += __shfl_xor(s1, 32); s2 += __shfl_xor(s2, 16); s2 += __shfl_xor(s2, 32);
;                     if (fq == 0) vst[(size_t)row * 16 + (u.pn - 4) * 4 + wc] = (f32x2){s1, s2}; } }
	v_lshlrev_b64 v[98:99], 12, v[96:97]
	v_cndmask_b32_e32 v81, v120, v82, vcc
	v_cmp_gt_f32_e32 vcc, 0, v84
	v_lshl_add_u64 v[98:99], s[20:21], 0, v[98:99]
	v_lshl_add_u64 v[98:99], v[162:163], 1, v[98:99]
	v_cndmask_b32_e32 v80, v122, v100, vcc
	v_cmp_gt_f32_e32 vcc, 0, v87
	v_pk_mul_f32 v[86:87], v[118:119], v[118:119]
	v_cvt_pk_bf16_f32 v104, v88, v90
	v_cvt_pk_bf16_f32 v105, v89, v91
	s_nop 0
	v_cndmask_b32_e32 v83, v121, v83, vcc
	v_cmp_gt_f32_e32 vcc, 0, v85
	v_pk_fma_f32 v[84:85], v[124:125], s[0:1], v[92:93] op_sel_hi:[1,0,0]
	v_pk_mul_f32 v[86:87], v[86:87], s[86:87] op_sel_hi:[1,0]
	v_pk_fma_f32 v[84:85], v[124:125], v[84:85], s[2:3] op_sel_hi:[1,1,0]
	v_exp_f32_e32 v86, v86
	v_exp_f32_e32 v87, v87
	v_pk_fma_f32 v[84:85], v[124:125], v[84:85], s[4:5] op_sel_hi:[1,1,0]
	v_cndmask_b32_e32 v82, v123, v101, vcc
	v_pk_fma_f32 v[84:85], v[124:125], v[84:85], s[88:89] op_sel_hi:[1,1,0]
	v_cmp_gt_f32_e32 vcc, 0, v106
	v_pk_mul_f32 v[84:85], v[124:125], v[84:85]
	v_pk_mul_f32 v[120:121], v[116:117], v[116:117]
	v_pk_mul_f32 v[84:85], v[86:87], v[84:85]
	v_cndmask_b32_e32 v86, v110, v102, vcc
	v_pk_mul_f32 v[100:101], v[118:119], v[84:85]
	v_pk_fma_f32 v[122:123], v[118:119], v[84:85], v[118:119] neg_lo:[1,0,0] neg_hi:[1,0,0]
	v_cmp_gt_f32_e32 vcc, 0, v118
	v_and_b32_e32 v102, 0x7fffffff, v116
	s_nop 0
	v_cndmask_b32_e32 v87, v122, v100, vcc
	v_cmp_gt_f32_e32 vcc, 0, v107
	s_nop 1
	v_cndmask_b32_e32 v100, v111, v103, vcc
	v_and_b32_e32 v103, 0x7fffffff, v117
	v_pk_fma_f32 v[102:103], v[102:103], s[56:57], 1.0 op_sel_hi:[1,0,0]
	v_cmp_gt_f32_e32 vcc, 0, v108
	v_rcp_f32_e32 v108, v102
	v_rcp_f32_e32 v109, v103
	v_cvt_pk_bf16_f32 v106, v86, v100
	v_cndmask_b32_e32 v85, v114, v112, vcc
	v_cvt_pk_bf16_f32 v107, v85, v94
	global_store_dwordx4 v[98:99], v[104:107], off
	v_pk_fma_f32 v[92:93], v[108:109], s[0:1], v[92:93] op_sel_hi:[1,0,0]
	v_cmp_gt_f32_e32 vcc, 0, v119
	v_pk_mul_f32 v[104:105], v[120:121], s[86:87] op_sel_hi:[1,0]
	v_pk_fma_f32 v[92:93], v[108:109], v[92:93], s[2:3] op_sel_hi:[1,1,0]
	v_exp_f32_e32 v104, v104
	v_exp_f32_e32 v105, v105
	v_pk_fma_f32 v[92:93], v[108:109], v[92:93], s[4:5] op_sel_hi:[1,1,0]
	v_cndmask_b32_e32 v102, v123, v101, vcc
	v_pk_fma_f32 v[92:93], v[108:109], v[92:93], s[88:89] op_sel_hi:[1,1,0]
	v_cmp_gt_f32_e32 vcc, 0, v117
	v_pk_mul_f32 v[92:93], v[108:109], v[92:93]
	s_nop 0
	v_pk_mul_f32 v[92:93], v[104:105], v[92:93]
	s_nop 0
	v_pk_mul_f32 v[104:105], v[116:117], v[92:93]
	v_pk_fma_f32 v[92:93], v[116:117], v[92:93], v[116:117] neg_lo:[1,0,0] neg_hi:[1,0,0]
	s_nop 0
	v_cndmask_b32_e32 v93, v93, v105, vcc
	v_cmp_gt_f32_e32 vcc, 0, v116
	s_nop 1
	v_cndmask_b32_e32 v92, v92, v104, vcc
	s_and_b64 vcc, exec, s[12:13]
	v_cvt_pk_bf16_f32 v104, v80, v82
	v_cvt_pk_bf16_f32 v105, v81, v83
	v_cvt_pk_bf16_f32 v106, v87, v102
	v_cvt_pk_bf16_f32 v107, v92, v93
	global_store_dwordx4 v[98:99], v[104:107], off offset:256
	s_cbranch_vccnz .LBB0_764
	v_mov_b32_e32 v84, v87
	v_mov_b32_e32 v103, v85
	v_pk_add_f32 v[98:99], v[84:85], v[102:103]
	v_pk_mul_f32 v[104:105], v[84:85], v[102:103]
	v_mov_b32_e32 v106, v86
	v_mov_b32_e32 v107, v100
	v_mul_f32_e32 v84, v86, v86
	v_mov_b32_e32 v101, v87
	v_pk_fma_f32 v[106:107], v[106:107], v[106:107], v[84:85] op_sel_hi:[1,1,0]
	v_mul_f32_e32 v84, v92, v92
	v_pk_fma_f32 v[108:109], v[92:93], v[92:93], v[84:85] op_sel_hi:[1,1,0]
	v_mov_b32_e32 v110, v80
	v_mov_b32_e32 v111, v82
	v_mul_f32_e32 v84, v80, v80
	v_pk_add_f32 v[114:115], v[86:87], v[100:101]
	v_pk_mul_f32 v[86:87], v[86:87], v[100:101]
	v_mov_b32_e32 v99, v105
	v_pk_mul_f32 v[104:105], v[90:91], v[90:91]
	v_pk_fma_f32 v[110:111], v[110:111], v[110:111], v[84:85] op_sel_hi:[1,1,0]
	v_mov_b32_e32 v112, v81
	v_mov_b32_e32 v113, v83
	v_mul_f32_e32 v84, v81, v81
	v_mov_b32_e32 v115, v87
	v_pk_mul_f32 v[86:87], v[102:103], v[102:103]
	v_pk_add_f32 v[80:81], v[80:81], v[82:83]
	v_and_b32_e32 v83, 64, v192
	v_pk_fma_f32 v[104:105], v[88:89], v[88:89], v[104:105]
	v_pk_add_f32 v[88:89], v[88:89], v[90:91]
	v_xor_b32_e32 v82, 16, v192
	v_add_u32_e32 v87, 64, v83
	v_pk_fma_f32 v[112:113], v[112:113], v[112:113], v[84:85] op_sel_hi:[1,1,0]
	v_pk_add_f32 v[88:89], v[88:89], v[88:89] op_sel:[0,1] op_sel_hi:[1,0]
	v_cmp_lt_i32_e32 vcc, v82, v87
	v_mul_f32_e32 v116, v94, v94
	v_pk_add_f32 v[104:105], v[104:105], v[104:105] op_sel_hi:[0,1]
	v_cndmask_b32_e32 v82, v192, v82, vcc
	v_mov_b32_e32 v110, v85
	v_mov_b32_e32 v95, v113
	v_mov_b32_e32 v89, v86
	v_pk_add_f32 v[80:81], v[80:81], v[80:81] op_sel:[0,1] op_sel_hi:[1,0]
	v_lshlrev_b32_e32 v90, 2, v82
	v_pk_add_f32 v[82:83], v[110:111], v[94:95]
	v_pk_add_f32 v[84:85], v[114:115], v[88:89]
	v_mov_b32_e32 v106, v92
	v_mov_b32_e32 v104, v93
	v_mov_b32_e32 v81, v116
	v_pk_add_f32 v[82:83], v[84:85], v[82:83]
	v_mov_b32_e32 v147, v109
	v_pk_add_f32 v[84:85], v[106:107], v[104:105]
	v_pk_add_f32 v[80:81], v[98:99], v[80:81]
	v_pk_add_f32 v[82:83], v[82:83], v[146:147]
	v_pk_add_f32 v[80:81], v[80:81], v[84:85]
	v_xor_b32_e32 v84, 32, v192
	v_pk_add_f32 v[80:81], v[80:81], v[82:83]
	ds_bpermute_b32 v82, v90, v80
	ds_bpermute_b32 v83, v90, v81
	v_cmp_lt_i32_e32 vcc, v84, v87
	s_waitcnt lgkmcnt(0)
	v_pk_add_f32 v[80:81], v[80:81], v[82:83]
	v_cndmask_b32_e32 v84, v192, v84, vcc
	v_lshlrev_b32_e32 v84, 2, v84
	v_mov_b32_e32 v82, v80
	s_nop 1
	v_permlane32_swap_b32_e32 v82, v80
	v_mov_b32_e32 v83, v81
	s_nop 1
	v_permlane32_swap_b32_e32 v83, v81
	s_and_saveexec_b64 s[0:1], s[10:11]
	s_cbranch_execz .LBB0_763
	s_waitcnt lgkmcnt(0)
	v_pk_add_f32 v[80:81], v[80:81], v[82:83]
	v_lshlrev_b64 v[82:83], 7, v[96:97]
	v_lshl_add_u64 v[82:83], s[16:17], 0, v[82:83]
	v_lshl_add_u64 v[82:83], s[38:39], 3, v[82:83]
	s_lshl_b32 s88, s44, 3
	v_lshl_add_u64 v[82:83], v[82:83], 0, s[88:89]
	global_store_dwordx2 v[82:83], v[80:81], off

; __device__ __forceinline__ u32x4 pack8(const f32x4& a, const f32x4& b) { u32x4 w; w.x = cvt_pk_bf16(a[0], a[1]); w.y = cvt_pk_bf16(a[2], a[3]); w.z = cvt_pk_bf16(b[0], b[1]); w.w = cvt_pk_bf16(b[2], b[3]); return w; }
; __device__ __forceinline__ f32x2 gelu_pk(f32x2 v) {
;     const f32x2 av = __builtin_elementwise_abs(v), d = av * 0.2316418882f + 1.0f;
;     f32x2 t; t.x = __builtin_amdgcn_rcpf(d.x); t.y = __builtin_amdgcn_rcpf(d.y);
;     f32x2 q = t * 0.5307027145f + (-0.7265760135f); q = q * t + 0.7107068705f; q = q * t + (-0.142248368f); q = q * t + 0.127414796f; q = q * t;
;     const f32x2 s = (v * v) * (-0.72134752044f);
;     f32x2 e; e.x = __builtin_amdgcn_exp2f(s.x); e.y = __builtin_amdgcn_exp2f(s.y);
;     const f32x2 m = v * (q * e), r = v - m;
;     f32x2 o; o.x = v.x < 0.f ? m.x : r.x; o.y = v.y < 0.f ? m.y : r.y; return o;
;     __device__ __forceinline__ void operator()(const f32x4 (&acc)[2][2][4][2], const Unit& u, int ui, int wr, int wc, int fr, int fq) const {
;     ...
;             for (int m = 0; m < 4; ++m) { const float r = rs[ai][m]; const int row = row0 + ai * HALF + m * 16; bf16_t* rowp = Z + (size_t)row * 2048 + col0; float s1 = 0.f, s2 = 0.f;
; #pragma unroll
;                 for (int bj = 0; bj < 2; ++bj) { const f32x4 v0 = acc[ai][bj][m][0] * r, v1 = acc[ai][bj][m][1] * r;
;                     const f32x2 a = gelu_pk((f32x2){v0[0], v0[1]}), b = gelu_pk((f32x2){v0[2], v0[3]}), c = gelu_pk((f32x2){v1[0], v1[1]}), d = gelu_pk((f32x2){v1[2], v1[3]});
;                     const f32x4 z0 = (f32x4){a.x, a.y, b.x, b.y}, z1 = (f32x4){c.x, c.y, d.x, d.y};
;                     *(u32x4*)(rowp + bj * HALF) = pack8(z0, z1);
.LBB0_764:
	v_mov_b32_e32 v84, v167
	v_pk_mul_f32 v[86:87], v[76:77], v[84:85] op_sel_hi:[1,0]
	s_mov_b32 s0, 0xbf3a00e3
	v_and_b32_e32 v77, 0x7fffffff, v87
	v_and_b32_e32 v76, 0x7fffffff, v86
	v_pk_fma_f32 v[76:77], v[76:77], s[56:57], 1.0 op_sel_hi:[1,0,0]
	v_pk_mul_f32 v[90:91], v[72:73], v[84:85] op_sel_hi:[1,0]
	v_rcp_f32_e32 v88, v76
	v_rcp_f32_e32 v89, v77
	v_mov_b64_e32 v[76:77], s[0:1]
	s_mov_b32 s0, 0x3f07dc22
	s_mov_b32 s88, 0x3e027906
	v_pk_fma_f32 v[72:73], v[88:89], s[0:1], v[76:77] op_sel_hi:[1,0,0]
	v_pk_mul_f32 v[78:79], v[78:79], v[84:85] op_sel_hi:[1,0]
	v_pk_fma_f32 v[72:73], v[88:89], v[72:73], s[2:3] op_sel_hi:[1,1,0]
	v_and_b32_e32 v95, 0x7fffffff, v79
	v_pk_fma_f32 v[72:73], v[88:89], v[72:73], s[4:5] op_sel_hi:[1,1,0]
	v_and_b32_e32 v94, 0x7fffffff, v78
	v_pk_fma_f32 v[72:73], v[88:89], v[72:73], s[88:89] op_sel_hi:[1,1,0]
	v_pk_fma_f32 v[94:95], v[94:95], s[56:57], 1.0 op_sel_hi:[1,0,0]
	v_pk_mul_f32 v[72:73], v[88:89], v[72:73]
	v_pk_mul_f32 v[88:89], v[86:87], v[86:87]
	v_rcp_f32_e32 v94, v94
	v_pk_mul_f32 v[88:89], v[88:89], s[86:87] op_sel_hi:[1,0]
	v_rcp_f32_e32 v95, v95
	v_exp_f32_e32 v88, v88
	v_exp_f32_e32 v89, v89
	v_pk_mul_f32 v[92:93], v[74:75], v[84:85] op_sel_hi:[1,0]
	v_pk_mul_f32 v[74:75], v[78:79], v[78:79]
	v_pk_mul_f32 v[68:69], v[68:69], v[84:85] op_sel_hi:[1,0]
	v_pk_mul_f32 v[72:73], v[88:89], v[72:73]
	v_pk_mul_f32 v[74:75], v[74:75], s[86:87] op_sel_hi:[1,0]
	v_pk_mul_f32 v[88:89], v[86:87], v[72:73]
	v_pk_fma_f32 v[96:97], v[86:87], v[72:73], v[86:87] neg_lo:[1,0,0] neg_hi:[1,0,0]
	v_pk_fma_f32 v[72:73], v[94:95], s[0:1], v[76:77] op_sel_hi:[1,0,0]
	v_exp_f32_e32 v74, v74
	v_pk_fma_f32 v[72:73], v[94:95], v[72:73], s[2:3] op_sel_hi:[1,1,0]
	v_exp_f32_e32 v75, v75
	v_and_b32_e32 v101, 0x7fffffff, v69
	v_and_b32_e32 v100, 0x7fffffff, v68
	v_pk_fma_f32 v[72:73], v[94:95], v[72:73], s[4:5] op_sel_hi:[1,1,0]
	v_pk_fma_f32 v[100:101], v[100:101], s[56:57], 1.0 op_sel_hi:[1,0,0]
	v_pk_fma_f32 v[72:73], v[94:95], v[72:73], s[88:89] op_sel_hi:[1,1,0]
	v_rcp_f32_e32 v100, v100
	v_rcp_f32_e32 v101, v101
	v_pk_mul_f32 v[72:73], v[94:95], v[72:73]
	v_and_b32_e32 v99, 0x7fffffff, v91
	v_pk_mul_f32 v[72:73], v[74:75], v[72:73]
	v_and_b32_e32 v98, 0x7fffffff, v90
	v_pk_mul_f32 v[74:75], v[78:79], v[72:73]
	v_pk_fma_f32 v[94:95], v[78:79], v[72:73], v[78:79] neg_lo:[1,0,0] neg_hi:[1,0,0]
	v_cmp_gt_f32_e32 vcc, 0, v78
	v_pk_fma_f32 v[98:99], v[98:99], s[56:57], 1.0 op_sel_hi:[1,0,0]
	v_pk_mul_f32 v[70:71], v[70:71], v[84:85] op_sel_hi:[1,0]
	v_cndmask_b32_e32 v73, v94, v74, vcc
	v_cmp_gt_f32_e32 vcc, 0, v86
	v_rcp_f32_e32 v98, v98
	v_rcp_f32_e32 v99, v99
	v_pk_mul_f32 v[102:103], v[66:67], v[84:85] op_sel_hi:[1,0]
	v_pk_mul_f32 v[84:85], v[64:65], v[84:85] op_sel_hi:[1,0]
	v_pk_fma_f32 v[64:65], v[100:101], s[0:1], v[76:77] op_sel_hi:[1,0,0]
	v_cndmask_b32_e32 v72, v96, v88, vcc
	v_cmp_gt_f32_e32 vcc, 0, v79
	v_pk_fma_f32 v[64:65], v[100:101], v[64:65], s[2:3] op_sel_hi:[1,1,0]
	v_pk_fma_f32 v[78:79], v[98:99], s[0:1], v[76:77] op_sel_hi:[1,0,0]
	v_cndmask_b32_e32 v75, v95, v75, vcc
	v_cmp_gt_f32_e32 vcc, 0, v87
	v_pk_fma_f32 v[64:65], v[100:101], v[64:65], s[4:5] op_sel_hi:[1,1,0]
	v_and_b32_e32 v95, 0x7fffffff, v93
	v_cndmask_b32_e32 v74, v97, v89, vcc
	v_pk_mul_f32 v[88:89], v[90:91], v[90:91]
	v_pk_fma_f32 v[64:65], v[100:101], v[64:65], s[88:89] op_sel_hi:[1,1,0]
	v_pk_mul_f32 v[88:89], v[88:89], s[86:87] op_sel_hi:[1,0]
	v_and_b32_e32 v94, 0x7fffffff, v92
	v_pk_mul_f32 v[64:65], v[100:101], v[64:65]
	v_pk_mul_f32 v[100:101], v[68:69], v[68:69]
	v_pk_fma_f32 v[78:79], v[98:99], v[78:79], s[2:3] op_sel_hi:[1,1,0]
	v_exp_f32_e32 v88, v88
	v_exp_f32_e32 v89, v89
	v_pk_fma_f32 v[94:95], v[94:95], s[56:57], 1.0 op_sel_hi:[1,0,0]
	v_pk_mul_f32 v[100:101], v[100:101], s[86:87] op_sel_hi:[1,0]
	v_and_b32_e32 v105, 0x7fffffff, v71
	v_and_b32_e32 v104, 0x7fffffff, v70
	v_pk_fma_f32 v[78:79], v[98:99], v[78:79], s[4:5] op_sel_hi:[1,1,0]
	v_rcp_f32_e32 v94, v94
	v_rcp_f32_e32 v95, v95
	v_exp_f32_e32 v100, v100
	v_exp_f32_e32 v101, v101
	v_pk_fma_f32 v[104:105], v[104:105], s[56:57], 1.0 op_sel_hi:[1,0,0]
	v_pk_fma_f32 v[78:79], v[98:99], v[78:79], s[88:89] op_sel_hi:[1,1,0]
	v_rcp_f32_e32 v104, v104
	v_rcp_f32_e32 v105, v105
	v_pk_mul_f32 v[78:79], v[98:99], v[78:79]
	v_pk_mul_f32 v[86:87], v[92:93], v[92:93]
	v_pk_mul_f32 v[78:79], v[88:89], v[78:79]
	v_pk_mul_f32 v[86:87], v[86:87], s[86:87] op_sel_hi:[1,0]
	v_pk_mul_f32 v[96:97], v[90:91], v[78:79]
	v_pk_fma_f32 v[98:99], v[90:91], v[78:79], v[90:91] neg_lo:[1,0,0] neg_hi:[1,0,0]
	v_pk_fma_f32 v[78:79], v[94:95], s[0:1], v[76:77] op_sel_hi:[1,0,0]
	v_pk_mul_f32 v[66:67], v[70:71], v[70:71]
	v_pk_mul_f32 v[64:65], v[100:101], v[64:65]
	v_pk_fma_f32 v[78:79], v[94:95], v[78:79], s[2:3] op_sel_hi:[1,1,0]
	v_exp_f32_e32 v86, v86
	v_exp_f32_e32 v87, v87
	v_pk_mul_f32 v[100:101], v[68:69], v[64:65]
	v_pk_fma_f32 v[106:107], v[68:69], v[64:65], v[68:69] neg_lo:[1,0,0] neg_hi:[1,0,0]
	v_pk_fma_f32 v[64:65], v[104:105], s[0:1], v[76:77] op_sel_hi:[1,0,0]
	v_pk_mul_f32 v[66:67], v[66:67], s[86:87] op_sel_hi:[1,0]
	v_pk_fma_f32 v[78:79], v[94:95], v[78:79], s[4:5] op_sel_hi:[1,1,0]
	v_pk_fma_f32 v[64:65], v[104:105], v[64:65], s[2:3] op_sel_hi:[1,1,0]
	v_exp_f32_e32 v66, v66
	v_exp_f32_e32 v67, v67
	v_pk_fma_f32 v[78:79], v[94:95], v[78:79], s[88:89] op_sel_hi:[1,1,0]
	v_pk_fma_f32 v[64:65], v[104:105], v[64:65], s[4:5] op_sel_hi:[1,1,0]
	v_pk_mul_f32 v[78:79], v[94:95], v[78:79]
	v_pk_fma_f32 v[64:65], v[104:105], v[64:65], s[88:89] op_sel_hi:[1,1,0]
	v_and_b32_e32 v109, 0x7fffffff, v85
	v_and_b32_e32 v108, 0x7fffffff, v84
	v_pk_mul_f32 v[78:79], v[86:87], v[78:79]
	v_pk_mul_f32 v[64:65], v[104:105], v[64:65]
	v_pk_fma_f32 v[108:109], v[108:109], s[56:57], 1.0 op_sel_hi:[1,0,0]
	v_pk_mul_f32 v[86:87], v[92:93], v[78:79]
	v_pk_fma_f32 v[94:95], v[92:93], v[78:79], v[92:93] neg_lo:[1,0,0] neg_hi:[1,0,0]
	v_cmp_gt_f32_e32 vcc, 0, v93
	v_pk_mul_f32 v[64:65], v[66:67], v[64:65]
	v_rcp_f32_e32 v108, v108
	v_rcp_f32_e32 v109, v109
	v_cndmask_b32_e32 v78, v95, v87, vcc
	v_pk_mul_f32 v[66:67], v[70:71], v[64:65]
	v_pk_fma_f32 v[104:105], v[70:71], v[64:65], v[70:71] neg_lo:[1,0,0] neg_hi:[1,0,0]
	v_cmp_gt_f32_e32 vcc, 0, v70
	v_and_b32_e32 v87, 0x7fffffff, v103
	v_add_u32_e32 v80, 48, v140
	v_cndmask_b32_e32 v65, v104, v66, vcc
	v_cmp_gt_f32_e32 vcc, 0, v68
	v_ashrrev_i32_e32 v81, 31, v80
	s_waitcnt lgkmcnt(0)
; __device__ __forceinline__ u32x4 pack8(const f32x4& a, const f32x4& b) { u32x4 w; w.x = cvt_pk_bf16(a[0], a[1]); w.y = cvt_pk_bf16(a[2], a[3]); w.z = cvt_pk_bf16(b[0], b[1]); w.w = cvt_pk_bf16(b[2], b[3]); return w; }
;     __device__ __forceinline__ void operator()(const f32x4 (&acc)[2][2][4][2], const Unit& u, int ui, int wr, int wc, int fr, int fq) const {
;     ...
;             for (int m = 0; m < 4; ++m) { const float r = rs[ai][m]; const int row = row0 + ai * HALF + m * 16; bf16_t* rowp = Z + (size_t)row * 2048 + col0; float s1 = 0.f, s2 = 0.f;
; #pragma unroll
;                 for (int bj = 0; bj < 2; ++bj) { const f32x4 v0 = acc[ai][bj][m][0] * r, v1 = acc[ai][bj][m][1] * r;
;                     const f32x2 a = gelu_pk((f32x2){v0[0], v0[1]}), b = gelu_pk((f32x2){v0[2], v0[3]}), c = gelu_pk((f32x2){v1[0], v1[1]}), d = gelu_pk((f32x2){v1[2], v1[3]});
;                     const f32x4 z0 = (f32x4){a.x, a.y, b.x, b.y}, z1 = (f32x4){c.x, c.y, d.x, d.y};
;                     *(u32x4*)(rowp + bj * HALF) = pack8(z0, z1);
;                     s1 += (z0[0] + z0[1]) + (z0[2] + z0[3]) + (z1[0] + z1[1]) + (z1[2] + z1[3]);
;                     s2 += (z0[0] * z0[0] + z0[1] * z0[1]) + (z0[2] * z0[2] + z0[3] * z0[3]) + (z1[0] * z1[0] + z1[1] * z1[1]) + (z1[2] * z1[2] + z1[3] * z1[3]); }
;                 if (u.pn >= 4) { s1 += __shfl_xor(s1, 16); s1 += __shfl_xor(s1, 32); s2 += __shfl_xor(s2, 16); s2 += __shfl_xor(s2, 32);
;                     if (fq == 0) vst[(size_t)row * 16 + (u.pn - 4) * 4 + wc] = (f32x2){s1, s2}; } }
	v_lshlrev_b64 v[82:83], 12, v[80:81]
	v_cndmask_b32_e32 v64, v106, v100, vcc
	v_cmp_gt_f32_e32 vcc, 0, v71
	v_pk_mul_f32 v[70:71], v[84:85], v[84:85]
	v_lshl_add_u64 v[82:83], s[20:21], 0, v[82:83]
	v_cndmask_b32_e32 v67, v105, v67, vcc
	v_cmp_gt_f32_e32 vcc, 0, v69
	v_pk_fma_f32 v[68:69], v[108:109], s[0:1], v[76:77] op_sel_hi:[1,0,0]
	v_pk_mul_f32 v[70:71], v[70:71], s[86:87] op_sel_hi:[1,0]
	v_pk_fma_f32 v[68:69], v[108:109], v[68:69], s[2:3] op_sel_hi:[1,1,0]
	v_exp_f32_e32 v70, v70
	v_exp_f32_e32 v71, v71
	v_pk_fma_f32 v[68:69], v[108:109], v[68:69], s[4:5] op_sel_hi:[1,1,0]
	v_cndmask_b32_e32 v66, v107, v101, vcc
	v_pk_fma_f32 v[68:69], v[108:109], v[68:69], s[88:89] op_sel_hi:[1,1,0]
	v_cmp_gt_f32_e32 vcc, 0, v90
	v_pk_mul_f32 v[68:69], v[108:109], v[68:69]
	v_lshl_add_u64 v[82:83], v[162:163], 1, v[82:83]
	v_pk_mul_f32 v[68:69], v[70:71], v[68:69]
	v_cndmask_b32_e32 v70, v98, v96, vcc
	v_pk_mul_f32 v[104:105], v[84:85], v[68:69]
	v_pk_fma_f32 v[106:107], v[84:85], v[68:69], v[84:85] neg_lo:[1,0,0] neg_hi:[1,0,0]
	v_cmp_gt_f32_e32 vcc, 0, v84
	v_cvt_pk_bf16_f32 v88, v72, v74
	v_cvt_pk_bf16_f32 v89, v73, v75
	v_pk_mul_f32 v[100:101], v[102:103], v[102:103]
	s_nop 0
	v_cndmask_b32_e32 v71, v106, v104, vcc
	v_cmp_gt_f32_e32 vcc, 0, v91
	s_nop 1
	v_cndmask_b32_e32 v84, v99, v97, vcc
	v_cmp_gt_f32_e32 vcc, 0, v92
	v_cvt_pk_bf16_f32 v90, v70, v84
	s_nop 1
	v_cndmask_b32_e32 v69, v94, v86, vcc
	v_and_b32_e32 v86, 0x7fffffff, v102
	v_pk_fma_f32 v[86:87], v[86:87], s[56:57], 1.0 op_sel_hi:[1,0,0]
	v_cvt_pk_bf16_f32 v91, v69, v78
	global_store_dwordx4 v[82:83], v[88:91], off
	v_rcp_f32_e32 v92, v86
	v_rcp_f32_e32 v93, v87
	v_pk_mul_f32 v[88:89], v[100:101], s[86:87] op_sel_hi:[1,0]
	v_cmp_gt_f32_e32 vcc, 0, v85
	v_exp_f32_e32 v88, v88
	v_pk_fma_f32 v[76:77], v[92:93], s[0:1], v[76:77] op_sel_hi:[1,0,0]
	v_exp_f32_e32 v89, v89
	v_pk_fma_f32 v[76:77], v[92:93], v[76:77], s[2:3] op_sel_hi:[1,1,0]
	v_cndmask_b32_e32 v86, v107, v105, vcc
	v_pk_fma_f32 v[76:77], v[92:93], v[76:77], s[4:5] op_sel_hi:[1,1,0]
	v_cmp_gt_f32_e32 vcc, 0, v103
	v_pk_fma_f32 v[76:77], v[92:93], v[76:77], s[88:89] op_sel_hi:[1,1,0]
	s_nop 0
	v_pk_mul_f32 v[76:77], v[92:93], v[76:77]
	s_nop 0
	v_pk_mul_f32 v[76:77], v[88:89], v[76:77]
	s_nop 0
	v_pk_mul_f32 v[88:89], v[102:103], v[76:77]
	v_pk_fma_f32 v[76:77], v[102:103], v[76:77], v[102:103] neg_lo:[1,0,0] neg_hi:[1,0,0]
	s_nop 0
	v_cndmask_b32_e32 v77, v77, v89, vcc
	v_cmp_gt_f32_e32 vcc, 0, v102
	s_nop 1
	v_cndmask_b32_e32 v76, v76, v88, vcc
	s_and_b64 vcc, exec, s[12:13]
	v_cvt_pk_bf16_f32 v88, v64, v66
	v_cvt_pk_bf16_f32 v89, v65, v67
	v_cvt_pk_bf16_f32 v90, v71, v86
	v_cvt_pk_bf16_f32 v91, v76, v77
	global_store_dwordx4 v[82:83], v[88:91], off offset:256
	s_cbranch_vccnz .LBB0_768
	v_mov_b32_e32 v68, v71
	v_mov_b32_e32 v87, v69
	v_pk_add_f32 v[82:83], v[68:69], v[86:87]
	v_pk_mul_f32 v[88:89], v[68:69], v[86:87]
	v_mov_b32_e32 v90, v70
	v_mov_b32_e32 v91, v84
	v_mul_f32_e32 v68, v70, v70
	v_mov_b32_e32 v85, v71
	v_pk_fma_f32 v[90:91], v[90:91], v[90:91], v[68:69] op_sel_hi:[1,1,0]
	v_mul_f32_e32 v68, v76, v76
	v_pk_fma_f32 v[92:93], v[76:77], v[76:77], v[68:69] op_sel_hi:[1,1,0]
	v_mov_b32_e32 v94, v64
	v_mov_b32_e32 v95, v66
	v_mul_f32_e32 v68, v64, v64
	v_pk_add_f32 v[98:99], v[70:71], v[84:85]
	v_pk_mul_f32 v[70:71], v[70:71], v[84:85]
	v_mov_b32_e32 v83, v89
	v_pk_mul_f32 v[88:89], v[74:75], v[74:75]
	v_pk_fma_f32 v[94:95], v[94:95], v[94:95], v[68:69] op_sel_hi:[1,1,0]
	v_mov_b32_e32 v96, v65
	v_mov_b32_e32 v97, v67
	v_mul_f32_e32 v68, v65, v65
	v_mov_b32_e32 v99, v71
	v_pk_mul_f32 v[70:71], v[86:87], v[86:87]
	v_pk_add_f32 v[64:65], v[64:65], v[66:67]
	v_and_b32_e32 v67, 64, v192
	v_pk_fma_f32 v[88:89], v[72:73], v[72:73], v[88:89]
	v_pk_add_f32 v[72:73], v[72:73], v[74:75]
	v_xor_b32_e32 v66, 16, v192
	v_add_u32_e32 v71, 64, v67
	v_pk_fma_f32 v[96:97], v[96:97], v[96:97], v[68:69] op_sel_hi:[1,1,0]
	v_pk_add_f32 v[72:73], v[72:73], v[72:73] op_sel:[0,1] op_sel_hi:[1,0]
	v_cmp_lt_i32_e32 vcc, v66, v71
	v_mul_f32_e32 v100, v78, v78
	v_pk_add_f32 v[88:89], v[88:89], v[88:89] op_sel_hi:[0,1]
	v_cndmask_b32_e32 v66, v192, v66, vcc
	v_mov_b32_e32 v94, v69
	v_mov_b32_e32 v79, v97
	v_mov_b32_e32 v73, v70
	v_pk_add_f32 v[64:65], v[64:65], v[64:65] op_sel:[0,1] op_sel_hi:[1,0]
	v_lshlrev_b32_e32 v74, 2, v66
	v_pk_add_f32 v[66:67], v[94:95], v[78:79]
	v_pk_add_f32 v[68:69], v[98:99], v[72:73]
	v_mov_b32_e32 v90, v76
	v_mov_b32_e32 v88, v77
	v_mov_b32_e32 v65, v100
	v_pk_add_f32 v[66:67], v[68:69], v[66:67]
	v_mov_b32_e32 v147, v93
	v_pk_add_f32 v[68:69], v[90:91], v[88:89]
	v_pk_add_f32 v[64:65], v[82:83], v[64:65]
	v_pk_add_f32 v[66:67], v[66:67], v[146:147]
	v_pk_add_f32 v[64:65], v[64:65], v[68:69]
	v_xor_b32_e32 v68, 32, v192
	v_pk_add_f32 v[64:65], v[64:65], v[66:67]
	ds_bpermute_b32 v66, v74, v64
	ds_bpermute_b32 v67, v74, v65
	v_cmp_lt_i32_e32 vcc, v68, v71
	s_waitcnt lgkmcnt(0)
	v_pk_add_f32 v[64:65], v[64:65], v[66:67]
	v_cndmask_b32_e32 v68, v192, v68, vcc
	v_lshlrev_b32_e32 v68, 2, v68
	v_mov_b32_e32 v66, v64
	s_nop 1
	v_permlane32_swap_b32_e32 v66, v64
	v_mov_b32_e32 v67, v65
	s_nop 1
	v_permlane32_swap_b32_e32 v67, v65
	s_and_saveexec_b64 s[0:1], s[10:11]
	s_cbranch_execz .LBB0_767
	s_waitcnt lgkmcnt(0)
	v_pk_add_f32 v[64:65], v[64:65], v[66:67]
	v_lshlrev_b64 v[66:67], 7, v[80:81]
	v_lshl_add_u64 v[66:67], s[16:17], 0, v[66:67]
	v_lshl_add_u64 v[66:67], s[38:39], 3, v[66:67]
	s_lshl_b32 s88, s44, 3
	v_lshl_add_u64 v[66:67], v[66:67], 0, s[88:89]
	global_store_dwordx2 v[66:67], v[64:65], off

; __device__ __forceinline__ u32x4 pack8(const f32x4& a, const f32x4& b) { u32x4 w; w.x = cvt_pk_bf16(a[0], a[1]); w.y = cvt_pk_bf16(a[2], a[3]); w.z = cvt_pk_bf16(b[0], b[1]); w.w = cvt_pk_bf16(b[2], b[3]); return w; }
; __device__ __forceinline__ f32x2 gelu_pk(f32x2 v) {
;     const f32x2 av = __builtin_elementwise_abs(v), d = av * 0.2316418882f + 1.0f;
;     f32x2 t; t.x = __builtin_amdgcn_rcpf(d.x); t.y = __builtin_amdgcn_rcpf(d.y);
;     f32x2 q = t * 0.5307027145f + (-0.7265760135f); q = q * t + 0.7107068705f; q = q * t + (-0.142248368f); q = q * t + 0.127414796f; q = q * t;
;     const f32x2 s = (v * v) * (-0.72134752044f);
;     f32x2 e; e.x = __builtin_amdgcn_exp2f(s.x); e.y = __builtin_amdgcn_exp2f(s.y);
;     const f32x2 m = v * (q * e), r = v - m;
;     f32x2 o; o.x = v.x < 0.f ? m.x : r.x; o.y = v.y < 0.f ? m.y : r.y; return o;
;     __device__ __forceinline__ void operator()(const f32x4 (&acc)[2][2][4][2], const Unit& u, int ui, int wr, int wc, int fr, int fq) const {
;     ...
;             for (int m = 0; m < 4; ++m) { const float r = rs[ai][m]; const int row = row0 + ai * HALF + m * 16; bf16_t* rowp = Z + (size_t)row * 2048 + col0; float s1 = 0.f, s2 = 0.f;
; #pragma unroll
;                 for (int bj = 0; bj < 2; ++bj) { const f32x4 v0 = acc[ai][bj][m][0] * r, v1 = acc[ai][bj][m][1] * r;
;                     const f32x2 a = gelu_pk((f32x2){v0[0], v0[1]}), b = gelu_pk((f32x2){v0[2], v0[3]}), c = gelu_pk((f32x2){v1[0], v1[1]}), d = gelu_pk((f32x2){v1[2], v1[3]});
;                     const f32x4 z0 = (f32x4){a.x, a.y, b.x, b.y}, z1 = (f32x4){c.x, c.y, d.x, d.y};
;                     *(u32x4*)(rowp + bj * HALF) = pack8(z0, z1);
.LBB0_768:
	v_pk_mul_f32 v[68:69], v[60:61], v[164:165] op_sel_hi:[1,0]
	s_mov_b32 s0, 0xbf3a00e3
	v_and_b32_e32 v61, 0x7fffffff, v69
	v_and_b32_e32 v60, 0x7fffffff, v68
	v_pk_fma_f32 v[60:61], v[60:61], s[56:57], 1.0 op_sel_hi:[1,0,0]
	v_pk_mul_f32 v[74:75], v[56:57], v[164:165] op_sel_hi:[1,0]
	v_rcp_f32_e32 v70, v60
	v_rcp_f32_e32 v71, v61
	v_mov_b64_e32 v[60:61], s[0:1]
	s_mov_b32 s0, 0x3f07dc22
	s_mov_b32 s88, 0x3e027906
	v_pk_fma_f32 v[56:57], v[70:71], s[0:1], v[60:61] op_sel_hi:[1,0,0]
	v_pk_mul_f32 v[62:63], v[62:63], v[164:165] op_sel_hi:[1,0]
	v_pk_fma_f32 v[56:57], v[70:71], v[56:57], s[2:3] op_sel_hi:[1,1,0]
	v_and_b32_e32 v73, 0x7fffffff, v63
	v_pk_fma_f32 v[56:57], v[70:71], v[56:57], s[4:5] op_sel_hi:[1,1,0]
	v_and_b32_e32 v72, 0x7fffffff, v62
	v_pk_fma_f32 v[56:57], v[70:71], v[56:57], s[88:89] op_sel_hi:[1,1,0]
	v_pk_fma_f32 v[72:73], v[72:73], s[56:57], 1.0 op_sel_hi:[1,0,0]
	v_pk_mul_f32 v[56:57], v[70:71], v[56:57]
	v_pk_mul_f32 v[70:71], v[68:69], v[68:69]
	v_rcp_f32_e32 v72, v72
	v_pk_mul_f32 v[70:71], v[70:71], s[86:87] op_sel_hi:[1,0]
	v_rcp_f32_e32 v73, v73
	v_exp_f32_e32 v70, v70
	v_exp_f32_e32 v71, v71
	v_pk_mul_f32 v[76:77], v[58:59], v[164:165] op_sel_hi:[1,0]
	v_pk_mul_f32 v[58:59], v[62:63], v[62:63]
	v_and_b32_e32 v81, 0x7fffffff, v75
	v_pk_mul_f32 v[56:57], v[70:71], v[56:57]
	v_pk_mul_f32 v[58:59], v[58:59], s[86:87] op_sel_hi:[1,0]
	v_pk_mul_f32 v[70:71], v[68:69], v[56:57]
	v_pk_fma_f32 v[78:79], v[68:69], v[56:57], v[68:69] neg_lo:[1,0,0] neg_hi:[1,0,0]
	v_pk_fma_f32 v[56:57], v[72:73], s[0:1], v[60:61] op_sel_hi:[1,0,0]
	v_exp_f32_e32 v58, v58
	v_pk_fma_f32 v[56:57], v[72:73], v[56:57], s[2:3] op_sel_hi:[1,1,0]
	v_exp_f32_e32 v59, v59
	v_pk_fma_f32 v[56:57], v[72:73], v[56:57], s[4:5] op_sel_hi:[1,1,0]
	v_and_b32_e32 v80, 0x7fffffff, v74
	v_pk_fma_f32 v[56:57], v[72:73], v[56:57], s[88:89] op_sel_hi:[1,1,0]
	v_cmp_gt_f32_e32 vcc, 0, v62
	v_pk_mul_f32 v[56:57], v[72:73], v[56:57]
	v_pk_fma_f32 v[80:81], v[80:81], s[56:57], 1.0 op_sel_hi:[1,0,0]
	v_pk_mul_f32 v[56:57], v[58:59], v[56:57]
	v_rcp_f32_e32 v80, v80
	v_pk_mul_f32 v[58:59], v[62:63], v[56:57]
	v_pk_fma_f32 v[72:73], v[62:63], v[56:57], v[62:63] neg_lo:[1,0,0] neg_hi:[1,0,0]
	v_rcp_f32_e32 v81, v81
	v_cndmask_b32_e32 v57, v72, v58, vcc
	v_cmp_gt_f32_e32 vcc, 0, v68
	v_and_b32_e32 v72, 0x7fffffff, v76
	v_pk_mul_f32 v[52:53], v[52:53], v[164:165] op_sel_hi:[1,0]
	v_cndmask_b32_e32 v56, v78, v70, vcc
	v_cmp_gt_f32_e32 vcc, 0, v63
	v_pk_fma_f32 v[62:63], v[80:81], s[0:1], v[60:61] op_sel_hi:[1,0,0]
	v_pk_mul_f32 v[86:87], v[48:49], v[164:165] op_sel_hi:[1,0]
	v_cndmask_b32_e32 v59, v73, v59, vcc
	v_cmp_gt_f32_e32 vcc, 0, v69
	v_and_b32_e32 v73, 0x7fffffff, v77
	v_pk_fma_f32 v[62:63], v[80:81], v[62:63], s[2:3] op_sel_hi:[1,1,0]
	v_cndmask_b32_e32 v58, v79, v71, vcc
	v_pk_mul_f32 v[70:71], v[74:75], v[74:75]
	v_pk_fma_f32 v[72:73], v[72:73], s[56:57], 1.0 op_sel_hi:[1,0,0]
	v_pk_mul_f32 v[70:71], v[70:71], s[86:87] op_sel_hi:[1,0]
	v_pk_fma_f32 v[62:63], v[80:81], v[62:63], s[4:5] op_sel_hi:[1,1,0]
	v_exp_f32_e32 v70, v70
	v_exp_f32_e32 v71, v71
	v_rcp_f32_e32 v72, v72
	v_rcp_f32_e32 v73, v73
	v_pk_fma_f32 v[62:63], v[80:81], v[62:63], s[88:89] op_sel_hi:[1,1,0]
	v_pk_mul_f32 v[68:69], v[76:77], v[76:77]
	v_pk_mul_f32 v[62:63], v[80:81], v[62:63]
	v_pk_mul_f32 v[68:69], v[68:69], s[86:87] op_sel_hi:[1,0]
	v_pk_mul_f32 v[62:63], v[70:71], v[62:63]
	v_exp_f32_e32 v68, v68
	v_pk_mul_f32 v[70:71], v[74:75], v[62:63]
	v_pk_fma_f32 v[78:79], v[74:75], v[62:63], v[74:75] neg_lo:[1,0,0] neg_hi:[1,0,0]
	v_pk_fma_f32 v[62:63], v[72:73], s[0:1], v[60:61] op_sel_hi:[1,0,0]
	v_exp_f32_e32 v69, v69
	v_pk_fma_f32 v[62:63], v[72:73], v[62:63], s[2:3] op_sel_hi:[1,1,0]
	v_pk_mul_f32 v[54:55], v[54:55], v[164:165] op_sel_hi:[1,0]
	v_pk_fma_f32 v[62:63], v[72:73], v[62:63], s[4:5] op_sel_hi:[1,1,0]
	v_and_b32_e32 v89, 0x7fffffff, v55
	v_pk_fma_f32 v[62:63], v[72:73], v[62:63], s[88:89] op_sel_hi:[1,1,0]
	v_and_b32_e32 v88, 0x7fffffff, v54
	v_pk_mul_f32 v[62:63], v[72:73], v[62:63]
	v_pk_fma_f32 v[88:89], v[88:89], s[56:57], 1.0 op_sel_hi:[1,0,0]
	v_pk_mul_f32 v[62:63], v[68:69], v[62:63]
	v_and_b32_e32 v69, 0x7fffffff, v53
	v_and_b32_e32 v68, 0x7fffffff, v52
	v_pk_fma_f32 v[68:69], v[68:69], s[56:57], 1.0 op_sel_hi:[1,0,0]
	v_rcp_f32_e32 v88, v88
	v_rcp_f32_e32 v68, v68
	v_rcp_f32_e32 v69, v69
	v_rcp_f32_e32 v89, v89
	v_pk_mul_f32 v[84:85], v[50:51], v[164:165] op_sel_hi:[1,0]
	v_pk_mul_f32 v[50:51], v[54:55], v[54:55]
	v_pk_fma_f32 v[48:49], v[68:69], s[0:1], v[60:61] op_sel_hi:[1,0,0]
	v_pk_mul_f32 v[50:51], v[50:51], s[86:87] op_sel_hi:[1,0]
	v_pk_fma_f32 v[48:49], v[68:69], v[48:49], s[2:3] op_sel_hi:[1,1,0]
	v_exp_f32_e32 v50, v50
	v_pk_fma_f32 v[48:49], v[68:69], v[48:49], s[4:5] op_sel_hi:[1,1,0]
	v_exp_f32_e32 v51, v51
	v_pk_fma_f32 v[48:49], v[68:69], v[48:49], s[88:89] op_sel_hi:[1,1,0]
	v_and_b32_e32 v93, 0x7fffffff, v87
	v_pk_mul_f32 v[48:49], v[68:69], v[48:49]
	v_pk_mul_f32 v[68:69], v[52:53], v[52:53]
	v_and_b32_e32 v92, 0x7fffffff, v86
	v_pk_mul_f32 v[68:69], v[68:69], s[86:87] op_sel_hi:[1,0]
	v_pk_fma_f32 v[92:93], v[92:93], s[56:57], 1.0 op_sel_hi:[1,0,0]
	v_exp_f32_e32 v68, v68
	v_exp_f32_e32 v69, v69
	v_pk_mul_f32 v[80:81], v[76:77], v[62:63]
	v_pk_fma_f32 v[82:83], v[76:77], v[62:63], v[76:77] neg_lo:[1,0,0] neg_hi:[1,0,0]
	v_cmp_gt_f32_e32 vcc, 0, v77
	v_pk_mul_f32 v[48:49], v[68:69], v[48:49]
	v_rcp_f32_e32 v92, v92
	v_pk_mul_f32 v[68:69], v[52:53], v[48:49]
	v_pk_fma_f32 v[90:91], v[52:53], v[48:49], v[52:53] neg_lo:[1,0,0] neg_hi:[1,0,0]
	v_pk_fma_f32 v[48:49], v[88:89], s[0:1], v[60:61] op_sel_hi:[1,0,0]
	v_rcp_f32_e32 v93, v93
	v_pk_fma_f32 v[48:49], v[88:89], v[48:49], s[2:3] op_sel_hi:[1,1,0]
	v_cndmask_b32_e32 v62, v83, v81, vcc
	v_pk_fma_f32 v[48:49], v[88:89], v[48:49], s[4:5] op_sel_hi:[1,1,0]
	v_cmp_gt_f32_e32 vcc, 0, v54
	v_pk_fma_f32 v[48:49], v[88:89], v[48:49], s[88:89] op_sel_hi:[1,1,0]
	v_add_u32_e32 v64, 0x80, v140
	v_pk_mul_f32 v[48:49], v[88:89], v[48:49]
	v_ashrrev_i32_e32 v65, 31, v64
	v_pk_mul_f32 v[48:49], v[50:51], v[48:49]
	s_waitcnt lgkmcnt(0)
; __device__ __forceinline__ u32x4 pack8(const f32x4& a, const f32x4& b) { u32x4 w; w.x = cvt_pk_bf16(a[0], a[1]); w.y = cvt_pk_bf16(a[2], a[3]); w.z = cvt_pk_bf16(b[0], b[1]); w.w = cvt_pk_bf16(b[2], b[3]); return w; }
;     __device__ __forceinline__ void operator()(const f32x4 (&acc)[2][2][4][2], const Unit& u, int ui, int wr, int wc, int fr, int fq) const {
;     ...
;             for (int m = 0; m < 4; ++m) { const float r = rs[ai][m]; const int row = row0 + ai * HALF + m * 16; bf16_t* rowp = Z + (size_t)row * 2048 + col0; float s1 = 0.f, s2 = 0.f;
; #pragma unroll
;                 for (int bj = 0; bj < 2; ++bj) { const f32x4 v0 = acc[ai][bj][m][0] * r, v1 = acc[ai][bj][m][1] * r;
;                     const f32x2 a = gelu_pk((f32x2){v0[0], v0[1]}), b = gelu_pk((f32x2){v0[2], v0[3]}), c = gelu_pk((f32x2){v1[0], v1[1]}), d = gelu_pk((f32x2){v1[2], v1[3]});
;                     const f32x4 z0 = (f32x4){a.x, a.y, b.x, b.y}, z1 = (f32x4){c.x, c.y, d.x, d.y};
;                     *(u32x4*)(rowp + bj * HALF) = pack8(z0, z1);
;                     s1 += (z0[0] + z0[1]) + (z0[2] + z0[3]) + (z1[0] + z1[1]) + (z1[2] + z1[3]);
;                     s2 += (z0[0] * z0[0] + z0[1] * z0[1]) + (z0[2] * z0[2] + z0[3] * z0[3]) + (z1[0] * z1[0] + z1[1] * z1[1]) + (z1[2] * z1[2] + z1[3] * z1[3]); }
;                 if (u.pn >= 4) { s1 += __shfl_xor(s1, 16); s1 += __shfl_xor(s1, 32); s2 += __shfl_xor(s2, 16); s2 += __shfl_xor(s2, 32);
;                     if (fq == 0) vst[(size_t)row * 16 + (u.pn - 4) * 4 + wc] = (f32x2){s1, s2}; } }
	v_lshlrev_b64 v[66:67], 12, v[64:65]
	v_pk_mul_f32 v[50:51], v[54:55], v[48:49]
	v_pk_fma_f32 v[88:89], v[54:55], v[48:49], v[54:55] neg_lo:[1,0,0] neg_hi:[1,0,0]
	v_lshl_add_u64 v[66:67], s[20:21], 0, v[66:67]
	v_cndmask_b32_e32 v49, v88, v50, vcc
	v_cmp_gt_f32_e32 vcc, 0, v52
	v_lshl_add_u64 v[66:67], v[162:163], 1, v[66:67]
	v_cvt_pk_bf16_f32 v72, v56, v58
	v_cvt_pk_bf16_f32 v73, v57, v59
	s_nop 0
	v_cndmask_b32_e32 v48, v90, v68, vcc
	v_cmp_gt_f32_e32 vcc, 0, v55
	v_pk_mul_f32 v[54:55], v[86:87], v[86:87]
	s_nop 0
	v_cndmask_b32_e32 v51, v89, v51, vcc
	v_cmp_gt_f32_e32 vcc, 0, v53
	v_pk_fma_f32 v[52:53], v[92:93], s[0:1], v[60:61] op_sel_hi:[1,0,0]
	v_pk_mul_f32 v[54:55], v[54:55], s[86:87] op_sel_hi:[1,0]
	v_pk_fma_f32 v[52:53], v[92:93], v[52:53], s[2:3] op_sel_hi:[1,1,0]
	v_exp_f32_e32 v54, v54
	v_exp_f32_e32 v55, v55
	v_pk_fma_f32 v[52:53], v[92:93], v[52:53], s[4:5] op_sel_hi:[1,1,0]
	v_cndmask_b32_e32 v50, v91, v69, vcc
	v_pk_fma_f32 v[52:53], v[92:93], v[52:53], s[88:89] op_sel_hi:[1,1,0]
	v_cmp_gt_f32_e32 vcc, 0, v74
	v_pk_mul_f32 v[52:53], v[92:93], v[52:53]
	v_pk_mul_f32 v[88:89], v[84:85], v[84:85]
	v_pk_mul_f32 v[52:53], v[54:55], v[52:53]
	v_cndmask_b32_e32 v54, v78, v70, vcc
	v_pk_mul_f32 v[68:69], v[86:87], v[52:53]
	v_pk_fma_f32 v[90:91], v[86:87], v[52:53], v[86:87] neg_lo:[1,0,0] neg_hi:[1,0,0]
	v_cmp_gt_f32_e32 vcc, 0, v86
	v_and_b32_e32 v70, 0x7fffffff, v84
	s_nop 0
	v_cndmask_b32_e32 v55, v90, v68, vcc
	v_cmp_gt_f32_e32 vcc, 0, v75
	s_nop 1
	v_cndmask_b32_e32 v68, v79, v71, vcc
	v_and_b32_e32 v71, 0x7fffffff, v85
	v_pk_fma_f32 v[70:71], v[70:71], s[56:57], 1.0 op_sel_hi:[1,0,0]
	v_cmp_gt_f32_e32 vcc, 0, v76
	v_rcp_f32_e32 v76, v70
	v_rcp_f32_e32 v77, v71
	v_cvt_pk_bf16_f32 v74, v54, v68
	v_cndmask_b32_e32 v53, v82, v80, vcc
	v_cvt_pk_bf16_f32 v75, v53, v62
	global_store_dwordx4 v[66:67], v[72:75], off
	v_pk_fma_f32 v[60:61], v[76:77], s[0:1], v[60:61] op_sel_hi:[1,0,0]
	v_cmp_gt_f32_e32 vcc, 0, v87
	v_pk_mul_f32 v[72:73], v[88:89], s[86:87] op_sel_hi:[1,0]
	v_pk_fma_f32 v[60:61], v[76:77], v[60:61], s[2:3] op_sel_hi:[1,1,0]
	v_exp_f32_e32 v72, v72
	v_exp_f32_e32 v73, v73
	v_pk_fma_f32 v[60:61], v[76:77], v[60:61], s[4:5] op_sel_hi:[1,1,0]
	v_cndmask_b32_e32 v70, v91, v69, vcc
	v_pk_fma_f32 v[60:61], v[76:77], v[60:61], s[88:89] op_sel_hi:[1,1,0]
	v_cmp_gt_f32_e32 vcc, 0, v85
	v_pk_mul_f32 v[60:61], v[76:77], v[60:61]
	s_nop 0
	v_pk_mul_f32 v[60:61], v[72:73], v[60:61]
	s_nop 0
	v_pk_mul_f32 v[72:73], v[84:85], v[60:61]
	v_pk_fma_f32 v[60:61], v[84:85], v[60:61], v[84:85] neg_lo:[1,0,0] neg_hi:[1,0,0]
	s_nop 0
	v_cndmask_b32_e32 v61, v61, v73, vcc
	v_cmp_gt_f32_e32 vcc, 0, v84
	s_nop 1
	v_cndmask_b32_e32 v60, v60, v72, vcc
	s_and_b64 vcc, exec, s[12:13]
	v_cvt_pk_bf16_f32 v72, v48, v50
	v_cvt_pk_bf16_f32 v73, v49, v51
	v_cvt_pk_bf16_f32 v74, v55, v70
	v_cvt_pk_bf16_f32 v75, v60, v61
	global_store_dwordx4 v[66:67], v[72:75], off offset:256
	s_cbranch_vccnz .LBB0_772
	v_mov_b32_e32 v52, v55
	v_mov_b32_e32 v71, v53
	v_pk_add_f32 v[66:67], v[52:53], v[70:71]
	v_pk_mul_f32 v[72:73], v[52:53], v[70:71]
	v_mov_b32_e32 v74, v54
	v_mov_b32_e32 v75, v68
	v_mul_f32_e32 v52, v54, v54
	v_mov_b32_e32 v69, v55
	v_pk_fma_f32 v[74:75], v[74:75], v[74:75], v[52:53] op_sel_hi:[1,1,0]
	v_mul_f32_e32 v52, v60, v60
	v_pk_fma_f32 v[76:77], v[60:61], v[60:61], v[52:53] op_sel_hi:[1,1,0]
	v_mov_b32_e32 v78, v48
	v_mov_b32_e32 v79, v50
	v_mul_f32_e32 v52, v48, v48
	v_pk_add_f32 v[82:83], v[54:55], v[68:69]
	v_pk_mul_f32 v[54:55], v[54:55], v[68:69]
	v_mov_b32_e32 v67, v73
	v_pk_mul_f32 v[72:73], v[58:59], v[58:59]
	v_pk_fma_f32 v[78:79], v[78:79], v[78:79], v[52:53] op_sel_hi:[1,1,0]
	v_mov_b32_e32 v80, v49
	v_mov_b32_e32 v81, v51
	v_mul_f32_e32 v52, v49, v49
	v_mov_b32_e32 v83, v55
	v_pk_mul_f32 v[54:55], v[70:71], v[70:71]
	v_pk_add_f32 v[48:49], v[48:49], v[50:51]
	v_and_b32_e32 v51, 64, v192
	v_pk_fma_f32 v[72:73], v[56:57], v[56:57], v[72:73]
	v_pk_add_f32 v[56:57], v[56:57], v[58:59]
	v_xor_b32_e32 v50, 16, v192
	v_add_u32_e32 v55, 64, v51
	v_pk_fma_f32 v[80:81], v[80:81], v[80:81], v[52:53] op_sel_hi:[1,1,0]
	v_pk_add_f32 v[56:57], v[56:57], v[56:57] op_sel:[0,1] op_sel_hi:[1,0]
	v_cmp_lt_i32_e32 vcc, v50, v55
	v_mul_f32_e32 v84, v62, v62
	v_pk_add_f32 v[72:73], v[72:73], v[72:73] op_sel_hi:[0,1]
	v_cndmask_b32_e32 v50, v192, v50, vcc
	v_mov_b32_e32 v78, v53
	v_mov_b32_e32 v63, v81
	v_mov_b32_e32 v57, v54
	v_pk_add_f32 v[48:49], v[48:49], v[48:49] op_sel:[0,1] op_sel_hi:[1,0]
	v_lshlrev_b32_e32 v58, 2, v50
	v_pk_add_f32 v[50:51], v[78:79], v[62:63]
	v_pk_add_f32 v[52:53], v[82:83], v[56:57]
	v_mov_b32_e32 v74, v60
	v_mov_b32_e32 v72, v61
	v_mov_b32_e32 v49, v84
	v_pk_add_f32 v[50:51], v[52:53], v[50:51]
	v_mov_b32_e32 v147, v77
	v_pk_add_f32 v[52:53], v[74:75], v[72:73]
	v_pk_add_f32 v[48:49], v[66:67], v[48:49]
	v_pk_add_f32 v[50:51], v[50:51], v[146:147]
	v_pk_add_f32 v[48:49], v[48:49], v[52:53]
	v_xor_b32_e32 v52, 32, v192
	v_pk_add_f32 v[48:49], v[48:49], v[50:51]
	ds_bpermute_b32 v50, v58, v48
	ds_bpermute_b32 v51, v58, v49
	v_cmp_lt_i32_e32 vcc, v52, v55
	s_waitcnt lgkmcnt(0)
	v_pk_add_f32 v[48:49], v[48:49], v[50:51]
	v_cndmask_b32_e32 v52, v192, v52, vcc
	v_lshlrev_b32_e32 v52, 2, v52
	v_mov_b32_e32 v50, v48
	s_nop 1
	v_permlane32_swap_b32_e32 v50, v48
	v_mov_b32_e32 v51, v49
	s_nop 1
	v_permlane32_swap_b32_e32 v51, v49
	s_and_saveexec_b64 s[0:1], s[10:11]
	s_cbranch_execz .LBB0_771
	s_waitcnt lgkmcnt(0)
	v_pk_add_f32 v[48:49], v[48:49], v[50:51]
	v_lshlrev_b64 v[50:51], 7, v[64:65]
	v_lshl_add_u64 v[50:51], s[16:17], 0, v[50:51]
	v_lshl_add_u64 v[50:51], s[38:39], 3, v[50:51]
	s_lshl_b32 s88, s44, 3
	v_lshl_add_u64 v[50:51], v[50:51], 0, s[88:89]
	global_store_dwordx2 v[50:51], v[48:49], off

; __device__ __forceinline__ u32x4 pack8(const f32x4& a, const f32x4& b) { u32x4 w; w.x = cvt_pk_bf16(a[0], a[1]); w.y = cvt_pk_bf16(a[2], a[3]); w.z = cvt_pk_bf16(b[0], b[1]); w.w = cvt_pk_bf16(b[2], b[3]); return w; }
; __device__ __forceinline__ f32x2 gelu_pk(f32x2 v) {
;     const f32x2 av = __builtin_elementwise_abs(v), d = av * 0.2316418882f + 1.0f;
;     f32x2 t; t.x = __builtin_amdgcn_rcpf(d.x); t.y = __builtin_amdgcn_rcpf(d.y);
;     f32x2 q = t * 0.5307027145f + (-0.7265760135f); q = q * t + 0.7107068705f; q = q * t + (-0.142248368f); q = q * t + 0.127414796f; q = q * t;
;     const f32x2 s = (v * v) * (-0.72134752044f);
;     f32x2 e; e.x = __builtin_amdgcn_exp2f(s.x); e.y = __builtin_amdgcn_exp2f(s.y);
;     const f32x2 m = v * (q * e), r = v - m;
;     f32x2 o; o.x = v.x < 0.f ? m.x : r.x; o.y = v.y < 0.f ? m.y : r.y; return o;
;     __device__ __forceinline__ void operator()(const f32x4 (&acc)[2][2][4][2], const Unit& u, int ui, int wr, int wc, int fr, int fq) const {
;     ...
;             for (int m = 0; m < 4; ++m) { const float r = rs[ai][m]; const int row = row0 + ai * HALF + m * 16; bf16_t* rowp = Z + (size_t)row * 2048 + col0; float s1 = 0.f, s2 = 0.f;
; #pragma unroll
;                 for (int bj = 0; bj < 2; ++bj) { const f32x4 v0 = acc[ai][bj][m][0] * r, v1 = acc[ai][bj][m][1] * r;
;                     const f32x2 a = gelu_pk((f32x2){v0[0], v0[1]}), b = gelu_pk((f32x2){v0[2], v0[3]}), c = gelu_pk((f32x2){v1[0], v1[1]}), d = gelu_pk((f32x2){v1[2], v1[3]});
;                     const f32x4 z0 = (f32x4){a.x, a.y, b.x, b.y}, z1 = (f32x4){c.x, c.y, d.x, d.y};
;                     *(u32x4*)(rowp + bj * HALF) = pack8(z0, z1);
.LBB0_772:
	v_mov_b32_e32 v52, v165
	v_pk_mul_f32 v[54:55], v[44:45], v[52:53] op_sel_hi:[1,0]
	s_mov_b32 s0, 0xbf3a00e3
	v_and_b32_e32 v45, 0x7fffffff, v55
	v_and_b32_e32 v44, 0x7fffffff, v54
	v_pk_fma_f32 v[44:45], v[44:45], s[56:57], 1.0 op_sel_hi:[1,0,0]
	v_pk_mul_f32 v[58:59], v[40:41], v[52:53] op_sel_hi:[1,0]
	v_rcp_f32_e32 v56, v44
	v_rcp_f32_e32 v57, v45
	v_mov_b64_e32 v[44:45], s[0:1]
	s_mov_b32 s0, 0x3f07dc22
	s_mov_b32 s88, 0x3e027906
	v_pk_fma_f32 v[40:41], v[56:57], s[0:1], v[44:45] op_sel_hi:[1,0,0]
	v_pk_mul_f32 v[46:47], v[46:47], v[52:53] op_sel_hi:[1,0]
	v_pk_fma_f32 v[40:41], v[56:57], v[40:41], s[2:3] op_sel_hi:[1,1,0]
	v_and_b32_e32 v63, 0x7fffffff, v47
	v_pk_fma_f32 v[40:41], v[56:57], v[40:41], s[4:5] op_sel_hi:[1,1,0]
	v_and_b32_e32 v62, 0x7fffffff, v46
	v_pk_fma_f32 v[40:41], v[56:57], v[40:41], s[88:89] op_sel_hi:[1,1,0]
	v_pk_fma_f32 v[62:63], v[62:63], s[56:57], 1.0 op_sel_hi:[1,0,0]
	v_pk_mul_f32 v[40:41], v[56:57], v[40:41]
	v_pk_mul_f32 v[56:57], v[54:55], v[54:55]
	v_rcp_f32_e32 v62, v62
	v_pk_mul_f32 v[56:57], v[56:57], s[86:87] op_sel_hi:[1,0]
	v_rcp_f32_e32 v63, v63
	v_exp_f32_e32 v56, v56
	v_exp_f32_e32 v57, v57
	v_pk_mul_f32 v[60:61], v[42:43], v[52:53] op_sel_hi:[1,0]
	v_pk_mul_f32 v[42:43], v[46:47], v[46:47]
	v_pk_mul_f32 v[36:37], v[36:37], v[52:53] op_sel_hi:[1,0]
	v_pk_mul_f32 v[40:41], v[56:57], v[40:41]
	v_pk_mul_f32 v[42:43], v[42:43], s[86:87] op_sel_hi:[1,0]
	v_pk_mul_f32 v[56:57], v[54:55], v[40:41]
	v_pk_fma_f32 v[64:65], v[54:55], v[40:41], v[54:55] neg_lo:[1,0,0] neg_hi:[1,0,0]
	v_pk_fma_f32 v[40:41], v[62:63], s[0:1], v[44:45] op_sel_hi:[1,0,0]
	v_exp_f32_e32 v42, v42
	v_pk_fma_f32 v[40:41], v[62:63], v[40:41], s[2:3] op_sel_hi:[1,1,0]
	v_exp_f32_e32 v43, v43
	v_and_b32_e32 v69, 0x7fffffff, v37
	v_and_b32_e32 v68, 0x7fffffff, v36
	v_pk_fma_f32 v[40:41], v[62:63], v[40:41], s[4:5] op_sel_hi:[1,1,0]
	v_pk_fma_f32 v[68:69], v[68:69], s[56:57], 1.0 op_sel_hi:[1,0,0]
	v_pk_fma_f32 v[40:41], v[62:63], v[40:41], s[88:89] op_sel_hi:[1,1,0]
	v_rcp_f32_e32 v68, v68
	v_rcp_f32_e32 v69, v69
	v_pk_mul_f32 v[40:41], v[62:63], v[40:41]
	v_and_b32_e32 v67, 0x7fffffff, v59
	v_pk_mul_f32 v[40:41], v[42:43], v[40:41]
	v_and_b32_e32 v66, 0x7fffffff, v58
	v_pk_mul_f32 v[42:43], v[46:47], v[40:41]
	v_pk_fma_f32 v[62:63], v[46:47], v[40:41], v[46:47] neg_lo:[1,0,0] neg_hi:[1,0,0]
	v_cmp_gt_f32_e32 vcc, 0, v46
	v_pk_fma_f32 v[66:67], v[66:67], s[56:57], 1.0 op_sel_hi:[1,0,0]
	v_pk_mul_f32 v[38:39], v[38:39], v[52:53] op_sel_hi:[1,0]
	v_cndmask_b32_e32 v41, v62, v42, vcc
	v_cmp_gt_f32_e32 vcc, 0, v54
	v_rcp_f32_e32 v66, v66
	v_rcp_f32_e32 v67, v67
	v_pk_mul_f32 v[70:71], v[34:35], v[52:53] op_sel_hi:[1,0]
	v_pk_mul_f32 v[52:53], v[32:33], v[52:53] op_sel_hi:[1,0]
	v_pk_fma_f32 v[32:33], v[68:69], s[0:1], v[44:45] op_sel_hi:[1,0,0]
	v_cndmask_b32_e32 v40, v64, v56, vcc
	v_cmp_gt_f32_e32 vcc, 0, v47
	v_pk_fma_f32 v[32:33], v[68:69], v[32:33], s[2:3] op_sel_hi:[1,1,0]
	v_pk_fma_f32 v[46:47], v[66:67], s[0:1], v[44:45] op_sel_hi:[1,0,0]
	v_cndmask_b32_e32 v43, v63, v43, vcc
	v_cmp_gt_f32_e32 vcc, 0, v55
	v_pk_fma_f32 v[32:33], v[68:69], v[32:33], s[4:5] op_sel_hi:[1,1,0]
	v_and_b32_e32 v63, 0x7fffffff, v61
	v_cndmask_b32_e32 v42, v65, v57, vcc
	v_pk_mul_f32 v[56:57], v[58:59], v[58:59]
	v_pk_fma_f32 v[32:33], v[68:69], v[32:33], s[88:89] op_sel_hi:[1,1,0]
	v_pk_mul_f32 v[56:57], v[56:57], s[86:87] op_sel_hi:[1,0]
	v_and_b32_e32 v62, 0x7fffffff, v60
	v_pk_mul_f32 v[32:33], v[68:69], v[32:33]
	v_pk_mul_f32 v[68:69], v[36:37], v[36:37]
	v_pk_fma_f32 v[46:47], v[66:67], v[46:47], s[2:3] op_sel_hi:[1,1,0]
	v_exp_f32_e32 v56, v56
	v_exp_f32_e32 v57, v57
	v_pk_fma_f32 v[62:63], v[62:63], s[56:57], 1.0 op_sel_hi:[1,0,0]
	v_pk_mul_f32 v[68:69], v[68:69], s[86:87] op_sel_hi:[1,0]
	v_and_b32_e32 v73, 0x7fffffff, v39
	v_and_b32_e32 v72, 0x7fffffff, v38
	v_pk_fma_f32 v[46:47], v[66:67], v[46:47], s[4:5] op_sel_hi:[1,1,0]
	v_rcp_f32_e32 v62, v62
	v_rcp_f32_e32 v63, v63
	v_exp_f32_e32 v68, v68
	v_exp_f32_e32 v69, v69
	v_pk_fma_f32 v[72:73], v[72:73], s[56:57], 1.0 op_sel_hi:[1,0,0]
	v_pk_fma_f32 v[46:47], v[66:67], v[46:47], s[88:89] op_sel_hi:[1,1,0]
	v_rcp_f32_e32 v72, v72
	v_rcp_f32_e32 v73, v73
	v_pk_mul_f32 v[46:47], v[66:67], v[46:47]
	v_pk_mul_f32 v[54:55], v[60:61], v[60:61]
	v_pk_mul_f32 v[46:47], v[56:57], v[46:47]
	v_pk_mul_f32 v[54:55], v[54:55], s[86:87] op_sel_hi:[1,0]
	v_pk_mul_f32 v[64:65], v[58:59], v[46:47]
	v_pk_fma_f32 v[66:67], v[58:59], v[46:47], v[58:59] neg_lo:[1,0,0] neg_hi:[1,0,0]
	v_pk_fma_f32 v[46:47], v[62:63], s[0:1], v[44:45] op_sel_hi:[1,0,0]
	v_pk_mul_f32 v[34:35], v[38:39], v[38:39]
	v_pk_mul_f32 v[32:33], v[68:69], v[32:33]
	v_pk_fma_f32 v[46:47], v[62:63], v[46:47], s[2:3] op_sel_hi:[1,1,0]
	v_exp_f32_e32 v54, v54
	v_exp_f32_e32 v55, v55
	v_pk_mul_f32 v[68:69], v[36:37], v[32:33]
	v_pk_fma_f32 v[74:75], v[36:37], v[32:33], v[36:37] neg_lo:[1,0,0] neg_hi:[1,0,0]
	v_pk_fma_f32 v[32:33], v[72:73], s[0:1], v[44:45] op_sel_hi:[1,0,0]
	v_pk_mul_f32 v[34:35], v[34:35], s[86:87] op_sel_hi:[1,0]
	v_pk_fma_f32 v[46:47], v[62:63], v[46:47], s[4:5] op_sel_hi:[1,1,0]
	v_pk_fma_f32 v[32:33], v[72:73], v[32:33], s[2:3] op_sel_hi:[1,1,0]
	v_exp_f32_e32 v34, v34
	v_exp_f32_e32 v35, v35
	v_pk_fma_f32 v[46:47], v[62:63], v[46:47], s[88:89] op_sel_hi:[1,1,0]
	v_pk_fma_f32 v[32:33], v[72:73], v[32:33], s[4:5] op_sel_hi:[1,1,0]
	v_pk_mul_f32 v[46:47], v[62:63], v[46:47]
	v_pk_fma_f32 v[32:33], v[72:73], v[32:33], s[88:89] op_sel_hi:[1,1,0]
	v_and_b32_e32 v77, 0x7fffffff, v53
	v_and_b32_e32 v76, 0x7fffffff, v52
	v_pk_mul_f32 v[46:47], v[54:55], v[46:47]
	v_pk_mul_f32 v[32:33], v[72:73], v[32:33]
	v_pk_fma_f32 v[76:77], v[76:77], s[56:57], 1.0 op_sel_hi:[1,0,0]
	v_pk_mul_f32 v[54:55], v[60:61], v[46:47]
	v_pk_fma_f32 v[62:63], v[60:61], v[46:47], v[60:61] neg_lo:[1,0,0] neg_hi:[1,0,0]
	v_cmp_gt_f32_e32 vcc, 0, v61
	v_pk_mul_f32 v[32:33], v[34:35], v[32:33]
	v_rcp_f32_e32 v76, v76
	v_rcp_f32_e32 v77, v77
	v_cndmask_b32_e32 v46, v63, v55, vcc
	v_pk_mul_f32 v[34:35], v[38:39], v[32:33]
	v_pk_fma_f32 v[72:73], v[38:39], v[32:33], v[38:39] neg_lo:[1,0,0] neg_hi:[1,0,0]
	v_cmp_gt_f32_e32 vcc, 0, v38
	v_and_b32_e32 v55, 0x7fffffff, v71
	v_add_u32_e32 v48, 0x90, v140
	v_cndmask_b32_e32 v33, v72, v34, vcc
	v_cmp_gt_f32_e32 vcc, 0, v36
	v_ashrrev_i32_e32 v49, 31, v48
	s_waitcnt lgkmcnt(0)
; __device__ __forceinline__ u32x4 pack8(const f32x4& a, const f32x4& b) { u32x4 w; w.x = cvt_pk_bf16(a[0], a[1]); w.y = cvt_pk_bf16(a[2], a[3]); w.z = cvt_pk_bf16(b[0], b[1]); w.w = cvt_pk_bf16(b[2], b[3]); return w; }
;     __device__ __forceinline__ void operator()(const f32x4 (&acc)[2][2][4][2], const Unit& u, int ui, int wr, int wc, int fr, int fq) const {
;     ...
;             for (int m = 0; m < 4; ++m) { const float r = rs[ai][m]; const int row = row0 + ai * HALF + m * 16; bf16_t* rowp = Z + (size_t)row * 2048 + col0; float s1 = 0.f, s2 = 0.f;
; #pragma unroll
;                 for (int bj = 0; bj < 2; ++bj) { const f32x4 v0 = acc[ai][bj][m][0] * r, v1 = acc[ai][bj][m][1] * r;
;                     const f32x2 a = gelu_pk((f32x2){v0[0], v0[1]}), b = gelu_pk((f32x2){v0[2], v0[3]}), c = gelu_pk((f32x2){v1[0], v1[1]}), d = gelu_pk((f32x2){v1[2], v1[3]});
;                     const f32x4 z0 = (f32x4){a.x, a.y, b.x, b.y}, z1 = (f32x4){c.x, c.y, d.x, d.y};
;                     *(u32x4*)(rowp + bj * HALF) = pack8(z0, z1);
;                     s1 += (z0[0] + z0[1]) + (z0[2] + z0[3]) + (z1[0] + z1[1]) + (z1[2] + z1[3]);
;                     s2 += (z0[0] * z0[0] + z0[1] * z0[1]) + (z0[2] * z0[2] + z0[3] * z0[3]) + (z1[0] * z1[0] + z1[1] * z1[1]) + (z1[2] * z1[2] + z1[3] * z1[3]); }
;                 if (u.pn >= 4) { s1 += __shfl_xor(s1, 16); s1 += __shfl_xor(s1, 32); s2 += __shfl_xor(s2, 16); s2 += __shfl_xor(s2, 32);
;                     if (fq == 0) vst[(size_t)row * 16 + (u.pn - 4) * 4 + wc] = (f32x2){s1, s2}; } }
	v_lshlrev_b64 v[50:51], 12, v[48:49]
	v_cndmask_b32_e32 v32, v74, v68, vcc
	v_cmp_gt_f32_e32 vcc, 0, v39
	v_pk_mul_f32 v[38:39], v[52:53], v[52:53]
	v_lshl_add_u64 v[50:51], s[20:21], 0, v[50:51]
	v_cndmask_b32_e32 v35, v73, v35, vcc
	v_cmp_gt_f32_e32 vcc, 0, v37
	v_pk_fma_f32 v[36:37], v[76:77], s[0:1], v[44:45] op_sel_hi:[1,0,0]
	v_pk_mul_f32 v[38:39], v[38:39], s[86:87] op_sel_hi:[1,0]
	v_pk_fma_f32 v[36:37], v[76:77], v[36:37], s[2:3] op_sel_hi:[1,1,0]
	v_exp_f32_e32 v38, v38
	v_exp_f32_e32 v39, v39
	v_pk_fma_f32 v[36:37], v[76:77], v[36:37], s[4:5] op_sel_hi:[1,1,0]
	v_cndmask_b32_e32 v34, v75, v69, vcc
	v_pk_fma_f32 v[36:37], v[76:77], v[36:37], s[88:89] op_sel_hi:[1,1,0]
	v_cmp_gt_f32_e32 vcc, 0, v58
	v_pk_mul_f32 v[36:37], v[76:77], v[36:37]
	v_lshl_add_u64 v[50:51], v[162:163], 1, v[50:51]
	v_pk_mul_f32 v[36:37], v[38:39], v[36:37]
	v_cndmask_b32_e32 v38, v66, v64, vcc
	v_pk_mul_f32 v[72:73], v[52:53], v[36:37]
	v_pk_fma_f32 v[74:75], v[52:53], v[36:37], v[52:53] neg_lo:[1,0,0] neg_hi:[1,0,0]
	v_cmp_gt_f32_e32 vcc, 0, v52
	v_cvt_pk_bf16_f32 v56, v40, v42
	v_cvt_pk_bf16_f32 v57, v41, v43
	v_pk_mul_f32 v[68:69], v[70:71], v[70:71]
	s_nop 0
	v_cndmask_b32_e32 v39, v74, v72, vcc
	v_cmp_gt_f32_e32 vcc, 0, v59
	s_nop 1
	v_cndmask_b32_e32 v52, v67, v65, vcc
	v_cmp_gt_f32_e32 vcc, 0, v60
	v_cvt_pk_bf16_f32 v58, v38, v52
	s_nop 1
	v_cndmask_b32_e32 v37, v62, v54, vcc
	v_and_b32_e32 v54, 0x7fffffff, v70
	v_pk_fma_f32 v[54:55], v[54:55], s[56:57], 1.0 op_sel_hi:[1,0,0]
	v_cvt_pk_bf16_f32 v59, v37, v46
	global_store_dwordx4 v[50:51], v[56:59], off
	v_rcp_f32_e32 v60, v54
	v_rcp_f32_e32 v61, v55
	v_pk_mul_f32 v[56:57], v[68:69], s[86:87] op_sel_hi:[1,0]
	v_cmp_gt_f32_e32 vcc, 0, v53
	v_exp_f32_e32 v56, v56
	v_pk_fma_f32 v[44:45], v[60:61], s[0:1], v[44:45] op_sel_hi:[1,0,0]
	v_exp_f32_e32 v57, v57
	v_pk_fma_f32 v[44:45], v[60:61], v[44:45], s[2:3] op_sel_hi:[1,1,0]
	v_cndmask_b32_e32 v54, v75, v73, vcc
	v_pk_fma_f32 v[44:45], v[60:61], v[44:45], s[4:5] op_sel_hi:[1,1,0]
	v_cmp_gt_f32_e32 vcc, 0, v71
	v_pk_fma_f32 v[44:45], v[60:61], v[44:45], s[88:89] op_sel_hi:[1,1,0]
	s_nop 0
	v_pk_mul_f32 v[44:45], v[60:61], v[44:45]
	s_nop 0
	v_pk_mul_f32 v[44:45], v[56:57], v[44:45]
	s_nop 0
	v_pk_mul_f32 v[56:57], v[70:71], v[44:45]
	v_pk_fma_f32 v[44:45], v[70:71], v[44:45], v[70:71] neg_lo:[1,0,0] neg_hi:[1,0,0]
	s_nop 0
	v_cndmask_b32_e32 v45, v45, v57, vcc
	v_cmp_gt_f32_e32 vcc, 0, v70
	s_nop 1
	v_cndmask_b32_e32 v44, v44, v56, vcc
	s_and_b64 vcc, exec, s[12:13]
	v_cvt_pk_bf16_f32 v56, v32, v34
	v_cvt_pk_bf16_f32 v57, v33, v35
	v_cvt_pk_bf16_f32 v58, v39, v54
	v_cvt_pk_bf16_f32 v59, v44, v45
	global_store_dwordx4 v[50:51], v[56:59], off offset:256
	s_cbranch_vccnz .LBB0_776
	v_mov_b32_e32 v36, v39
	v_mov_b32_e32 v55, v37
	v_pk_add_f32 v[50:51], v[36:37], v[54:55]
	v_pk_mul_f32 v[56:57], v[36:37], v[54:55]
	v_mov_b32_e32 v58, v38
	v_mov_b32_e32 v59, v52
	v_mul_f32_e32 v36, v38, v38
	v_mov_b32_e32 v53, v39
	v_pk_fma_f32 v[58:59], v[58:59], v[58:59], v[36:37] op_sel_hi:[1,1,0]
	v_mul_f32_e32 v36, v44, v44
	v_pk_fma_f32 v[60:61], v[44:45], v[44:45], v[36:37] op_sel_hi:[1,1,0]
	v_mov_b32_e32 v62, v32
	v_mov_b32_e32 v63, v34
	v_mul_f32_e32 v36, v32, v32
	v_pk_add_f32 v[66:67], v[38:39], v[52:53]
	v_pk_mul_f32 v[38:39], v[38:39], v[52:53]
	v_mov_b32_e32 v51, v57
	v_pk_mul_f32 v[56:57], v[42:43], v[42:43]
	v_pk_fma_f32 v[62:63], v[62:63], v[62:63], v[36:37] op_sel_hi:[1,1,0]
	v_mov_b32_e32 v64, v33
	v_mov_b32_e32 v65, v35
	v_mul_f32_e32 v36, v33, v33
	v_mov_b32_e32 v67, v39
	v_pk_mul_f32 v[38:39], v[54:55], v[54:55]
	v_pk_add_f32 v[32:33], v[32:33], v[34:35]
	v_and_b32_e32 v35, 64, v192
	v_pk_fma_f32 v[56:57], v[40:41], v[40:41], v[56:57]
	v_pk_add_f32 v[40:41], v[40:41], v[42:43]
	v_xor_b32_e32 v34, 16, v192
	v_add_u32_e32 v39, 64, v35
	v_pk_fma_f32 v[64:65], v[64:65], v[64:65], v[36:37] op_sel_hi:[1,1,0]
	v_pk_add_f32 v[40:41], v[40:41], v[40:41] op_sel:[0,1] op_sel_hi:[1,0]
	v_cmp_lt_i32_e32 vcc, v34, v39
	v_mul_f32_e32 v68, v46, v46
	v_pk_add_f32 v[56:57], v[56:57], v[56:57] op_sel_hi:[0,1]
	v_cndmask_b32_e32 v34, v192, v34, vcc
	v_mov_b32_e32 v62, v37
	v_mov_b32_e32 v47, v65
	v_mov_b32_e32 v41, v38
	v_pk_add_f32 v[32:33], v[32:33], v[32:33] op_sel:[0,1] op_sel_hi:[1,0]
	v_lshlrev_b32_e32 v42, 2, v34
	v_pk_add_f32 v[34:35], v[62:63], v[46:47]
	v_pk_add_f32 v[36:37], v[66:67], v[40:41]
	v_mov_b32_e32 v58, v44
	v_mov_b32_e32 v56, v45
	v_mov_b32_e32 v33, v68
	v_pk_add_f32 v[34:35], v[36:37], v[34:35]
	v_mov_b32_e32 v147, v61
	v_pk_add_f32 v[36:37], v[58:59], v[56:57]
	v_pk_add_f32 v[32:33], v[50:51], v[32:33]
	v_pk_add_f32 v[34:35], v[34:35], v[146:147]
	v_pk_add_f32 v[32:33], v[32:33], v[36:37]
	v_xor_b32_e32 v36, 32, v192
	v_pk_add_f32 v[32:33], v[32:33], v[34:35]
	ds_bpermute_b32 v34, v42, v32
	ds_bpermute_b32 v35, v42, v33
	v_cmp_lt_i32_e32 vcc, v36, v39
	s_waitcnt lgkmcnt(0)
	v_pk_add_f32 v[32:33], v[32:33], v[34:35]
	v_cndmask_b32_e32 v36, v192, v36, vcc
	v_lshlrev_b32_e32 v36, 2, v36
	v_mov_b32_e32 v34, v32
	s_nop 1
	v_permlane32_swap_b32_e32 v34, v32
	v_mov_b32_e32 v35, v33
	s_nop 1
	v_permlane32_swap_b32_e32 v35, v33
	s_and_saveexec_b64 s[0:1], s[10:11]
	s_cbranch_execz .LBB0_775
	s_waitcnt lgkmcnt(0)
	v_pk_add_f32 v[32:33], v[32:33], v[34:35]
	v_lshlrev_b64 v[34:35], 7, v[48:49]
	v_lshl_add_u64 v[34:35], s[16:17], 0, v[34:35]
	v_lshl_add_u64 v[34:35], s[38:39], 3, v[34:35]
	s_lshl_b32 s88, s44, 3
	v_lshl_add_u64 v[34:35], v[34:35], 0, s[88:89]
	global_store_dwordx2 v[34:35], v[32:33], off

; __device__ __forceinline__ u32x4 pack8(const f32x4& a, const f32x4& b) { u32x4 w; w.x = cvt_pk_bf16(a[0], a[1]); w.y = cvt_pk_bf16(a[2], a[3]); w.z = cvt_pk_bf16(b[0], b[1]); w.w = cvt_pk_bf16(b[2], b[3]); return w; }
; __device__ __forceinline__ f32x2 gelu_pk(f32x2 v) {
;     const f32x2 av = __builtin_elementwise_abs(v), d = av * 0.2316418882f + 1.0f;
;     f32x2 t; t.x = __builtin_amdgcn_rcpf(d.x); t.y = __builtin_amdgcn_rcpf(d.y);
;     f32x2 q = t * 0.5307027145f + (-0.7265760135f); q = q * t + 0.7107068705f; q = q * t + (-0.142248368f); q = q * t + 0.127414796f; q = q * t;
;     const f32x2 s = (v * v) * (-0.72134752044f);
;     f32x2 e; e.x = __builtin_amdgcn_exp2f(s.x); e.y = __builtin_amdgcn_exp2f(s.y);
;     const f32x2 m = v * (q * e), r = v - m;
;     f32x2 o; o.x = v.x < 0.f ? m.x : r.x; o.y = v.y < 0.f ? m.y : r.y; return o;
;     __device__ __forceinline__ void operator()(const f32x4 (&acc)[2][2][4][2], const Unit& u, int ui, int wr, int wc, int fr, int fq) const {
;     ...
;             for (int m = 0; m < 4; ++m) { const float r = rs[ai][m]; const int row = row0 + ai * HALF + m * 16; bf16_t* rowp = Z + (size_t)row * 2048 + col0; float s1 = 0.f, s2 = 0.f;
; #pragma unroll
;                 for (int bj = 0; bj < 2; ++bj) { const f32x4 v0 = acc[ai][bj][m][0] * r, v1 = acc[ai][bj][m][1] * r;
;                     const f32x2 a = gelu_pk((f32x2){v0[0], v0[1]}), b = gelu_pk((f32x2){v0[2], v0[3]}), c = gelu_pk((f32x2){v1[0], v1[1]}), d = gelu_pk((f32x2){v1[2], v1[3]});
;                     const f32x4 z0 = (f32x4){a.x, a.y, b.x, b.y}, z1 = (f32x4){c.x, c.y, d.x, d.y};
;                     *(u32x4*)(rowp + bj * HALF) = pack8(z0, z1);
.LBB0_776:
	v_pk_mul_f32 v[36:37], v[28:29], v[142:143] op_sel_hi:[1,0]
	s_mov_b32 s0, 0xbf3a00e3
	v_and_b32_e32 v29, 0x7fffffff, v37
	v_and_b32_e32 v28, 0x7fffffff, v36
	v_pk_fma_f32 v[28:29], v[28:29], s[56:57], 1.0 op_sel_hi:[1,0,0]
	v_pk_mul_f32 v[42:43], v[24:25], v[142:143] op_sel_hi:[1,0]
	v_rcp_f32_e32 v38, v28
	v_rcp_f32_e32 v39, v29
	v_mov_b64_e32 v[28:29], s[0:1]
	s_mov_b32 s0, 0x3f07dc22
	s_mov_b32 s88, 0x3e027906
	v_pk_fma_f32 v[24:25], v[38:39], s[0:1], v[28:29] op_sel_hi:[1,0,0]
	v_pk_mul_f32 v[30:31], v[30:31], v[142:143] op_sel_hi:[1,0]
	v_pk_fma_f32 v[24:25], v[38:39], v[24:25], s[2:3] op_sel_hi:[1,1,0]
	v_and_b32_e32 v41, 0x7fffffff, v31
	v_pk_fma_f32 v[24:25], v[38:39], v[24:25], s[4:5] op_sel_hi:[1,1,0]
	v_and_b32_e32 v40, 0x7fffffff, v30
	v_pk_fma_f32 v[24:25], v[38:39], v[24:25], s[88:89] op_sel_hi:[1,1,0]
	v_pk_fma_f32 v[40:41], v[40:41], s[56:57], 1.0 op_sel_hi:[1,0,0]
	v_pk_mul_f32 v[24:25], v[38:39], v[24:25]
	v_pk_mul_f32 v[38:39], v[36:37], v[36:37]
	v_rcp_f32_e32 v40, v40
	v_pk_mul_f32 v[38:39], v[38:39], s[86:87] op_sel_hi:[1,0]
	v_rcp_f32_e32 v41, v41
	v_exp_f32_e32 v38, v38
	v_exp_f32_e32 v39, v39
	v_pk_mul_f32 v[44:45], v[26:27], v[142:143] op_sel_hi:[1,0]
	v_pk_mul_f32 v[26:27], v[30:31], v[30:31]
	v_and_b32_e32 v49, 0x7fffffff, v43
	v_pk_mul_f32 v[24:25], v[38:39], v[24:25]
	v_pk_mul_f32 v[26:27], v[26:27], s[86:87] op_sel_hi:[1,0]
	v_pk_mul_f32 v[38:39], v[36:37], v[24:25]
	v_pk_fma_f32 v[46:47], v[36:37], v[24:25], v[36:37] neg_lo:[1,0,0] neg_hi:[1,0,0]
	v_pk_fma_f32 v[24:25], v[40:41], s[0:1], v[28:29] op_sel_hi:[1,0,0]
	v_exp_f32_e32 v26, v26
	v_pk_fma_f32 v[24:25], v[40:41], v[24:25], s[2:3] op_sel_hi:[1,1,0]
	v_exp_f32_e32 v27, v27
	v_pk_fma_f32 v[24:25], v[40:41], v[24:25], s[4:5] op_sel_hi:[1,1,0]
	v_and_b32_e32 v48, 0x7fffffff, v42
	v_pk_fma_f32 v[24:25], v[40:41], v[24:25], s[88:89] op_sel_hi:[1,1,0]
	v_cmp_gt_f32_e32 vcc, 0, v30
	v_pk_mul_f32 v[24:25], v[40:41], v[24:25]
	v_pk_fma_f32 v[48:49], v[48:49], s[56:57], 1.0 op_sel_hi:[1,0,0]
	v_pk_mul_f32 v[24:25], v[26:27], v[24:25]
	v_rcp_f32_e32 v48, v48
	v_pk_mul_f32 v[26:27], v[30:31], v[24:25]
	v_pk_fma_f32 v[40:41], v[30:31], v[24:25], v[30:31] neg_lo:[1,0,0] neg_hi:[1,0,0]
	v_rcp_f32_e32 v49, v49
	v_cndmask_b32_e32 v25, v40, v26, vcc
	v_cmp_gt_f32_e32 vcc, 0, v36
	v_and_b32_e32 v40, 0x7fffffff, v44
	v_pk_mul_f32 v[20:21], v[20:21], v[142:143] op_sel_hi:[1,0]
	v_cndmask_b32_e32 v24, v46, v38, vcc
	v_cmp_gt_f32_e32 vcc, 0, v31
	v_pk_fma_f32 v[30:31], v[48:49], s[0:1], v[28:29] op_sel_hi:[1,0,0]
	v_pk_mul_f32 v[54:55], v[16:17], v[142:143] op_sel_hi:[1,0]
	v_cndmask_b32_e32 v27, v41, v27, vcc
	v_cmp_gt_f32_e32 vcc, 0, v37
	v_and_b32_e32 v41, 0x7fffffff, v45
	v_pk_fma_f32 v[30:31], v[48:49], v[30:31], s[2:3] op_sel_hi:[1,1,0]
	v_cndmask_b32_e32 v26, v47, v39, vcc
	v_pk_mul_f32 v[38:39], v[42:43], v[42:43]
	v_pk_fma_f32 v[40:41], v[40:41], s[56:57], 1.0 op_sel_hi:[1,0,0]
	v_pk_mul_f32 v[38:39], v[38:39], s[86:87] op_sel_hi:[1,0]
	v_pk_fma_f32 v[30:31], v[48:49], v[30:31], s[4:5] op_sel_hi:[1,1,0]
	v_exp_f32_e32 v38, v38
	v_exp_f32_e32 v39, v39
	v_rcp_f32_e32 v40, v40
	v_rcp_f32_e32 v41, v41
	v_pk_fma_f32 v[30:31], v[48:49], v[30:31], s[88:89] op_sel_hi:[1,1,0]
	v_pk_mul_f32 v[36:37], v[44:45], v[44:45]
	v_pk_mul_f32 v[30:31], v[48:49], v[30:31]
	v_pk_mul_f32 v[36:37], v[36:37], s[86:87] op_sel_hi:[1,0]
	v_pk_mul_f32 v[30:31], v[38:39], v[30:31]
	v_exp_f32_e32 v36, v36
	v_pk_mul_f32 v[38:39], v[42:43], v[30:31]
	v_pk_fma_f32 v[46:47], v[42:43], v[30:31], v[42:43] neg_lo:[1,0,0] neg_hi:[1,0,0]
	v_pk_fma_f32 v[30:31], v[40:41], s[0:1], v[28:29] op_sel_hi:[1,0,0]
	v_exp_f32_e32 v37, v37
	v_pk_fma_f32 v[30:31], v[40:41], v[30:31], s[2:3] op_sel_hi:[1,1,0]
	v_pk_mul_f32 v[22:23], v[22:23], v[142:143] op_sel_hi:[1,0]
	v_pk_fma_f32 v[30:31], v[40:41], v[30:31], s[4:5] op_sel_hi:[1,1,0]
	v_and_b32_e32 v57, 0x7fffffff, v23
	v_pk_fma_f32 v[30:31], v[40:41], v[30:31], s[88:89] op_sel_hi:[1,1,0]
	v_and_b32_e32 v56, 0x7fffffff, v22
	v_pk_mul_f32 v[30:31], v[40:41], v[30:31]
	v_pk_fma_f32 v[56:57], v[56:57], s[56:57], 1.0 op_sel_hi:[1,0,0]
	v_pk_mul_f32 v[30:31], v[36:37], v[30:31]
	v_and_b32_e32 v37, 0x7fffffff, v21
	v_and_b32_e32 v36, 0x7fffffff, v20
	v_pk_fma_f32 v[36:37], v[36:37], s[56:57], 1.0 op_sel_hi:[1,0,0]
	v_rcp_f32_e32 v56, v56
	v_rcp_f32_e32 v36, v36
	v_rcp_f32_e32 v37, v37
	v_rcp_f32_e32 v57, v57
	v_pk_mul_f32 v[52:53], v[18:19], v[142:143] op_sel_hi:[1,0]
	v_pk_mul_f32 v[18:19], v[22:23], v[22:23]
	v_pk_fma_f32 v[16:17], v[36:37], s[0:1], v[28:29] op_sel_hi:[1,0,0]
	v_pk_mul_f32 v[18:19], v[18:19], s[86:87] op_sel_hi:[1,0]
	v_pk_fma_f32 v[16:17], v[36:37], v[16:17], s[2:3] op_sel_hi:[1,1,0]
	v_exp_f32_e32 v18, v18
	v_pk_fma_f32 v[16:17], v[36:37], v[16:17], s[4:5] op_sel_hi:[1,1,0]
	v_exp_f32_e32 v19, v19
	v_pk_fma_f32 v[16:17], v[36:37], v[16:17], s[88:89] op_sel_hi:[1,1,0]
	v_and_b32_e32 v61, 0x7fffffff, v55
	v_pk_mul_f32 v[16:17], v[36:37], v[16:17]
	v_pk_mul_f32 v[36:37], v[20:21], v[20:21]
	v_and_b32_e32 v60, 0x7fffffff, v54
	v_pk_mul_f32 v[36:37], v[36:37], s[86:87] op_sel_hi:[1,0]
	v_pk_fma_f32 v[60:61], v[60:61], s[56:57], 1.0 op_sel_hi:[1,0,0]
	v_exp_f32_e32 v36, v36
	v_exp_f32_e32 v37, v37
	v_pk_mul_f32 v[48:49], v[44:45], v[30:31]
	v_pk_fma_f32 v[50:51], v[44:45], v[30:31], v[44:45] neg_lo:[1,0,0] neg_hi:[1,0,0]
	v_cmp_gt_f32_e32 vcc, 0, v45
	v_pk_mul_f32 v[16:17], v[36:37], v[16:17]
	v_rcp_f32_e32 v60, v60
	v_pk_mul_f32 v[36:37], v[20:21], v[16:17]
	v_pk_fma_f32 v[58:59], v[20:21], v[16:17], v[20:21] neg_lo:[1,0,0] neg_hi:[1,0,0]
	v_pk_fma_f32 v[16:17], v[56:57], s[0:1], v[28:29] op_sel_hi:[1,0,0]
	v_rcp_f32_e32 v61, v61
	v_pk_fma_f32 v[16:17], v[56:57], v[16:17], s[2:3] op_sel_hi:[1,1,0]
	v_cndmask_b32_e32 v30, v51, v49, vcc
	v_pk_fma_f32 v[16:17], v[56:57], v[16:17], s[4:5] op_sel_hi:[1,1,0]
	v_cmp_gt_f32_e32 vcc, 0, v22
	v_pk_fma_f32 v[16:17], v[56:57], v[16:17], s[88:89] op_sel_hi:[1,1,0]
	v_add_u32_e32 v32, 0xa0, v140
	v_pk_mul_f32 v[16:17], v[56:57], v[16:17]
	v_ashrrev_i32_e32 v33, 31, v32
	v_pk_mul_f32 v[16:17], v[18:19], v[16:17]
	s_waitcnt lgkmcnt(0)
; __device__ __forceinline__ u32x4 pack8(const f32x4& a, const f32x4& b) { u32x4 w; w.x = cvt_pk_bf16(a[0], a[1]); w.y = cvt_pk_bf16(a[2], a[3]); w.z = cvt_pk_bf16(b[0], b[1]); w.w = cvt_pk_bf16(b[2], b[3]); return w; }
;     __device__ __forceinline__ void operator()(const f32x4 (&acc)[2][2][4][2], const Unit& u, int ui, int wr, int wc, int fr, int fq) const {
;     ...
;             for (int m = 0; m < 4; ++m) { const float r = rs[ai][m]; const int row = row0 + ai * HALF + m * 16; bf16_t* rowp = Z + (size_t)row * 2048 + col0; float s1 = 0.f, s2 = 0.f;
; #pragma unroll
;                 for (int bj = 0; bj < 2; ++bj) { const f32x4 v0 = acc[ai][bj][m][0] * r, v1 = acc[ai][bj][m][1] * r;
;                     const f32x2 a = gelu_pk((f32x2){v0[0], v0[1]}), b = gelu_pk((f32x2){v0[2], v0[3]}), c = gelu_pk((f32x2){v1[0], v1[1]}), d = gelu_pk((f32x2){v1[2], v1[3]});
;                     const f32x4 z0 = (f32x4){a.x, a.y, b.x, b.y}, z1 = (f32x4){c.x, c.y, d.x, d.y};
;                     *(u32x4*)(rowp + bj * HALF) = pack8(z0, z1);
;                     s1 += (z0[0] + z0[1]) + (z0[2] + z0[3]) + (z1[0] + z1[1]) + (z1[2] + z1[3]);
;                     s2 += (z0[0] * z0[0] + z0[1] * z0[1]) + (z0[2] * z0[2] + z0[3] * z0[3]) + (z1[0] * z1[0] + z1[1] * z1[1]) + (z1[2] * z1[2] + z1[3] * z1[3]); }
;                 if (u.pn >= 4) { s1 += __shfl_xor(s1, 16); s1 += __shfl_xor(s1, 32); s2 += __shfl_xor(s2, 16); s2 += __shfl_xor(s2, 32);
;                     if (fq == 0) vst[(size_t)row * 16 + (u.pn - 4) * 4 + wc] = (f32x2){s1, s2}; } }
	v_lshlrev_b64 v[34:35], 12, v[32:33]
	v_pk_mul_f32 v[18:19], v[22:23], v[16:17]
	v_pk_fma_f32 v[56:57], v[22:23], v[16:17], v[22:23] neg_lo:[1,0,0] neg_hi:[1,0,0]
	v_lshl_add_u64 v[34:35], s[20:21], 0, v[34:35]
	v_cndmask_b32_e32 v17, v56, v18, vcc
	v_cmp_gt_f32_e32 vcc, 0, v20
	v_lshl_add_u64 v[34:35], v[162:163], 1, v[34:35]
	v_cvt_pk_bf16_f32 v40, v24, v26
	v_cvt_pk_bf16_f32 v41, v25, v27
	s_nop 0
	v_cndmask_b32_e32 v16, v58, v36, vcc
	v_cmp_gt_f32_e32 vcc, 0, v23
	v_pk_mul_f32 v[22:23], v[54:55], v[54:55]
	s_nop 0
	v_cndmask_b32_e32 v19, v57, v19, vcc
	v_cmp_gt_f32_e32 vcc, 0, v21
	v_pk_fma_f32 v[20:21], v[60:61], s[0:1], v[28:29] op_sel_hi:[1,0,0]
	v_pk_mul_f32 v[22:23], v[22:23], s[86:87] op_sel_hi:[1,0]
	v_pk_fma_f32 v[20:21], v[60:61], v[20:21], s[2:3] op_sel_hi:[1,1,0]
	v_exp_f32_e32 v22, v22
	v_exp_f32_e32 v23, v23
	v_pk_fma_f32 v[20:21], v[60:61], v[20:21], s[4:5] op_sel_hi:[1,1,0]
	v_cndmask_b32_e32 v18, v59, v37, vcc
	v_pk_fma_f32 v[20:21], v[60:61], v[20:21], s[88:89] op_sel_hi:[1,1,0]
	v_cmp_gt_f32_e32 vcc, 0, v42
	v_pk_mul_f32 v[20:21], v[60:61], v[20:21]
	v_pk_mul_f32 v[56:57], v[52:53], v[52:53]
	v_pk_mul_f32 v[20:21], v[22:23], v[20:21]
	v_cndmask_b32_e32 v22, v46, v38, vcc
	v_pk_mul_f32 v[36:37], v[54:55], v[20:21]
	v_pk_fma_f32 v[58:59], v[54:55], v[20:21], v[54:55] neg_lo:[1,0,0] neg_hi:[1,0,0]
	v_cmp_gt_f32_e32 vcc, 0, v54
	v_and_b32_e32 v38, 0x7fffffff, v52
	s_nop 0
	v_cndmask_b32_e32 v23, v58, v36, vcc
	v_cmp_gt_f32_e32 vcc, 0, v43
	s_nop 1
	v_cndmask_b32_e32 v36, v47, v39, vcc
	v_and_b32_e32 v39, 0x7fffffff, v53
	v_pk_fma_f32 v[38:39], v[38:39], s[56:57], 1.0 op_sel_hi:[1,0,0]
	v_cmp_gt_f32_e32 vcc, 0, v44
	v_rcp_f32_e32 v44, v38
	v_rcp_f32_e32 v45, v39
	v_cvt_pk_bf16_f32 v42, v22, v36
	v_cndmask_b32_e32 v21, v50, v48, vcc
	v_cvt_pk_bf16_f32 v43, v21, v30
	global_store_dwordx4 v[34:35], v[40:43], off
	v_pk_fma_f32 v[28:29], v[44:45], s[0:1], v[28:29] op_sel_hi:[1,0,0]
	v_cmp_gt_f32_e32 vcc, 0, v55
	v_pk_mul_f32 v[40:41], v[56:57], s[86:87] op_sel_hi:[1,0]
	v_pk_fma_f32 v[28:29], v[44:45], v[28:29], s[2:3] op_sel_hi:[1,1,0]
	v_exp_f32_e32 v40, v40
	v_exp_f32_e32 v41, v41
	v_pk_fma_f32 v[28:29], v[44:45], v[28:29], s[4:5] op_sel_hi:[1,1,0]
	v_cndmask_b32_e32 v38, v59, v37, vcc
	v_pk_fma_f32 v[28:29], v[44:45], v[28:29], s[88:89] op_sel_hi:[1,1,0]
	v_cmp_gt_f32_e32 vcc, 0, v53
	v_pk_mul_f32 v[28:29], v[44:45], v[28:29]
	s_nop 0
	v_pk_mul_f32 v[28:29], v[40:41], v[28:29]
	s_nop 0
	v_pk_mul_f32 v[40:41], v[52:53], v[28:29]
	v_pk_fma_f32 v[28:29], v[52:53], v[28:29], v[52:53] neg_lo:[1,0,0] neg_hi:[1,0,0]
	s_nop 0
	v_cndmask_b32_e32 v29, v29, v41, vcc
	v_cmp_gt_f32_e32 vcc, 0, v52
	s_nop 1
	v_cndmask_b32_e32 v28, v28, v40, vcc
	s_and_b64 vcc, exec, s[12:13]
	v_cvt_pk_bf16_f32 v40, v16, v18
	v_cvt_pk_bf16_f32 v41, v17, v19
	v_cvt_pk_bf16_f32 v42, v23, v38
	v_cvt_pk_bf16_f32 v43, v28, v29
	global_store_dwordx4 v[34:35], v[40:43], off offset:256
	s_cbranch_vccnz .LBB0_780
	v_mov_b32_e32 v20, v23
	v_mov_b32_e32 v39, v21
	v_pk_add_f32 v[34:35], v[20:21], v[38:39]
	v_pk_mul_f32 v[40:41], v[20:21], v[38:39]
	v_mov_b32_e32 v42, v22
	v_mov_b32_e32 v43, v36
	v_mul_f32_e32 v20, v22, v22
	v_mov_b32_e32 v37, v23
	v_pk_fma_f32 v[42:43], v[42:43], v[42:43], v[20:21] op_sel_hi:[1,1,0]
	v_mul_f32_e32 v20, v28, v28
	v_pk_fma_f32 v[44:45], v[28:29], v[28:29], v[20:21] op_sel_hi:[1,1,0]
	v_mov_b32_e32 v46, v16
	v_mov_b32_e32 v47, v18
	v_mul_f32_e32 v20, v16, v16
	v_pk_add_f32 v[50:51], v[22:23], v[36:37]
	v_pk_mul_f32 v[22:23], v[22:23], v[36:37]
	v_mov_b32_e32 v35, v41
	v_pk_mul_f32 v[40:41], v[26:27], v[26:27]
	v_pk_fma_f32 v[46:47], v[46:47], v[46:47], v[20:21] op_sel_hi:[1,1,0]
	v_mov_b32_e32 v48, v17
	v_mov_b32_e32 v49, v19
	v_mul_f32_e32 v20, v17, v17
	v_mov_b32_e32 v51, v23
	v_pk_mul_f32 v[22:23], v[38:39], v[38:39]
	v_pk_add_f32 v[16:17], v[16:17], v[18:19]
	v_and_b32_e32 v19, 64, v192
	v_pk_fma_f32 v[40:41], v[24:25], v[24:25], v[40:41]
	v_pk_add_f32 v[24:25], v[24:25], v[26:27]
	v_xor_b32_e32 v18, 16, v192
	v_add_u32_e32 v23, 64, v19
	v_pk_fma_f32 v[48:49], v[48:49], v[48:49], v[20:21] op_sel_hi:[1,1,0]
	v_pk_add_f32 v[24:25], v[24:25], v[24:25] op_sel:[0,1] op_sel_hi:[1,0]
	v_cmp_lt_i32_e32 vcc, v18, v23
	v_mul_f32_e32 v52, v30, v30
	v_pk_add_f32 v[40:41], v[40:41], v[40:41] op_sel_hi:[0,1]
	v_cndmask_b32_e32 v18, v192, v18, vcc
	v_mov_b32_e32 v46, v21
	v_mov_b32_e32 v31, v49
	v_mov_b32_e32 v25, v22
	v_pk_add_f32 v[16:17], v[16:17], v[16:17] op_sel:[0,1] op_sel_hi:[1,0]
	v_lshlrev_b32_e32 v26, 2, v18
	v_pk_add_f32 v[18:19], v[46:47], v[30:31]
	v_pk_add_f32 v[20:21], v[50:51], v[24:25]
	v_mov_b32_e32 v42, v28
	v_mov_b32_e32 v40, v29
	v_mov_b32_e32 v17, v52
	v_pk_add_f32 v[18:19], v[20:21], v[18:19]
	v_mov_b32_e32 v147, v45
	v_pk_add_f32 v[20:21], v[42:43], v[40:41]
	v_pk_add_f32 v[16:17], v[34:35], v[16:17]
	v_pk_add_f32 v[18:19], v[18:19], v[146:147]
	v_pk_add_f32 v[16:17], v[16:17], v[20:21]
	v_xor_b32_e32 v20, 32, v192
	v_pk_add_f32 v[16:17], v[16:17], v[18:19]
	ds_bpermute_b32 v18, v26, v16
	ds_bpermute_b32 v19, v26, v17
	v_cmp_lt_i32_e32 vcc, v20, v23
	s_waitcnt lgkmcnt(0)
	v_pk_add_f32 v[16:17], v[16:17], v[18:19]
	v_cndmask_b32_e32 v20, v192, v20, vcc
	v_lshlrev_b32_e32 v20, 2, v20
	v_mov_b32_e32 v18, v16
	s_nop 1
	v_permlane32_swap_b32_e32 v18, v16
	v_mov_b32_e32 v19, v17
	s_nop 1
	v_permlane32_swap_b32_e32 v19, v17
	s_and_saveexec_b64 s[0:1], s[10:11]
	s_cbranch_execz .LBB0_779
	s_waitcnt lgkmcnt(0)
	v_pk_add_f32 v[16:17], v[16:17], v[18:19]
	v_lshlrev_b64 v[18:19], 7, v[32:33]
	v_lshl_add_u64 v[18:19], s[16:17], 0, v[18:19]
	v_lshl_add_u64 v[18:19], s[38:39], 3, v[18:19]
	s_lshl_b32 s88, s44, 3
	v_lshl_add_u64 v[18:19], v[18:19], 0, s[88:89]
	global_store_dwordx2 v[18:19], v[16:17], off

; __device__ __forceinline__ u32x4 pack8(const f32x4& a, const f32x4& b) { u32x4 w; w.x = cvt_pk_bf16(a[0], a[1]); w.y = cvt_pk_bf16(a[2], a[3]); w.z = cvt_pk_bf16(b[0], b[1]); w.w = cvt_pk_bf16(b[2], b[3]); return w; }
; __device__ __forceinline__ f32x2 gelu_pk(f32x2 v) {
;     const f32x2 av = __builtin_elementwise_abs(v), d = av * 0.2316418882f + 1.0f;
;     f32x2 t; t.x = __builtin_amdgcn_rcpf(d.x); t.y = __builtin_amdgcn_rcpf(d.y);
;     f32x2 q = t * 0.5307027145f + (-0.7265760135f); q = q * t + 0.7107068705f; q = q * t + (-0.142248368f); q = q * t + 0.127414796f; q = q * t;
;     const f32x2 s = (v * v) * (-0.72134752044f);
;     f32x2 e; e.x = __builtin_amdgcn_exp2f(s.x); e.y = __builtin_amdgcn_exp2f(s.y);
;     const f32x2 m = v * (q * e), r = v - m;
;     f32x2 o; o.x = v.x < 0.f ? m.x : r.x; o.y = v.y < 0.f ? m.y : r.y; return o;
;     __device__ __forceinline__ void operator()(const f32x4 (&acc)[2][2][4][2], const Unit& u, int ui, int wr, int wc, int fr, int fq) const {
;     ...
;             for (int m = 0; m < 4; ++m) { const float r = rs[ai][m]; const int row = row0 + ai * HALF + m * 16; bf16_t* rowp = Z + (size_t)row * 2048 + col0; float s1 = 0.f, s2 = 0.f;
; #pragma unroll
;                 for (int bj = 0; bj < 2; ++bj) { const f32x4 v0 = acc[ai][bj][m][0] * r, v1 = acc[ai][bj][m][1] * r;
;                     const f32x2 a = gelu_pk((f32x2){v0[0], v0[1]}), b = gelu_pk((f32x2){v0[2], v0[3]}), c = gelu_pk((f32x2){v1[0], v1[1]}), d = gelu_pk((f32x2){v1[2], v1[3]});
;                     const f32x4 z0 = (f32x4){a.x, a.y, b.x, b.y}, z1 = (f32x4){c.x, c.y, d.x, d.y};
;                     *(u32x4*)(rowp + bj * HALF) = pack8(z0, z1);
.LBB0_780:
	v_mov_b32_e32 v20, v143
	v_pk_mul_f32 v[22:23], v[12:13], v[20:21] op_sel_hi:[1,0]
	s_mov_b32 s0, 0xbf3a00e3
	v_and_b32_e32 v13, 0x7fffffff, v23
	v_and_b32_e32 v12, 0x7fffffff, v22
	v_pk_fma_f32 v[12:13], v[12:13], s[56:57], 1.0 op_sel_hi:[1,0,0]
	v_pk_mul_f32 v[26:27], v[8:9], v[20:21] op_sel_hi:[1,0]
	v_rcp_f32_e32 v24, v12
	v_rcp_f32_e32 v25, v13
	v_mov_b64_e32 v[12:13], s[0:1]
	s_mov_b32 s0, 0x3f07dc22
	s_mov_b32 s88, 0x3e027906
	v_pk_fma_f32 v[8:9], v[24:25], s[0:1], v[12:13] op_sel_hi:[1,0,0]
	v_pk_mul_f32 v[14:15], v[14:15], v[20:21] op_sel_hi:[1,0]
	v_pk_fma_f32 v[8:9], v[24:25], v[8:9], s[2:3] op_sel_hi:[1,1,0]
	v_and_b32_e32 v31, 0x7fffffff, v15
	v_pk_fma_f32 v[8:9], v[24:25], v[8:9], s[4:5] op_sel_hi:[1,1,0]
	v_and_b32_e32 v30, 0x7fffffff, v14
	v_pk_fma_f32 v[8:9], v[24:25], v[8:9], s[88:89] op_sel_hi:[1,1,0]
	v_pk_fma_f32 v[30:31], v[30:31], s[56:57], 1.0 op_sel_hi:[1,0,0]
	v_pk_mul_f32 v[8:9], v[24:25], v[8:9]
	v_pk_mul_f32 v[24:25], v[22:23], v[22:23]
	v_rcp_f32_e32 v30, v30
	v_pk_mul_f32 v[24:25], v[24:25], s[86:87] op_sel_hi:[1,0]
	v_rcp_f32_e32 v31, v31
	v_exp_f32_e32 v24, v24
	v_exp_f32_e32 v25, v25
	v_pk_mul_f32 v[28:29], v[10:11], v[20:21] op_sel_hi:[1,0]
	v_pk_mul_f32 v[10:11], v[14:15], v[14:15]
	v_pk_mul_f32 v[4:5], v[4:5], v[20:21] op_sel_hi:[1,0]
	v_pk_mul_f32 v[8:9], v[24:25], v[8:9]
	v_pk_mul_f32 v[10:11], v[10:11], s[86:87] op_sel_hi:[1,0]
	v_pk_mul_f32 v[24:25], v[22:23], v[8:9]
	v_pk_fma_f32 v[32:33], v[22:23], v[8:9], v[22:23] neg_lo:[1,0,0] neg_hi:[1,0,0]
	v_pk_fma_f32 v[8:9], v[30:31], s[0:1], v[12:13] op_sel_hi:[1,0,0]
	v_exp_f32_e32 v10, v10
	v_pk_fma_f32 v[8:9], v[30:31], v[8:9], s[2:3] op_sel_hi:[1,1,0]
	v_exp_f32_e32 v11, v11
	v_and_b32_e32 v37, 0x7fffffff, v5
	v_and_b32_e32 v36, 0x7fffffff, v4
	v_pk_fma_f32 v[8:9], v[30:31], v[8:9], s[4:5] op_sel_hi:[1,1,0]
	v_pk_fma_f32 v[36:37], v[36:37], s[56:57], 1.0 op_sel_hi:[1,0,0]
	v_pk_fma_f32 v[8:9], v[30:31], v[8:9], s[88:89] op_sel_hi:[1,1,0]
	v_rcp_f32_e32 v36, v36
	v_rcp_f32_e32 v37, v37
	v_pk_mul_f32 v[8:9], v[30:31], v[8:9]
	v_and_b32_e32 v35, 0x7fffffff, v27
	v_pk_mul_f32 v[8:9], v[10:11], v[8:9]
	v_and_b32_e32 v34, 0x7fffffff, v26
	v_pk_mul_f32 v[10:11], v[14:15], v[8:9]
	v_pk_fma_f32 v[30:31], v[14:15], v[8:9], v[14:15] neg_lo:[1,0,0] neg_hi:[1,0,0]
	v_cmp_gt_f32_e32 vcc, 0, v14
	v_pk_fma_f32 v[34:35], v[34:35], s[56:57], 1.0 op_sel_hi:[1,0,0]
	v_pk_mul_f32 v[6:7], v[6:7], v[20:21] op_sel_hi:[1,0]
	v_cndmask_b32_e32 v9, v30, v10, vcc
	v_cmp_gt_f32_e32 vcc, 0, v22
	v_rcp_f32_e32 v34, v34
	v_rcp_f32_e32 v35, v35
	v_pk_mul_f32 v[38:39], v[2:3], v[20:21] op_sel_hi:[1,0]
	v_pk_mul_f32 v[20:21], v[0:1], v[20:21] op_sel_hi:[1,0]
	v_pk_fma_f32 v[0:1], v[36:37], s[0:1], v[12:13] op_sel_hi:[1,0,0]
	v_cndmask_b32_e32 v8, v32, v24, vcc
	v_cmp_gt_f32_e32 vcc, 0, v15
	v_pk_fma_f32 v[0:1], v[36:37], v[0:1], s[2:3] op_sel_hi:[1,1,0]
	v_pk_fma_f32 v[14:15], v[34:35], s[0:1], v[12:13] op_sel_hi:[1,0,0]
	v_cndmask_b32_e32 v11, v31, v11, vcc
	v_cmp_gt_f32_e32 vcc, 0, v23
	v_pk_fma_f32 v[0:1], v[36:37], v[0:1], s[4:5] op_sel_hi:[1,1,0]
	v_and_b32_e32 v31, 0x7fffffff, v29
	v_cndmask_b32_e32 v10, v33, v25, vcc
	v_pk_mul_f32 v[24:25], v[26:27], v[26:27]
	v_pk_fma_f32 v[0:1], v[36:37], v[0:1], s[88:89] op_sel_hi:[1,1,0]
	v_pk_mul_f32 v[24:25], v[24:25], s[86:87] op_sel_hi:[1,0]
	v_and_b32_e32 v30, 0x7fffffff, v28
	v_pk_mul_f32 v[0:1], v[36:37], v[0:1]
	v_pk_mul_f32 v[36:37], v[4:5], v[4:5]
	v_pk_fma_f32 v[14:15], v[34:35], v[14:15], s[2:3] op_sel_hi:[1,1,0]
	v_exp_f32_e32 v24, v24
	v_exp_f32_e32 v25, v25
	v_pk_fma_f32 v[30:31], v[30:31], s[56:57], 1.0 op_sel_hi:[1,0,0]
	v_pk_mul_f32 v[36:37], v[36:37], s[86:87] op_sel_hi:[1,0]
	v_and_b32_e32 v41, 0x7fffffff, v7
	v_and_b32_e32 v40, 0x7fffffff, v6
	v_pk_fma_f32 v[14:15], v[34:35], v[14:15], s[4:5] op_sel_hi:[1,1,0]
	v_rcp_f32_e32 v30, v30
	v_rcp_f32_e32 v31, v31
	v_exp_f32_e32 v36, v36
	v_exp_f32_e32 v37, v37
	v_pk_fma_f32 v[40:41], v[40:41], s[56:57], 1.0 op_sel_hi:[1,0,0]
	v_pk_fma_f32 v[14:15], v[34:35], v[14:15], s[88:89] op_sel_hi:[1,1,0]
	v_rcp_f32_e32 v40, v40
	v_rcp_f32_e32 v41, v41
	v_pk_mul_f32 v[14:15], v[34:35], v[14:15]
	v_pk_mul_f32 v[22:23], v[28:29], v[28:29]
	v_pk_mul_f32 v[14:15], v[24:25], v[14:15]
	v_pk_mul_f32 v[22:23], v[22:23], s[86:87] op_sel_hi:[1,0]
	v_pk_mul_f32 v[32:33], v[26:27], v[14:15]
	v_pk_fma_f32 v[34:35], v[26:27], v[14:15], v[26:27] neg_lo:[1,0,0] neg_hi:[1,0,0]
	v_pk_fma_f32 v[14:15], v[30:31], s[0:1], v[12:13] op_sel_hi:[1,0,0]
	v_pk_mul_f32 v[2:3], v[6:7], v[6:7]
	v_pk_mul_f32 v[0:1], v[36:37], v[0:1]
	v_pk_fma_f32 v[14:15], v[30:31], v[14:15], s[2:3] op_sel_hi:[1,1,0]
	v_exp_f32_e32 v22, v22
	v_exp_f32_e32 v23, v23
	v_pk_mul_f32 v[36:37], v[4:5], v[0:1]
	v_pk_fma_f32 v[42:43], v[4:5], v[0:1], v[4:5] neg_lo:[1,0,0] neg_hi:[1,0,0]
	v_pk_fma_f32 v[0:1], v[40:41], s[0:1], v[12:13] op_sel_hi:[1,0,0]
	v_pk_mul_f32 v[2:3], v[2:3], s[86:87] op_sel_hi:[1,0]
	v_pk_fma_f32 v[14:15], v[30:31], v[14:15], s[4:5] op_sel_hi:[1,1,0]
	v_pk_fma_f32 v[0:1], v[40:41], v[0:1], s[2:3] op_sel_hi:[1,1,0]
	v_exp_f32_e32 v2, v2
	v_exp_f32_e32 v3, v3
	v_pk_fma_f32 v[14:15], v[30:31], v[14:15], s[88:89] op_sel_hi:[1,1,0]
	v_pk_fma_f32 v[0:1], v[40:41], v[0:1], s[4:5] op_sel_hi:[1,1,0]
	v_pk_mul_f32 v[14:15], v[30:31], v[14:15]
	v_pk_fma_f32 v[0:1], v[40:41], v[0:1], s[88:89] op_sel_hi:[1,1,0]
	v_and_b32_e32 v45, 0x7fffffff, v21
	v_and_b32_e32 v44, 0x7fffffff, v20
	v_pk_mul_f32 v[14:15], v[22:23], v[14:15]
	v_pk_mul_f32 v[0:1], v[40:41], v[0:1]
	v_pk_fma_f32 v[44:45], v[44:45], s[56:57], 1.0 op_sel_hi:[1,0,0]
	v_pk_mul_f32 v[22:23], v[28:29], v[14:15]
	v_pk_fma_f32 v[30:31], v[28:29], v[14:15], v[28:29] neg_lo:[1,0,0] neg_hi:[1,0,0]
	v_cmp_gt_f32_e32 vcc, 0, v29
	v_pk_mul_f32 v[0:1], v[2:3], v[0:1]
	v_rcp_f32_e32 v44, v44
	v_rcp_f32_e32 v45, v45
	v_cndmask_b32_e32 v14, v31, v23, vcc
	v_pk_mul_f32 v[2:3], v[6:7], v[0:1]
	v_pk_fma_f32 v[40:41], v[6:7], v[0:1], v[6:7] neg_lo:[1,0,0] neg_hi:[1,0,0]
	v_cmp_gt_f32_e32 vcc, 0, v6
	v_and_b32_e32 v23, 0x7fffffff, v39
	v_add_u32_e32 v16, 0xb0, v140
	v_cndmask_b32_e32 v1, v40, v2, vcc
	v_cmp_gt_f32_e32 vcc, 0, v4
	v_ashrrev_i32_e32 v17, 31, v16
	s_waitcnt lgkmcnt(0)
; __device__ __forceinline__ u32x4 pack8(const f32x4& a, const f32x4& b) { u32x4 w; w.x = cvt_pk_bf16(a[0], a[1]); w.y = cvt_pk_bf16(a[2], a[3]); w.z = cvt_pk_bf16(b[0], b[1]); w.w = cvt_pk_bf16(b[2], b[3]); return w; }
;     __device__ __forceinline__ void operator()(const f32x4 (&acc)[2][2][4][2], const Unit& u, int ui, int wr, int wc, int fr, int fq) const {
;     ...
;             for (int m = 0; m < 4; ++m) { const float r = rs[ai][m]; const int row = row0 + ai * HALF + m * 16; bf16_t* rowp = Z + (size_t)row * 2048 + col0; float s1 = 0.f, s2 = 0.f;
; #pragma unroll
;                 for (int bj = 0; bj < 2; ++bj) { const f32x4 v0 = acc[ai][bj][m][0] * r, v1 = acc[ai][bj][m][1] * r;
;                     const f32x2 a = gelu_pk((f32x2){v0[0], v0[1]}), b = gelu_pk((f32x2){v0[2], v0[3]}), c = gelu_pk((f32x2){v1[0], v1[1]}), d = gelu_pk((f32x2){v1[2], v1[3]});
;                     const f32x4 z0 = (f32x4){a.x, a.y, b.x, b.y}, z1 = (f32x4){c.x, c.y, d.x, d.y};
;                     *(u32x4*)(rowp + bj * HALF) = pack8(z0, z1);
;                     s1 += (z0[0] + z0[1]) + (z0[2] + z0[3]) + (z1[0] + z1[1]) + (z1[2] + z1[3]);
;                     s2 += (z0[0] * z0[0] + z0[1] * z0[1]) + (z0[2] * z0[2] + z0[3] * z0[3]) + (z1[0] * z1[0] + z1[1] * z1[1]) + (z1[2] * z1[2] + z1[3] * z1[3]); }
;                 if (u.pn >= 4) { s1 += __shfl_xor(s1, 16); s1 += __shfl_xor(s1, 32); s2 += __shfl_xor(s2, 16); s2 += __shfl_xor(s2, 32);
;                     if (fq == 0) vst[(size_t)row * 16 + (u.pn - 4) * 4 + wc] = (f32x2){s1, s2}; } }
	v_lshlrev_b64 v[18:19], 12, v[16:17]
	v_cndmask_b32_e32 v0, v42, v36, vcc
	v_cmp_gt_f32_e32 vcc, 0, v7
	v_pk_mul_f32 v[6:7], v[20:21], v[20:21]
	v_lshl_add_u64 v[18:19], s[20:21], 0, v[18:19]
	v_cndmask_b32_e32 v3, v41, v3, vcc
	v_cmp_gt_f32_e32 vcc, 0, v5
	v_pk_fma_f32 v[4:5], v[44:45], s[0:1], v[12:13] op_sel_hi:[1,0,0]
	v_pk_mul_f32 v[6:7], v[6:7], s[86:87] op_sel_hi:[1,0]
	v_pk_fma_f32 v[4:5], v[44:45], v[4:5], s[2:3] op_sel_hi:[1,1,0]
	v_exp_f32_e32 v6, v6
	v_exp_f32_e32 v7, v7
	v_pk_fma_f32 v[4:5], v[44:45], v[4:5], s[4:5] op_sel_hi:[1,1,0]
	v_cndmask_b32_e32 v2, v43, v37, vcc
	v_pk_fma_f32 v[4:5], v[44:45], v[4:5], s[88:89] op_sel_hi:[1,1,0]
	v_cmp_gt_f32_e32 vcc, 0, v26
	v_pk_mul_f32 v[4:5], v[44:45], v[4:5]
	v_lshl_add_u64 v[18:19], v[162:163], 1, v[18:19]
	v_pk_mul_f32 v[4:5], v[6:7], v[4:5]
	v_cndmask_b32_e32 v6, v34, v32, vcc
	v_pk_mul_f32 v[40:41], v[20:21], v[4:5]
	v_pk_fma_f32 v[42:43], v[20:21], v[4:5], v[20:21] neg_lo:[1,0,0] neg_hi:[1,0,0]
	v_cmp_gt_f32_e32 vcc, 0, v20
	v_cvt_pk_bf16_f32 v24, v8, v10
	v_cvt_pk_bf16_f32 v25, v9, v11
	v_pk_mul_f32 v[36:37], v[38:39], v[38:39]
	s_nop 0
	v_cndmask_b32_e32 v7, v42, v40, vcc
	v_cmp_gt_f32_e32 vcc, 0, v27
	s_nop 1
	v_cndmask_b32_e32 v20, v35, v33, vcc
	v_cmp_gt_f32_e32 vcc, 0, v28
	v_cvt_pk_bf16_f32 v26, v6, v20
	s_nop 1
	v_cndmask_b32_e32 v5, v30, v22, vcc
	v_and_b32_e32 v22, 0x7fffffff, v38
	v_pk_fma_f32 v[22:23], v[22:23], s[56:57], 1.0 op_sel_hi:[1,0,0]
	v_cvt_pk_bf16_f32 v27, v5, v14
	global_store_dwordx4 v[18:19], v[24:27], off
	v_rcp_f32_e32 v28, v22
	v_rcp_f32_e32 v29, v23
	v_pk_mul_f32 v[24:25], v[36:37], s[86:87] op_sel_hi:[1,0]
	v_cmp_gt_f32_e32 vcc, 0, v21
	v_exp_f32_e32 v24, v24
	v_pk_fma_f32 v[12:13], v[28:29], s[0:1], v[12:13] op_sel_hi:[1,0,0]
	v_exp_f32_e32 v25, v25
	v_pk_fma_f32 v[12:13], v[28:29], v[12:13], s[2:3] op_sel_hi:[1,1,0]
	v_cndmask_b32_e32 v22, v43, v41, vcc
	v_pk_fma_f32 v[12:13], v[28:29], v[12:13], s[4:5] op_sel_hi:[1,1,0]
	v_cmp_gt_f32_e32 vcc, 0, v39
	v_pk_fma_f32 v[12:13], v[28:29], v[12:13], s[88:89] op_sel_hi:[1,1,0]
	s_nop 0
	v_pk_mul_f32 v[12:13], v[28:29], v[12:13]
	s_nop 0
	v_pk_mul_f32 v[12:13], v[24:25], v[12:13]
	s_nop 0
	v_pk_mul_f32 v[24:25], v[38:39], v[12:13]
	v_pk_fma_f32 v[12:13], v[38:39], v[12:13], v[38:39] neg_lo:[1,0,0] neg_hi:[1,0,0]
	s_nop 0
	v_cndmask_b32_e32 v13, v13, v25, vcc
	v_cmp_gt_f32_e32 vcc, 0, v38
	s_nop 1
	v_cndmask_b32_e32 v12, v12, v24, vcc
	s_and_b64 vcc, exec, s[12:13]
	v_cvt_pk_bf16_f32 v24, v0, v2
	v_cvt_pk_bf16_f32 v25, v1, v3
	v_cvt_pk_bf16_f32 v26, v7, v22
	v_cvt_pk_bf16_f32 v27, v12, v13
	global_store_dwordx4 v[18:19], v[24:27], off offset:256
	s_cbranch_vccnz .LBB0_784
	v_mov_b32_e32 v4, v7
	v_mov_b32_e32 v23, v5
	v_pk_add_f32 v[18:19], v[4:5], v[22:23]
	v_pk_mul_f32 v[24:25], v[4:5], v[22:23]
	v_mov_b32_e32 v26, v6
	v_mov_b32_e32 v27, v20
	v_mul_f32_e32 v4, v6, v6
	v_mov_b32_e32 v21, v7
	v_pk_fma_f32 v[26:27], v[26:27], v[26:27], v[4:5] op_sel_hi:[1,1,0]
	v_mul_f32_e32 v4, v12, v12
	v_pk_fma_f32 v[28:29], v[12:13], v[12:13], v[4:5] op_sel_hi:[1,1,0]
	v_mov_b32_e32 v30, v0
	v_mov_b32_e32 v31, v2
	v_mul_f32_e32 v4, v0, v0
	v_pk_add_f32 v[34:35], v[6:7], v[20:21]
	v_pk_mul_f32 v[6:7], v[6:7], v[20:21]
	v_mov_b32_e32 v19, v25
	v_pk_mul_f32 v[24:25], v[10:11], v[10:11]
	v_pk_fma_f32 v[30:31], v[30:31], v[30:31], v[4:5] op_sel_hi:[1,1,0]
	v_mov_b32_e32 v32, v1
	v_mov_b32_e32 v33, v3
	v_mul_f32_e32 v4, v1, v1
	v_mov_b32_e32 v35, v7
	v_pk_mul_f32 v[6:7], v[22:23], v[22:23]
	v_pk_add_f32 v[0:1], v[0:1], v[2:3]
	v_and_b32_e32 v3, 64, v192
	v_pk_fma_f32 v[24:25], v[8:9], v[8:9], v[24:25]
	v_pk_add_f32 v[8:9], v[8:9], v[10:11]
	v_xor_b32_e32 v2, 16, v192
	v_add_u32_e32 v7, 64, v3
	v_pk_fma_f32 v[32:33], v[32:33], v[32:33], v[4:5] op_sel_hi:[1,1,0]
	v_pk_add_f32 v[8:9], v[8:9], v[8:9] op_sel:[0,1] op_sel_hi:[1,0]
	v_cmp_lt_i32_e32 vcc, v2, v7
	v_mul_f32_e32 v36, v14, v14
	v_pk_add_f32 v[24:25], v[24:25], v[24:25] op_sel_hi:[0,1]
	v_cndmask_b32_e32 v2, v192, v2, vcc
	v_mov_b32_e32 v30, v5
	v_mov_b32_e32 v15, v33
	v_mov_b32_e32 v9, v6
	v_pk_add_f32 v[0:1], v[0:1], v[0:1] op_sel:[0,1] op_sel_hi:[1,0]
	v_lshlrev_b32_e32 v10, 2, v2
	v_pk_add_f32 v[2:3], v[30:31], v[14:15]
	v_pk_add_f32 v[4:5], v[34:35], v[8:9]
	v_mov_b32_e32 v26, v12
	v_mov_b32_e32 v24, v13
	v_mov_b32_e32 v1, v36
	v_pk_add_f32 v[2:3], v[4:5], v[2:3]
	v_mov_b32_e32 v147, v29
	v_pk_add_f32 v[4:5], v[26:27], v[24:25]
	v_pk_add_f32 v[0:1], v[18:19], v[0:1]
	v_pk_add_f32 v[2:3], v[2:3], v[146:147]
	v_pk_add_f32 v[0:1], v[0:1], v[4:5]
	v_xor_b32_e32 v4, 32, v192
	v_pk_add_f32 v[0:1], v[0:1], v[2:3]
	ds_bpermute_b32 v2, v10, v0
	ds_bpermute_b32 v3, v10, v1
	v_cmp_lt_i32_e32 vcc, v4, v7
	s_waitcnt lgkmcnt(0)
	v_pk_add_f32 v[0:1], v[0:1], v[2:3]
	v_cndmask_b32_e32 v4, v192, v4, vcc
	v_lshlrev_b32_e32 v4, 2, v4
	v_mov_b32_e32 v2, v0
	s_nop 1
	v_permlane32_swap_b32_e32 v2, v0
	v_mov_b32_e32 v3, v1
	s_nop 1
	v_permlane32_swap_b32_e32 v3, v1
	s_and_saveexec_b64 s[0:1], s[10:11]
	s_cbranch_execz .LBB0_783
	s_waitcnt lgkmcnt(0)
	v_pk_add_f32 v[0:1], v[0:1], v[2:3]
	v_lshlrev_b64 v[2:3], 7, v[16:17]
	v_lshl_add_u64 v[2:3], s[16:17], 0, v[2:3]
	v_lshl_add_u64 v[2:3], s[38:39], 3, v[2:3]
	s_lshl_b32 s88, s44, 3
	v_lshl_add_u64 v[2:3], v[2:3], 0, s[88:89]
	global_store_dwordx2 v[2:3], v[0:1], off

; __device__ __forceinline__ u32x4 pack8(const f32x4& a, const f32x4& b) { u32x4 w; w.x = cvt_pk_bf16(a[0], a[1]); w.y = cvt_pk_bf16(a[2], a[3]); w.z = cvt_pk_bf16(b[0], b[1]); w.w = cvt_pk_bf16(b[2], b[3]); return w; }
;     __device__ __forceinline__ void operator()(const f32x4 (&acc)[2][2][4][2], const Unit& u, int ui, int wr, int wc, int fr, int fq) const {
;     ...
;             for (int m = 0; m < 4; ++m) { const int row = row0 + ai * HALF + m * 16; const size_t off = (size_t)row * 1024 + col0; float q = 0.f;
;                 f32x4 v[2][2];
;                 if (basef) {
; #pragma unroll
;                     for (int bj = 0; bj < 2; ++bj) { v[bj][0] = *(const f32x4*)(basef + off + bj * HALF); v[bj][1] = *(const f32x4*)(basef + off + bj * HALF + 4); }
;                 } else {
; #pragma unroll
;                     for (int bj = 0; bj < 2; ++bj) { const u32x4 raw = *(const u32x4*)(xb + off + bj * HALF);
;                         v[bj][0] = (f32x4){__builtin_bit_cast(float, raw.x << 16), __builtin_bit_cast(float, raw.x & 0xffff0000u), __builtin_bit_cast(float, raw.y << 16), __builtin_bit_cast(float, raw.y & 0xffff0000u)};
;                         v[bj][1] = (f32x4){__builtin_bit_cast(float, raw.z << 16), __builtin_bit_cast(float, raw.z & 0xffff0000u), __builtin_bit_cast(float, raw.w << 16), __builtin_bit_cast(float, raw.w & 0xffff0000u)}; }
;                 }
; #pragma unroll
;                 for (int bj = 0; bj < 2; ++bj) {
;                     f32x4 v0 = v[bj][0] + acc[ai][bj][m][0] * alpha, v1 = v[bj][1] + acc[ai][bj][m][1] * alpha;
;                     if (HAS_BIAS) { v0 += bv[bj][0]; v1 += bv[bj][1]; }
;                     if (outf) { *(f32x4*)(outf + off + bj * HALF) = v0; *(f32x4*)(outf + off + bj * HALF + 4) = v1; }
;                     else *(u32x4*)(xb + off + bj * HALF) = pack8(v0, v1);
;                     q += (v0[0] * v0[0] + v0[1] * v0[1]) + (v0[2] * v0[2] + v0[3] * v0[3]) + (v1[0] * v1[0] + v1[1] * v1[1]) + (v1[2] * v1[2] + v1[3] * v1[3]); }
;                 q += __shfl_xor(q, 16); q += __shfl_xor(q, 32);
;                 if (fq == 0) ssp[(size_t)row * 16 + u.pn * 4 + wc] = q;
.LBB0_1045:
	s_lshl_b32 s0, s11, 8
	v_mov_b32_e32 v143, v147
	v_mov_b32_e32 v140, v162
	s_add_i32 s0, s0, s41
	s_nop 0
	v_add_u32_e32 v142, s0, v140
	s_lshl_b32 s0, s10, 8
	s_or_b32 s0, s0, s42
	v_lshl_add_u32 v140, v143, 3, s0
	v_cmp_eq_u32_e32 vcc, 0, v143
	v_ashrrev_i32_e32 v143, 31, v142
	v_lshlrev_b64 v[166:167], 11, v[142:143]
	v_ashrrev_i32_e32 v141, 31, v140
	v_lshl_add_u64 v[166:167], s[14:15], 0, v[166:167]
	v_lshl_add_u64 v[170:171], v[140:141], 1, v[166:167]
	global_load_dwordx4 v[166:169], v[170:171], off
	s_lshl_b32 s0, s10, 2
	s_ashr_i32 s1, s0, 31
	s_waitcnt vmcnt(0)
	v_lshlrev_b32_e32 v172, 16, v166
	v_and_b32_e32 v173, 0xffff0000, v166
	v_lshlrev_b32_e32 v174, 16, v167
	v_and_b32_e32 v175, 0xffff0000, v167
	v_lshlrev_b32_e32 v176, 16, v168
	v_and_b32_e32 v177, 0xffff0000, v168
	v_lshlrev_b32_e32 v178, 16, v169
	v_and_b32_e32 v179, 0xffff0000, v169
	global_load_dwordx4 v[166:169], v[170:171], off offset:256
	v_pk_add_f32 v[126:127], v[126:127], v[174:175]
	v_pk_add_f32 v[124:125], v[124:125], v[172:173]
	v_pk_add_f32 v[172:173], v[120:121], v[176:177]
	v_cvt_pk_bf16_f32 v120, v124, v125
	v_cvt_pk_bf16_f32 v121, v126, v127
	v_pk_add_f32 v[174:175], v[122:123], v[178:179]
	v_cvt_pk_bf16_f32 v122, v172, v173
	s_waitcnt vmcnt(0)
	v_lshlrev_b32_e32 v180, 16, v166
	v_cvt_pk_bf16_f32 v123, v174, v175
	global_store_dwordx4 v[170:171], v[120:123], off
	v_and_b32_e32 v181, 0xffff0000, v166
	v_lshlrev_b32_e32 v166, 16, v167
	v_mul_f32_e32 v120, v124, v124
	v_mul_f32_e32 v121, v126, v126
	v_fmac_f32_e32 v120, v125, v125
	v_fmac_f32_e32 v121, v127, v127
	v_add_f32_e32 v120, v121, v120
	v_mul_f32_e32 v121, v172, v172
	v_fmac_f32_e32 v121, v173, v173
	v_and_b32_e32 v167, 0xffff0000, v167
	v_lshlrev_b32_e32 v182, 16, v168
	v_and_b32_e32 v183, 0xffff0000, v168
	v_add_f32_e32 v120, v121, v120
	v_mul_f32_e32 v121, v175, v175
	v_lshlrev_b32_e32 v168, 16, v169
	v_and_b32_e32 v169, 0xffff0000, v169
	v_fmac_f32_e32 v121, v174, v174
	v_pk_add_f32 v[118:119], v[118:119], v[166:167]
	v_pk_add_f32 v[116:117], v[116:117], v[180:181]
	v_pk_add_f32 v[122:123], v[112:113], v[182:183]
	v_cvt_pk_bf16_f32 v112, v116, v117
	v_cvt_pk_bf16_f32 v113, v118, v119
	v_add_f32_e32 v124, v121, v120
	v_pk_add_f32 v[120:121], v[114:115], v[168:169]
	v_cvt_pk_bf16_f32 v114, v122, v123
	s_nop 0
	v_cvt_pk_bf16_f32 v115, v120, v121
	global_store_dwordx4 v[170:171], v[112:115], off offset:256
	s_nop 1
	v_mul_f32_e32 v112, v116, v116
	v_mul_f32_e32 v113, v118, v118
	v_fmac_f32_e32 v112, v117, v117
	v_fmac_f32_e32 v113, v119, v119
	v_add_f32_e32 v112, v113, v112
	v_mul_f32_e32 v113, v122, v122
	v_fmac_f32_e32 v113, v123, v123
	v_add_f32_e32 v112, v113, v112
	v_mul_f32_e32 v113, v120, v120
	v_fmac_f32_e32 v113, v121, v121
	v_and_b32_e32 v114, 64, v192
	v_add_f32_e32 v112, v113, v112
	v_xor_b32_e32 v113, 16, v192
	v_add_u32_e32 v115, 64, v114
	v_cmp_lt_i32_e64 s[10:11], v113, v115
	v_add_f32_e32 v112, v124, v112
	s_nop 0
	v_cndmask_b32_e64 v113, v192, v113, s[10:11]
	v_lshlrev_b32_e32 v114, 2, v113
	v_mov_b32_e32 v113, v112
	s_nop 1
	v_permlane16_swap_b32_e32 v113, v112
	s_waitcnt lgkmcnt(0)
	v_add_f32_e32 v112, v112, v113
	v_xor_b32_e32 v113, 32, v192
	v_cmp_lt_i32_e64 s[10:11], v113, v115
	s_nop 1
	v_cndmask_b32_e64 v113, v192, v113, s[10:11]
	v_lshlrev_b32_e32 v115, 2, v113
	v_mov_b32_e32 v113, v112
	s_nop 1
	v_permlane32_swap_b32_e32 v113, v112
	s_and_saveexec_b64 s[2:3], vcc
	s_cbranch_execz .LBB0_1047
	v_lshlrev_b64 v[116:117], 6, v[142:143]
	v_lshl_add_u64 v[116:117], s[16:17], 0, v[116:117]
	v_lshl_add_u64 v[116:117], s[0:1], 2, v[116:117]
	s_lshl_b32 s88, s40, 2
	v_lshl_add_u64 v[116:117], v[116:117], 0, s[88:89]
	s_waitcnt lgkmcnt(0)
	v_add_f32_e32 v112, v112, v113
	global_store_dword v[116:117], v112, off
.LBB0_1047:
	s_or_b64 exec, exec, s[2:3]
	v_add_u32_e32 v112, 16, v142
	s_waitcnt lgkmcnt(0)
	v_ashrrev_i32_e32 v113, 31, v112
	v_lshlrev_b64 v[116:117], 11, v[112:113]
	v_lshl_add_u64 v[116:117], s[14:15], 0, v[116:117]
	v_lshl_add_u64 v[124:125], v[140:141], 1, v[116:117]
	global_load_dwordx4 v[116:119], v[124:125], off
	global_load_dwordx4 v[120:123], v[124:125], off offset:256
	s_waitcnt vmcnt(1)
	v_lshlrev_b32_e32 v126, 16, v116
	v_and_b32_e32 v127, 0xffff0000, v116
	v_lshlrev_b32_e32 v116, 16, v117
	v_and_b32_e32 v117, 0xffff0000, v117
	s_waitcnt vmcnt(0)
	v_lshlrev_b32_e32 v168, 16, v120
	v_and_b32_e32 v169, 0xffff0000, v120
	v_lshlrev_b32_e32 v120, 16, v121
	v_and_b32_e32 v121, 0xffff0000, v121
	v_lshlrev_b32_e32 v166, 16, v118
	v_and_b32_e32 v167, 0xffff0000, v118
	v_lshlrev_b32_e32 v118, 16, v119
	v_and_b32_e32 v119, 0xffff0000, v119
	v_lshlrev_b32_e32 v170, 16, v122
	v_and_b32_e32 v171, 0xffff0000, v122
	v_lshlrev_b32_e32 v122, 16, v123
	v_and_b32_e32 v123, 0xffff0000, v123
	v_pk_add_f32 v[110:111], v[110:111], v[116:117]
	v_pk_add_f32 v[108:109], v[108:109], v[126:127]
	v_pk_add_f32 v[102:103], v[102:103], v[120:121]
	v_pk_add_f32 v[100:101], v[100:101], v[168:169]
	v_pk_add_f32 v[104:105], v[104:105], v[166:167]
	v_pk_add_f32 v[106:107], v[106:107], v[118:119]
	v_pk_add_f32 v[116:117], v[98:99], v[122:123]
	v_pk_add_f32 v[118:119], v[96:97], v[170:171]
	v_mul_f32_e32 v98, v108, v108
	v_mul_f32_e32 v99, v110, v110
	v_mul_f32_e32 v120, v100, v100
	v_mul_f32_e32 v121, v102, v102
	v_cvt_pk_bf16_f32 v96, v108, v109
	v_mul_f32_e32 v108, v104, v104
	v_mul_f32_e32 v122, v118, v118
	v_fmac_f32_e32 v98, v109, v109
	v_fmac_f32_e32 v99, v111, v111
	v_fmac_f32_e32 v120, v101, v101
	v_fmac_f32_e32 v121, v103, v103
	v_cvt_pk_bf16_f32 v97, v110, v111
	v_mul_f32_e32 v110, v107, v107
	v_mul_f32_e32 v123, v116, v116
	v_fmac_f32_e32 v108, v105, v105
	v_fmac_f32_e32 v122, v119, v119
	v_add_f32_e32 v98, v99, v98
	v_add_f32_e32 v99, v121, v120
	v_fmac_f32_e32 v110, v106, v106
	v_fmac_f32_e32 v123, v117, v117
	v_add_f32_e32 v98, v108, v98
	v_add_f32_e32 v99, v122, v99
	v_add_f32_e32 v98, v110, v98
	v_add_f32_e32 v99, v123, v99
	v_add_f32_e32 v108, v98, v99
	v_mov_b32_e32 v109, v108
	s_nop 1
	v_permlane16_swap_b32_e32 v109, v108
	v_cvt_pk_bf16_f32 v98, v104, v105
	v_cvt_pk_bf16_f32 v99, v106, v107
	global_store_dwordx4 v[124:125], v[96:99], off
	s_waitcnt lgkmcnt(0)
	s_nop 0
	v_add_f32_e32 v96, v108, v109
	v_mov_b32_e32 v97, v96
	s_nop 1
	v_permlane32_swap_b32_e32 v97, v96
	v_cvt_pk_bf16_f32 v98, v100, v101
	v_cvt_pk_bf16_f32 v99, v102, v103
	v_cvt_pk_bf16_f32 v100, v118, v119
	v_cvt_pk_bf16_f32 v101, v116, v117
	global_store_dwordx4 v[124:125], v[98:101], off offset:256
	s_and_saveexec_b64 s[2:3], vcc
	s_cbranch_execz .LBB0_1049
	v_lshlrev_b64 v[98:99], 6, v[112:113]
	v_lshl_add_u64 v[98:99], s[16:17], 0, v[98:99]
	v_lshl_add_u64 v[98:99], s[0:1], 2, v[98:99]
	s_lshl_b32 s88, s40, 2
	v_lshl_add_u64 v[98:99], v[98:99], 0, s[88:89]
	s_waitcnt lgkmcnt(0)
	v_add_f32_e32 v96, v96, v97
	global_store_dword v[98:99], v96, off
; __device__ __forceinline__ u32x4 pack8(const f32x4& a, const f32x4& b) { u32x4 w; w.x = cvt_pk_bf16(a[0], a[1]); w.y = cvt_pk_bf16(a[2], a[3]); w.z = cvt_pk_bf16(b[0], b[1]); w.w = cvt_pk_bf16(b[2], b[3]); return w; }
;     __device__ __forceinline__ void operator()(const f32x4 (&acc)[2][2][4][2], const Unit& u, int ui, int wr, int wc, int fr, int fq) const {
;     ...
;             for (int m = 0; m < 4; ++m) { const int row = row0 + ai * HALF + m * 16; const size_t off = (size_t)row * 1024 + col0; float q = 0.f;
;                 f32x4 v[2][2];
;                 if (basef) {
; #pragma unroll
;                     for (int bj = 0; bj < 2; ++bj) { v[bj][0] = *(const f32x4*)(basef + off + bj * HALF); v[bj][1] = *(const f32x4*)(basef + off + bj * HALF + 4); }
;                 } else {
; #pragma unroll
;                     for (int bj = 0; bj < 2; ++bj) { const u32x4 raw = *(const u32x4*)(xb + off + bj * HALF);
;                         v[bj][0] = (f32x4){__builtin_bit_cast(float, raw.x << 16), __builtin_bit_cast(float, raw.x & 0xffff0000u), __builtin_bit_cast(float, raw.y << 16), __builtin_bit_cast(float, raw.y & 0xffff0000u)};
;                         v[bj][1] = (f32x4){__builtin_bit_cast(float, raw.z << 16), __builtin_bit_cast(float, raw.z & 0xffff0000u), __builtin_bit_cast(float, raw.w << 16), __builtin_bit_cast(float, raw.w & 0xffff0000u)}; }
;                 }
; #pragma unroll
;                 for (int bj = 0; bj < 2; ++bj) {
;                     f32x4 v0 = v[bj][0] + acc[ai][bj][m][0] * alpha, v1 = v[bj][1] + acc[ai][bj][m][1] * alpha;
;                     if (HAS_BIAS) { v0 += bv[bj][0]; v1 += bv[bj][1]; }
;                     if (outf) { *(f32x4*)(outf + off + bj * HALF) = v0; *(f32x4*)(outf + off + bj * HALF + 4) = v1; }
;                     else *(u32x4*)(xb + off + bj * HALF) = pack8(v0, v1);
;                     q += (v0[0] * v0[0] + v0[1] * v0[1]) + (v0[2] * v0[2] + v0[3] * v0[3]) + (v1[0] * v1[0] + v1[1] * v1[1]) + (v1[2] * v1[2] + v1[3] * v1[3]); }
;                 q += __shfl_xor(q, 16); q += __shfl_xor(q, 32);
;                 if (fq == 0) ssp[(size_t)row * 16 + u.pn * 4 + wc] = q;
.LBB0_1049:
	s_or_b64 exec, exec, s[2:3]
	v_add_u32_e32 v96, 32, v142
	s_waitcnt lgkmcnt(0)
	v_ashrrev_i32_e32 v97, 31, v96
	v_lshlrev_b64 v[98:99], 11, v[96:97]
	v_lshl_add_u64 v[98:99], s[14:15], 0, v[98:99]
	v_lshl_add_u64 v[106:107], v[140:141], 1, v[98:99]
	global_load_dwordx4 v[98:101], v[106:107], off
	global_load_dwordx4 v[102:105], v[106:107], off offset:256
	s_waitcnt vmcnt(1)
	v_lshlrev_b32_e32 v108, 16, v98
	v_and_b32_e32 v109, 0xffff0000, v98
	v_lshlrev_b32_e32 v98, 16, v99
	v_and_b32_e32 v99, 0xffff0000, v99
	s_waitcnt vmcnt(0)
	v_lshlrev_b32_e32 v112, 16, v102
	v_and_b32_e32 v113, 0xffff0000, v102
	v_lshlrev_b32_e32 v102, 16, v103
	v_and_b32_e32 v103, 0xffff0000, v103
	v_lshlrev_b32_e32 v110, 16, v100
	v_and_b32_e32 v111, 0xffff0000, v100
	v_lshlrev_b32_e32 v100, 16, v101
	v_and_b32_e32 v101, 0xffff0000, v101
	v_lshlrev_b32_e32 v116, 16, v104
	v_and_b32_e32 v117, 0xffff0000, v104
	v_lshlrev_b32_e32 v104, 16, v105
	v_and_b32_e32 v105, 0xffff0000, v105
	v_pk_add_f32 v[94:95], v[94:95], v[98:99]
	v_pk_add_f32 v[92:93], v[92:93], v[108:109]
	v_pk_add_f32 v[86:87], v[86:87], v[102:103]
	v_pk_add_f32 v[84:85], v[84:85], v[112:113]
	v_pk_add_f32 v[88:89], v[88:89], v[110:111]
	v_pk_add_f32 v[90:91], v[90:91], v[100:101]
	v_pk_add_f32 v[98:99], v[82:83], v[104:105]
	v_pk_add_f32 v[100:101], v[80:81], v[116:117]
	v_mul_f32_e32 v82, v92, v92
	v_mul_f32_e32 v83, v94, v94
	v_mul_f32_e32 v102, v84, v84
	v_mul_f32_e32 v103, v86, v86
	v_cvt_pk_bf16_f32 v80, v92, v93
	v_mul_f32_e32 v92, v88, v88
	v_mul_f32_e32 v104, v100, v100
	v_fmac_f32_e32 v82, v93, v93
	v_fmac_f32_e32 v83, v95, v95
	v_fmac_f32_e32 v102, v85, v85
	v_fmac_f32_e32 v103, v87, v87
	v_cvt_pk_bf16_f32 v81, v94, v95
	v_mul_f32_e32 v94, v91, v91
	v_mul_f32_e32 v105, v98, v98
	v_fmac_f32_e32 v92, v89, v89
	v_fmac_f32_e32 v104, v101, v101
	v_add_f32_e32 v82, v83, v82
	v_add_f32_e32 v83, v103, v102
	v_fmac_f32_e32 v94, v90, v90
	v_fmac_f32_e32 v105, v99, v99
	v_add_f32_e32 v82, v92, v82
	v_add_f32_e32 v83, v104, v83
	v_add_f32_e32 v82, v94, v82
	v_add_f32_e32 v83, v105, v83
	v_add_f32_e32 v92, v82, v83
	v_mov_b32_e32 v93, v92
	s_nop 1
	v_permlane16_swap_b32_e32 v93, v92
	v_cvt_pk_bf16_f32 v82, v88, v89
	v_cvt_pk_bf16_f32 v83, v90, v91
	global_store_dwordx4 v[106:107], v[80:83], off
	s_waitcnt lgkmcnt(0)
	s_nop 0
	v_add_f32_e32 v80, v92, v93
	v_mov_b32_e32 v81, v80
	s_nop 1
	v_permlane32_swap_b32_e32 v81, v80
	v_cvt_pk_bf16_f32 v82, v84, v85
	v_cvt_pk_bf16_f32 v83, v86, v87
	v_cvt_pk_bf16_f32 v84, v100, v101
	v_cvt_pk_bf16_f32 v85, v98, v99
	global_store_dwordx4 v[106:107], v[82:85], off offset:256
	s_and_saveexec_b64 s[2:3], vcc
	s_cbranch_execz .LBB0_1051
	v_lshlrev_b64 v[82:83], 6, v[96:97]
	v_lshl_add_u64 v[82:83], s[16:17], 0, v[82:83]
	v_lshl_add_u64 v[82:83], s[0:1], 2, v[82:83]
	s_lshl_b32 s88, s40, 2
	v_lshl_add_u64 v[82:83], v[82:83], 0, s[88:89]
	s_waitcnt lgkmcnt(0)
	v_add_f32_e32 v80, v80, v81
	global_store_dword v[82:83], v80, off
.LBB0_1051:
	s_or_b64 exec, exec, s[2:3]
	v_add_u32_e32 v80, 48, v142
	s_waitcnt lgkmcnt(0)
	v_ashrrev_i32_e32 v81, 31, v80
	v_lshlrev_b64 v[82:83], 11, v[80:81]
	v_lshl_add_u64 v[82:83], s[14:15], 0, v[82:83]
	v_lshl_add_u64 v[90:91], v[140:141], 1, v[82:83]
	global_load_dwordx4 v[82:85], v[90:91], off
	global_load_dwordx4 v[86:89], v[90:91], off offset:256
	s_waitcnt vmcnt(1)
	v_lshlrev_b32_e32 v92, 16, v82
	v_and_b32_e32 v93, 0xffff0000, v82
	v_lshlrev_b32_e32 v82, 16, v83
	v_and_b32_e32 v83, 0xffff0000, v83
	s_waitcnt vmcnt(0)
	v_lshlrev_b32_e32 v96, 16, v86
	v_and_b32_e32 v97, 0xffff0000, v86
	v_lshlrev_b32_e32 v86, 16, v87
	v_and_b32_e32 v87, 0xffff0000, v87
	v_lshlrev_b32_e32 v94, 16, v84
	v_and_b32_e32 v95, 0xffff0000, v84
	v_lshlrev_b32_e32 v84, 16, v85
	v_and_b32_e32 v85, 0xffff0000, v85
	v_lshlrev_b32_e32 v98, 16, v88
	v_and_b32_e32 v99, 0xffff0000, v88
	v_lshlrev_b32_e32 v88, 16, v89
	v_and_b32_e32 v89, 0xffff0000, v89
	v_pk_add_f32 v[78:79], v[78:79], v[82:83]
	v_pk_add_f32 v[76:77], v[76:77], v[92:93]
	v_pk_add_f32 v[70:71], v[70:71], v[86:87]
	v_pk_add_f32 v[68:69], v[68:69], v[96:97]
	v_pk_add_f32 v[72:73], v[72:73], v[94:95]
	v_pk_add_f32 v[74:75], v[74:75], v[84:85]
	v_pk_add_f32 v[82:83], v[66:67], v[88:89]
	v_pk_add_f32 v[84:85], v[64:65], v[98:99]
	v_mul_f32_e32 v66, v76, v76
	v_mul_f32_e32 v67, v78, v78
	v_mul_f32_e32 v86, v68, v68
	v_mul_f32_e32 v87, v70, v70
	v_cvt_pk_bf16_f32 v64, v76, v77
	v_mul_f32_e32 v76, v72, v72
	v_mul_f32_e32 v88, v84, v84
	v_fmac_f32_e32 v66, v77, v77
	v_fmac_f32_e32 v67, v79, v79
	v_fmac_f32_e32 v86, v69, v69
	v_fmac_f32_e32 v87, v71, v71
	v_cvt_pk_bf16_f32 v65, v78, v79
	v_mul_f32_e32 v78, v75, v75
	v_mul_f32_e32 v89, v82, v82
	v_fmac_f32_e32 v76, v73, v73
	v_fmac_f32_e32 v88, v85, v85
	v_add_f32_e32 v66, v67, v66
	v_add_f32_e32 v67, v87, v86
	v_fmac_f32_e32 v78, v74, v74
	v_fmac_f32_e32 v89, v83, v83
	v_add_f32_e32 v66, v76, v66
	v_add_f32_e32 v67, v88, v67
	v_add_f32_e32 v66, v78, v66
	v_add_f32_e32 v67, v89, v67
	v_add_f32_e32 v76, v66, v67
	v_mov_b32_e32 v77, v76
	s_nop 1
	v_permlane16_swap_b32_e32 v77, v76
	v_cvt_pk_bf16_f32 v66, v72, v73
	v_cvt_pk_bf16_f32 v67, v74, v75
	global_store_dwordx4 v[90:91], v[64:67], off
	s_waitcnt lgkmcnt(0)
	s_nop 0
	v_add_f32_e32 v64, v76, v77
	v_mov_b32_e32 v65, v64
	s_nop 1
	v_permlane32_swap_b32_e32 v65, v64
	v_cvt_pk_bf16_f32 v66, v68, v69
	v_cvt_pk_bf16_f32 v67, v70, v71
	v_cvt_pk_bf16_f32 v68, v84, v85
	v_cvt_pk_bf16_f32 v69, v82, v83
	global_store_dwordx4 v[90:91], v[66:69], off offset:256
	s_and_saveexec_b64 s[2:3], vcc
	s_cbranch_execz .LBB0_1053
	v_lshlrev_b64 v[66:67], 6, v[80:81]
	v_lshl_add_u64 v[66:67], s[16:17], 0, v[66:67]
	v_lshl_add_u64 v[66:67], s[0:1], 2, v[66:67]
	s_lshl_b32 s88, s40, 2
	v_lshl_add_u64 v[66:67], v[66:67], 0, s[88:89]
	s_waitcnt lgkmcnt(0)
	v_add_f32_e32 v64, v64, v65
	global_store_dword v[66:67], v64, off
; __device__ __forceinline__ u32x4 pack8(const f32x4& a, const f32x4& b) { u32x4 w; w.x = cvt_pk_bf16(a[0], a[1]); w.y = cvt_pk_bf16(a[2], a[3]); w.z = cvt_pk_bf16(b[0], b[1]); w.w = cvt_pk_bf16(b[2], b[3]); return w; }
;     __device__ __forceinline__ void operator()(const f32x4 (&acc)[2][2][4][2], const Unit& u, int ui, int wr, int wc, int fr, int fq) const {
;     ...
;             for (int m = 0; m < 4; ++m) { const int row = row0 + ai * HALF + m * 16; const size_t off = (size_t)row * 1024 + col0; float q = 0.f;
;                 f32x4 v[2][2];
;                 if (basef) {
; #pragma unroll
;                     for (int bj = 0; bj < 2; ++bj) { v[bj][0] = *(const f32x4*)(basef + off + bj * HALF); v[bj][1] = *(const f32x4*)(basef + off + bj * HALF + 4); }
;                 } else {
; #pragma unroll
;                     for (int bj = 0; bj < 2; ++bj) { const u32x4 raw = *(const u32x4*)(xb + off + bj * HALF);
;                         v[bj][0] = (f32x4){__builtin_bit_cast(float, raw.x << 16), __builtin_bit_cast(float, raw.x & 0xffff0000u), __builtin_bit_cast(float, raw.y << 16), __builtin_bit_cast(float, raw.y & 0xffff0000u)};
;                         v[bj][1] = (f32x4){__builtin_bit_cast(float, raw.z << 16), __builtin_bit_cast(float, raw.z & 0xffff0000u), __builtin_bit_cast(float, raw.w << 16), __builtin_bit_cast(float, raw.w & 0xffff0000u)}; }
;                 }
; #pragma unroll
;                 for (int bj = 0; bj < 2; ++bj) {
;                     f32x4 v0 = v[bj][0] + acc[ai][bj][m][0] * alpha, v1 = v[bj][1] + acc[ai][bj][m][1] * alpha;
;                     if (HAS_BIAS) { v0 += bv[bj][0]; v1 += bv[bj][1]; }
;                     if (outf) { *(f32x4*)(outf + off + bj * HALF) = v0; *(f32x4*)(outf + off + bj * HALF + 4) = v1; }
;                     else *(u32x4*)(xb + off + bj * HALF) = pack8(v0, v1);
;                     q += (v0[0] * v0[0] + v0[1] * v0[1]) + (v0[2] * v0[2] + v0[3] * v0[3]) + (v1[0] * v1[0] + v1[1] * v1[1]) + (v1[2] * v1[2] + v1[3] * v1[3]); }
;                 q += __shfl_xor(q, 16); q += __shfl_xor(q, 32);
;                 if (fq == 0) ssp[(size_t)row * 16 + u.pn * 4 + wc] = q;
.LBB0_1053:
	s_or_b64 exec, exec, s[2:3]
	v_add_u32_e32 v64, 0x80, v142
	s_waitcnt lgkmcnt(0)
	v_ashrrev_i32_e32 v65, 31, v64
	v_lshlrev_b64 v[66:67], 11, v[64:65]
	v_lshl_add_u64 v[66:67], s[14:15], 0, v[66:67]
	v_lshl_add_u64 v[74:75], v[140:141], 1, v[66:67]
	global_load_dwordx4 v[66:69], v[74:75], off
	global_load_dwordx4 v[70:73], v[74:75], off offset:256
	s_waitcnt vmcnt(1)
	v_lshlrev_b32_e32 v76, 16, v66
	v_and_b32_e32 v77, 0xffff0000, v66
	v_lshlrev_b32_e32 v66, 16, v67
	v_and_b32_e32 v67, 0xffff0000, v67
	s_waitcnt vmcnt(0)
	v_lshlrev_b32_e32 v80, 16, v70
	v_and_b32_e32 v81, 0xffff0000, v70
	v_lshlrev_b32_e32 v70, 16, v71
	v_and_b32_e32 v71, 0xffff0000, v71
	v_lshlrev_b32_e32 v78, 16, v68
	v_and_b32_e32 v79, 0xffff0000, v68
	v_lshlrev_b32_e32 v68, 16, v69
	v_and_b32_e32 v69, 0xffff0000, v69
	v_lshlrev_b32_e32 v82, 16, v72
	v_and_b32_e32 v83, 0xffff0000, v72
	v_lshlrev_b32_e32 v72, 16, v73
	v_and_b32_e32 v73, 0xffff0000, v73
	v_pk_add_f32 v[62:63], v[62:63], v[66:67]
	v_pk_add_f32 v[60:61], v[60:61], v[76:77]
	v_pk_add_f32 v[54:55], v[54:55], v[70:71]
	v_pk_add_f32 v[52:53], v[52:53], v[80:81]
	v_pk_add_f32 v[56:57], v[56:57], v[78:79]
	v_pk_add_f32 v[58:59], v[58:59], v[68:69]
	v_pk_add_f32 v[66:67], v[50:51], v[72:73]
	v_pk_add_f32 v[68:69], v[48:49], v[82:83]
	v_mul_f32_e32 v50, v60, v60
	v_mul_f32_e32 v51, v62, v62
	v_mul_f32_e32 v70, v52, v52
	v_mul_f32_e32 v71, v54, v54
	v_cvt_pk_bf16_f32 v48, v60, v61
	v_mul_f32_e32 v60, v56, v56
	v_mul_f32_e32 v72, v68, v68
	v_fmac_f32_e32 v50, v61, v61
	v_fmac_f32_e32 v51, v63, v63
	v_fmac_f32_e32 v70, v53, v53
	v_fmac_f32_e32 v71, v55, v55
	v_cvt_pk_bf16_f32 v49, v62, v63
	v_mul_f32_e32 v62, v59, v59
	v_mul_f32_e32 v73, v66, v66
	v_fmac_f32_e32 v60, v57, v57
	v_fmac_f32_e32 v72, v69, v69
	v_add_f32_e32 v50, v51, v50
	v_add_f32_e32 v51, v71, v70
	v_fmac_f32_e32 v62, v58, v58
	v_fmac_f32_e32 v73, v67, v67
	v_add_f32_e32 v50, v60, v50
	v_add_f32_e32 v51, v72, v51
	v_add_f32_e32 v50, v62, v50
	v_add_f32_e32 v51, v73, v51
	v_add_f32_e32 v60, v50, v51
	v_mov_b32_e32 v61, v60
	s_nop 1
	v_permlane16_swap_b32_e32 v61, v60
	v_cvt_pk_bf16_f32 v50, v56, v57
	v_cvt_pk_bf16_f32 v51, v58, v59
	global_store_dwordx4 v[74:75], v[48:51], off
	s_waitcnt lgkmcnt(0)
	s_nop 0
	v_add_f32_e32 v48, v60, v61
	v_mov_b32_e32 v49, v48
	s_nop 1
	v_permlane32_swap_b32_e32 v49, v48
	v_cvt_pk_bf16_f32 v50, v52, v53
	v_cvt_pk_bf16_f32 v51, v54, v55
	v_cvt_pk_bf16_f32 v52, v68, v69
	v_cvt_pk_bf16_f32 v53, v66, v67
	global_store_dwordx4 v[74:75], v[50:53], off offset:256
	s_and_saveexec_b64 s[2:3], vcc
	s_cbranch_execz .LBB0_1055
	v_lshlrev_b64 v[50:51], 6, v[64:65]
	v_lshl_add_u64 v[50:51], s[16:17], 0, v[50:51]
	v_lshl_add_u64 v[50:51], s[0:1], 2, v[50:51]
	s_lshl_b32 s88, s40, 2
	v_lshl_add_u64 v[50:51], v[50:51], 0, s[88:89]
	s_waitcnt lgkmcnt(0)
	v_add_f32_e32 v48, v48, v49
	global_store_dword v[50:51], v48, off
.LBB0_1055:
	s_or_b64 exec, exec, s[2:3]
	v_add_u32_e32 v48, 0x90, v142
	s_waitcnt lgkmcnt(0)
	v_ashrrev_i32_e32 v49, 31, v48
	v_lshlrev_b64 v[50:51], 11, v[48:49]
	v_lshl_add_u64 v[50:51], s[14:15], 0, v[50:51]
	v_lshl_add_u64 v[58:59], v[140:141], 1, v[50:51]
	global_load_dwordx4 v[50:53], v[58:59], off
	global_load_dwordx4 v[54:57], v[58:59], off offset:256
	s_waitcnt vmcnt(1)
	v_lshlrev_b32_e32 v60, 16, v50
	v_and_b32_e32 v61, 0xffff0000, v50
	v_lshlrev_b32_e32 v50, 16, v51
	v_and_b32_e32 v51, 0xffff0000, v51
	s_waitcnt vmcnt(0)
	v_lshlrev_b32_e32 v64, 16, v54
	v_and_b32_e32 v65, 0xffff0000, v54
	v_lshlrev_b32_e32 v54, 16, v55
	v_and_b32_e32 v55, 0xffff0000, v55
	v_lshlrev_b32_e32 v62, 16, v52
	v_and_b32_e32 v63, 0xffff0000, v52
	v_lshlrev_b32_e32 v52, 16, v53
	v_and_b32_e32 v53, 0xffff0000, v53
	v_lshlrev_b32_e32 v66, 16, v56
	v_and_b32_e32 v67, 0xffff0000, v56
	v_lshlrev_b32_e32 v56, 16, v57
	v_and_b32_e32 v57, 0xffff0000, v57
	v_pk_add_f32 v[46:47], v[46:47], v[50:51]
	v_pk_add_f32 v[44:45], v[44:45], v[60:61]
	v_pk_add_f32 v[38:39], v[38:39], v[54:55]
	v_pk_add_f32 v[36:37], v[36:37], v[64:65]
	v_pk_add_f32 v[40:41], v[40:41], v[62:63]
	v_pk_add_f32 v[42:43], v[42:43], v[52:53]
	v_pk_add_f32 v[50:51], v[34:35], v[56:57]
	v_pk_add_f32 v[52:53], v[32:33], v[66:67]
	v_mul_f32_e32 v34, v44, v44
	v_mul_f32_e32 v35, v46, v46
	v_mul_f32_e32 v54, v36, v36
	v_mul_f32_e32 v55, v38, v38
	v_cvt_pk_bf16_f32 v32, v44, v45
	v_mul_f32_e32 v44, v40, v40
	v_mul_f32_e32 v56, v52, v52
	v_fmac_f32_e32 v34, v45, v45
	v_fmac_f32_e32 v35, v47, v47
	v_fmac_f32_e32 v54, v37, v37
	v_fmac_f32_e32 v55, v39, v39
	v_cvt_pk_bf16_f32 v33, v46, v47
	v_mul_f32_e32 v46, v43, v43
	v_mul_f32_e32 v57, v50, v50
	v_fmac_f32_e32 v44, v41, v41
	v_fmac_f32_e32 v56, v53, v53
	v_add_f32_e32 v34, v35, v34
	v_add_f32_e32 v35, v55, v54
	v_fmac_f32_e32 v46, v42, v42
	v_fmac_f32_e32 v57, v51, v51
	v_add_f32_e32 v34, v44, v34
	v_add_f32_e32 v35, v56, v35
	v_add_f32_e32 v34, v46, v34
	v_add_f32_e32 v35, v57, v35
	v_add_f32_e32 v44, v34, v35
	v_mov_b32_e32 v45, v44
	s_nop 1
	v_permlane16_swap_b32_e32 v45, v44
	v_cvt_pk_bf16_f32 v34, v40, v41
	v_cvt_pk_bf16_f32 v35, v42, v43
	global_store_dwordx4 v[58:59], v[32:35], off
	s_waitcnt lgkmcnt(0)
	s_nop 0
	v_add_f32_e32 v32, v44, v45
	v_mov_b32_e32 v33, v32
	s_nop 1
	v_permlane32_swap_b32_e32 v33, v32
	v_cvt_pk_bf16_f32 v34, v36, v37
	v_cvt_pk_bf16_f32 v35, v38, v39
	v_cvt_pk_bf16_f32 v36, v52, v53
	v_cvt_pk_bf16_f32 v37, v50, v51
	global_store_dwordx4 v[58:59], v[34:37], off offset:256
	s_and_saveexec_b64 s[2:3], vcc
	s_cbranch_execz .LBB0_1057
	v_lshlrev_b64 v[34:35], 6, v[48:49]
	v_lshl_add_u64 v[34:35], s[16:17], 0, v[34:35]
	v_lshl_add_u64 v[34:35], s[0:1], 2, v[34:35]
	s_lshl_b32 s88, s40, 2
	v_lshl_add_u64 v[34:35], v[34:35], 0, s[88:89]
	s_waitcnt lgkmcnt(0)
	v_add_f32_e32 v32, v32, v33
	global_store_dword v[34:35], v32, off
; __device__ __forceinline__ u32x4 pack8(const f32x4& a, const f32x4& b) { u32x4 w; w.x = cvt_pk_bf16(a[0], a[1]); w.y = cvt_pk_bf16(a[2], a[3]); w.z = cvt_pk_bf16(b[0], b[1]); w.w = cvt_pk_bf16(b[2], b[3]); return w; }
;     __device__ __forceinline__ void operator()(const f32x4 (&acc)[2][2][4][2], const Unit& u, int ui, int wr, int wc, int fr, int fq) const {
;     ...
;             for (int m = 0; m < 4; ++m) { const int row = row0 + ai * HALF + m * 16; const size_t off = (size_t)row * 1024 + col0; float q = 0.f;
;                 f32x4 v[2][2];
;                 if (basef) {
; #pragma unroll
;                     for (int bj = 0; bj < 2; ++bj) { v[bj][0] = *(const f32x4*)(basef + off + bj * HALF); v[bj][1] = *(const f32x4*)(basef + off + bj * HALF + 4); }
;                 } else {
; #pragma unroll
;                     for (int bj = 0; bj < 2; ++bj) { const u32x4 raw = *(const u32x4*)(xb + off + bj * HALF);
;                         v[bj][0] = (f32x4){__builtin_bit_cast(float, raw.x << 16), __builtin_bit_cast(float, raw.x & 0xffff0000u), __builtin_bit_cast(float, raw.y << 16), __builtin_bit_cast(float, raw.y & 0xffff0000u)};
;                         v[bj][1] = (f32x4){__builtin_bit_cast(float, raw.z << 16), __builtin_bit_cast(float, raw.z & 0xffff0000u), __builtin_bit_cast(float, raw.w << 16), __builtin_bit_cast(float, raw.w & 0xffff0000u)}; }
;                 }
; #pragma unroll
;                 for (int bj = 0; bj < 2; ++bj) {
;                     f32x4 v0 = v[bj][0] + acc[ai][bj][m][0] * alpha, v1 = v[bj][1] + acc[ai][bj][m][1] * alpha;
;                     if (HAS_BIAS) { v0 += bv[bj][0]; v1 += bv[bj][1]; }
;                     if (outf) { *(f32x4*)(outf + off + bj * HALF) = v0; *(f32x4*)(outf + off + bj * HALF + 4) = v1; }
;                     else *(u32x4*)(xb + off + bj * HALF) = pack8(v0, v1);
;                     q += (v0[0] * v0[0] + v0[1] * v0[1]) + (v0[2] * v0[2] + v0[3] * v0[3]) + (v1[0] * v1[0] + v1[1] * v1[1]) + (v1[2] * v1[2] + v1[3] * v1[3]); }
;                 q += __shfl_xor(q, 16); q += __shfl_xor(q, 32);
;                 if (fq == 0) ssp[(size_t)row * 16 + u.pn * 4 + wc] = q;
.LBB0_1057:
	s_or_b64 exec, exec, s[2:3]
	v_add_u32_e32 v32, 0xa0, v142
	s_waitcnt lgkmcnt(0)
	v_ashrrev_i32_e32 v33, 31, v32
	v_lshlrev_b64 v[34:35], 11, v[32:33]
	v_lshl_add_u64 v[34:35], s[14:15], 0, v[34:35]
	v_lshl_add_u64 v[42:43], v[140:141], 1, v[34:35]
	global_load_dwordx4 v[34:37], v[42:43], off
	global_load_dwordx4 v[38:41], v[42:43], off offset:256
	s_waitcnt vmcnt(1)
	v_lshlrev_b32_e32 v44, 16, v34
	v_and_b32_e32 v45, 0xffff0000, v34
	v_lshlrev_b32_e32 v34, 16, v35
	v_and_b32_e32 v35, 0xffff0000, v35
	s_waitcnt vmcnt(0)
	v_lshlrev_b32_e32 v48, 16, v38
	v_and_b32_e32 v49, 0xffff0000, v38
	v_lshlrev_b32_e32 v38, 16, v39
	v_and_b32_e32 v39, 0xffff0000, v39
	v_lshlrev_b32_e32 v46, 16, v36
	v_and_b32_e32 v47, 0xffff0000, v36
	v_lshlrev_b32_e32 v36, 16, v37
	v_and_b32_e32 v37, 0xffff0000, v37
	v_lshlrev_b32_e32 v50, 16, v40
	v_and_b32_e32 v51, 0xffff0000, v40
	v_lshlrev_b32_e32 v40, 16, v41
	v_and_b32_e32 v41, 0xffff0000, v41
	v_pk_add_f32 v[30:31], v[30:31], v[34:35]
	v_pk_add_f32 v[28:29], v[28:29], v[44:45]
	v_pk_add_f32 v[22:23], v[22:23], v[38:39]
	v_pk_add_f32 v[20:21], v[20:21], v[48:49]
	v_pk_add_f32 v[24:25], v[24:25], v[46:47]
	v_pk_add_f32 v[26:27], v[26:27], v[36:37]
	v_pk_add_f32 v[34:35], v[18:19], v[40:41]
	v_pk_add_f32 v[36:37], v[16:17], v[50:51]
	v_mul_f32_e32 v18, v28, v28
	v_mul_f32_e32 v19, v30, v30
	v_mul_f32_e32 v38, v20, v20
	v_mul_f32_e32 v39, v22, v22
	v_cvt_pk_bf16_f32 v16, v28, v29
	v_mul_f32_e32 v28, v24, v24
	v_mul_f32_e32 v40, v36, v36
	v_fmac_f32_e32 v18, v29, v29
	v_fmac_f32_e32 v19, v31, v31
	v_fmac_f32_e32 v38, v21, v21
	v_fmac_f32_e32 v39, v23, v23
	v_cvt_pk_bf16_f32 v17, v30, v31
	v_mul_f32_e32 v30, v27, v27
	v_mul_f32_e32 v41, v34, v34
	v_fmac_f32_e32 v28, v25, v25
	v_fmac_f32_e32 v40, v37, v37
	v_add_f32_e32 v18, v19, v18
	v_add_f32_e32 v19, v39, v38
	v_fmac_f32_e32 v30, v26, v26
	v_fmac_f32_e32 v41, v35, v35
	v_add_f32_e32 v18, v28, v18
	v_add_f32_e32 v19, v40, v19
	v_add_f32_e32 v18, v30, v18
	v_add_f32_e32 v19, v41, v19
	v_add_f32_e32 v28, v18, v19
	v_mov_b32_e32 v29, v28
	s_nop 1
	v_permlane16_swap_b32_e32 v29, v28
	v_cvt_pk_bf16_f32 v18, v24, v25
	v_cvt_pk_bf16_f32 v19, v26, v27
	global_store_dwordx4 v[42:43], v[16:19], off
	s_waitcnt lgkmcnt(0)
	s_nop 0
	v_add_f32_e32 v16, v28, v29
	v_mov_b32_e32 v17, v16
	s_nop 1
	v_permlane32_swap_b32_e32 v17, v16
	v_cvt_pk_bf16_f32 v18, v20, v21
	v_cvt_pk_bf16_f32 v19, v22, v23
	v_cvt_pk_bf16_f32 v20, v36, v37
	v_cvt_pk_bf16_f32 v21, v34, v35
	global_store_dwordx4 v[42:43], v[18:21], off offset:256
	s_and_saveexec_b64 s[2:3], vcc
	s_cbranch_execz .LBB0_1059
	v_lshlrev_b64 v[18:19], 6, v[32:33]
	v_lshl_add_u64 v[18:19], s[16:17], 0, v[18:19]
	v_lshl_add_u64 v[18:19], s[0:1], 2, v[18:19]
	s_lshl_b32 s88, s40, 2
	v_lshl_add_u64 v[18:19], v[18:19], 0, s[88:89]
	s_waitcnt lgkmcnt(0)
	v_add_f32_e32 v16, v16, v17
	global_store_dword v[18:19], v16, off
.LBB0_1059:
	s_or_b64 exec, exec, s[2:3]
	v_add_u32_e32 v16, 0xb0, v142
	s_waitcnt lgkmcnt(0)
	v_ashrrev_i32_e32 v17, 31, v16
	v_lshlrev_b64 v[18:19], 11, v[16:17]
	v_lshl_add_u64 v[18:19], s[14:15], 0, v[18:19]
	v_lshl_add_u64 v[26:27], v[140:141], 1, v[18:19]
	global_load_dwordx4 v[18:21], v[26:27], off
	global_load_dwordx4 v[22:25], v[26:27], off offset:256
	s_waitcnt vmcnt(1)
	v_lshlrev_b32_e32 v28, 16, v18
	v_and_b32_e32 v29, 0xffff0000, v18
	v_lshlrev_b32_e32 v18, 16, v19
	v_and_b32_e32 v19, 0xffff0000, v19
	s_waitcnt vmcnt(0)
	v_lshlrev_b32_e32 v32, 16, v22
	v_and_b32_e32 v33, 0xffff0000, v22
	v_lshlrev_b32_e32 v22, 16, v23
	v_and_b32_e32 v23, 0xffff0000, v23
	v_lshlrev_b32_e32 v30, 16, v20
	v_and_b32_e32 v31, 0xffff0000, v20
	v_lshlrev_b32_e32 v20, 16, v21
	v_and_b32_e32 v21, 0xffff0000, v21
	v_lshlrev_b32_e32 v34, 16, v24
	v_and_b32_e32 v35, 0xffff0000, v24
	v_lshlrev_b32_e32 v24, 16, v25
	v_and_b32_e32 v25, 0xffff0000, v25
	v_pk_add_f32 v[14:15], v[14:15], v[18:19]
	v_pk_add_f32 v[12:13], v[12:13], v[28:29]
	v_pk_add_f32 v[6:7], v[6:7], v[22:23]
	v_pk_add_f32 v[4:5], v[4:5], v[32:33]
	v_pk_add_f32 v[8:9], v[8:9], v[30:31]
	v_pk_add_f32 v[10:11], v[10:11], v[20:21]
	v_pk_add_f32 v[18:19], v[2:3], v[24:25]
	v_pk_add_f32 v[20:21], v[0:1], v[34:35]
	v_mul_f32_e32 v2, v12, v12
	v_mul_f32_e32 v3, v14, v14
	v_mul_f32_e32 v22, v4, v4
	v_mul_f32_e32 v23, v6, v6
	v_cvt_pk_bf16_f32 v0, v12, v13
	v_mul_f32_e32 v12, v8, v8
	v_mul_f32_e32 v24, v20, v20
	v_fmac_f32_e32 v2, v13, v13
	v_fmac_f32_e32 v3, v15, v15
	v_fmac_f32_e32 v22, v5, v5
	v_fmac_f32_e32 v23, v7, v7
	v_cvt_pk_bf16_f32 v1, v14, v15
	v_mul_f32_e32 v14, v11, v11
	v_mul_f32_e32 v25, v18, v18
	v_fmac_f32_e32 v12, v9, v9
	v_fmac_f32_e32 v24, v21, v21
	v_add_f32_e32 v2, v3, v2
	v_add_f32_e32 v3, v23, v22
	v_fmac_f32_e32 v14, v10, v10
	v_fmac_f32_e32 v25, v19, v19
	v_add_f32_e32 v2, v12, v2
	v_add_f32_e32 v3, v24, v3
	v_add_f32_e32 v2, v14, v2
	v_add_f32_e32 v3, v25, v3
	v_add_f32_e32 v12, v2, v3
	v_mov_b32_e32 v13, v12
	s_nop 1
	v_permlane16_swap_b32_e32 v13, v12
	v_cvt_pk_bf16_f32 v2, v8, v9
	v_cvt_pk_bf16_f32 v3, v10, v11
	global_store_dwordx4 v[26:27], v[0:3], off
	s_waitcnt lgkmcnt(0)
	s_nop 0
	v_add_f32_e32 v0, v12, v13
	v_mov_b32_e32 v1, v0
	s_nop 1
	v_permlane32_swap_b32_e32 v1, v0
	v_cvt_pk_bf16_f32 v2, v4, v5
	v_cvt_pk_bf16_f32 v3, v6, v7
	v_cvt_pk_bf16_f32 v4, v20, v21
	v_cvt_pk_bf16_f32 v5, v18, v19
	global_store_dwordx4 v[26:27], v[2:5], off offset:256
	s_and_saveexec_b64 s[2:3], vcc
	s_cbranch_execz .LBB0_1061
	v_lshlrev_b64 v[2:3], 6, v[16:17]
	v_lshl_add_u64 v[2:3], s[16:17], 0, v[2:3]
	v_lshl_add_u64 v[2:3], s[0:1], 2, v[2:3]
	s_lshl_b32 s88, s40, 2
	v_lshl_add_u64 v[2:3], v[2:3], 0, s[88:89]
	s_waitcnt lgkmcnt(0)
	v_add_f32_e32 v0, v0, v1
	global_store_dword v[2:3], v0, off
